# v_combo15 + FFT first-pass half-passes: second half's 16 loads requested right after the first half's (pair FFT and kernel-spectrum FFT), counted waits shifted by 16
# speedup vs baseline: 1.0028x; 1.0028x over previous
.LBB0_359:
	s_cmp_lg_u32 s5, 0
	s_cbranch_scc1 .Lmy_fft_k1
	v_add_u32_e32 v0, s5, v170
	v_lshl_add_u64 v[106:107], v[0:1], 2, s[44:45]
	v_add_co_u32_e32 v110, vcc, 0x1000, v106
	global_load_dword v108, v[106:107], off
	s_nop 0
	v_addc_co_u32_e32 v111, vcc, 0, v107, vcc
	v_add_co_u32_e32 v112, vcc, 0x2000, v106
	global_load_dword v109, v[110:111], off
	s_nop 0
	v_addc_co_u32_e32 v113, vcc, 0, v107, vcc
	v_add_co_u32_e32 v110, vcc, 0x3000, v106
	v_cndmask_b32_e64 v66, 0, 1, s[46:47]
	s_nop 0
	v_addc_co_u32_e32 v111, vcc, 0, v107, vcc
	v_add_co_u32_e32 v114, vcc, 0x4000, v106
	global_load_dword v112, v[112:113], off
	s_nop 0
	global_load_dword v113, v[110:111], off
	v_addc_co_u32_e32 v115, vcc, 0, v107, vcc
	v_add_co_u32_e32 v110, vcc, 0x5000, v106
	v_cmp_ne_u32_e64 s[0:1], 1, v66
	s_nop 0
	v_addc_co_u32_e32 v111, vcc, 0, v107, vcc
	v_add_co_u32_e32 v116, vcc, 0x6000, v106
	global_load_dword v114, v[114:115], off
	s_nop 0
	global_load_dword v115, v[110:111], off
	v_addc_co_u32_e32 v117, vcc, 0, v107, vcc
	v_add_co_u32_e32 v110, vcc, 0x7000, v106
	v_mov_b32_e32 v71, v1
	s_nop 0
	v_addc_co_u32_e32 v111, vcc, 0, v107, vcc
	v_add_co_u32_e32 v118, vcc, 0x8000, v106
	global_load_dword v116, v[116:117], off
	s_nop 0
	global_load_dword v117, v[110:111], off
	v_addc_co_u32_e32 v119, vcc, 0, v107, vcc
	v_add_co_u32_e32 v110, vcc, 0x9000, v106
	v_mov_b32_e32 v72, v1
	s_nop 0
	v_addc_co_u32_e32 v111, vcc, 0, v107, vcc
	v_add_co_u32_e32 v120, vcc, 0xa000, v106
	global_load_dword v118, v[118:119], off
	s_nop 0
	global_load_dword v119, v[110:111], off
	v_addc_co_u32_e32 v121, vcc, 0, v107, vcc
	v_add_co_u32_e32 v110, vcc, 0xb000, v106
	v_mov_b32_e32 v77, v1
	s_nop 0
	v_addc_co_u32_e32 v111, vcc, 0, v107, vcc
	v_add_co_u32_e32 v122, vcc, 0xc000, v106
	global_load_dword v120, v[120:121], off
	s_nop 0
	global_load_dword v121, v[110:111], off
	v_addc_co_u32_e32 v123, vcc, 0, v107, vcc
	v_add_co_u32_e32 v110, vcc, 0xd000, v106
	v_mov_b32_e32 v84, v1
	s_nop 0
	v_addc_co_u32_e32 v111, vcc, 0, v107, vcc
	v_add_co_u32_e32 v124, vcc, 0xe000, v106
	global_load_dword v122, v[122:123], off
	s_nop 0
	global_load_dword v123, v[110:111], off
	v_addc_co_u32_e32 v125, vcc, 0, v107, vcc
	v_add_co_u32_e32 v106, vcc, 0xf000, v106
	v_mov_b32_e32 v67, v1
	s_nop 0
	v_addc_co_u32_e32 v107, vcc, 0, v107, vcc
	global_load_dword v110, v[124:125], off
	global_load_dword v111, v[106:107], off
	v_mov_b32_e32 v219, 0
	v_add_u32_e32 v218, 0x200, v170
	v_lshl_add_u64 v[198:199], v[218:219], 2, s[44:45]
	v_add_co_u32_e32 v202, vcc, 0x1000, v198
	global_load_dword v200, v[198:199], off
	s_nop 0
	v_addc_co_u32_e32 v203, vcc, 0, v199, vcc
	v_add_co_u32_e32 v204, vcc, 0x2000, v198
	global_load_dword v201, v[202:203], off
	s_nop 0
	v_addc_co_u32_e32 v205, vcc, 0, v199, vcc
	v_add_co_u32_e32 v202, vcc, 0x3000, v198
	s_nop 0
	v_addc_co_u32_e32 v203, vcc, 0, v199, vcc
	v_add_co_u32_e32 v206, vcc, 0x4000, v198
	global_load_dword v204, v[204:205], off
	s_nop 0
	global_load_dword v205, v[202:203], off
	v_addc_co_u32_e32 v207, vcc, 0, v199, vcc
	v_add_co_u32_e32 v202, vcc, 0x5000, v198
	s_nop 0
	v_addc_co_u32_e32 v203, vcc, 0, v199, vcc
	v_add_co_u32_e32 v208, vcc, 0x6000, v198
	global_load_dword v206, v[206:207], off
	s_nop 0
	global_load_dword v207, v[202:203], off
	v_addc_co_u32_e32 v209, vcc, 0, v199, vcc
	v_add_co_u32_e32 v202, vcc, 0x7000, v198
	s_nop 0
	v_addc_co_u32_e32 v203, vcc, 0, v199, vcc
	v_add_co_u32_e32 v210, vcc, 0x8000, v198
	global_load_dword v208, v[208:209], off
	s_nop 0
	global_load_dword v209, v[202:203], off
	v_addc_co_u32_e32 v211, vcc, 0, v199, vcc
	v_add_co_u32_e32 v202, vcc, 0x9000, v198
	s_nop 0
	v_addc_co_u32_e32 v203, vcc, 0, v199, vcc
	v_add_co_u32_e32 v212, vcc, 0xa000, v198
	global_load_dword v210, v[210:211], off
	s_nop 0
	global_load_dword v211, v[202:203], off
	v_addc_co_u32_e32 v213, vcc, 0, v199, vcc
	v_add_co_u32_e32 v202, vcc, 0xb000, v198
	s_nop 0
	v_addc_co_u32_e32 v203, vcc, 0, v199, vcc
	v_add_co_u32_e32 v214, vcc, 0xc000, v198
	global_load_dword v212, v[212:213], off
	s_nop 0
	global_load_dword v213, v[202:203], off
	v_addc_co_u32_e32 v215, vcc, 0, v199, vcc
	v_add_co_u32_e32 v202, vcc, 0xd000, v198
	s_nop 0
	v_addc_co_u32_e32 v203, vcc, 0, v199, vcc
	v_add_co_u32_e32 v216, vcc, 0xe000, v198
	global_load_dword v214, v[214:215], off
	s_nop 0
	global_load_dword v215, v[202:203], off
	v_addc_co_u32_e32 v217, vcc, 0, v199, vcc
	v_add_co_u32_e32 v198, vcc, 0xf000, v198
	s_nop 0
	v_addc_co_u32_e32 v199, vcc, 0, v199, vcc
	global_load_dword v202, v[216:217], off
	global_load_dword v203, v[198:199], off
	s_branch .Lmy_fft_kj
.Lmy_fft_k1:
	v_add_u32_e32 v0, s5, v170
	v_cndmask_b32_e64 v66, 0, 1, s[46:47]
	v_cmp_ne_u32_e64 s[0:1], 1, v66
	v_mov_b32_e32 v71, v1
	v_mov_b32_e32 v72, v1
	v_mov_b32_e32 v77, v1
	v_mov_b32_e32 v84, v1
	v_mov_b32_e32 v67, v1
	s_waitcnt vmcnt(0)
	v_mov_b32_e32 v108, v200
	v_mov_b32_e32 v109, v201
	v_mov_b32_e32 v112, v204
	v_mov_b32_e32 v113, v205
	v_mov_b32_e32 v114, v206
	v_mov_b32_e32 v115, v207
	v_mov_b32_e32 v116, v208
	v_mov_b32_e32 v117, v209
	v_mov_b32_e32 v118, v210
	v_mov_b32_e32 v119, v211
	v_mov_b32_e32 v120, v212
	v_mov_b32_e32 v121, v213
	v_mov_b32_e32 v122, v214
	v_mov_b32_e32 v123, v215
	v_mov_b32_e32 v110, v202
	v_mov_b32_e32 v111, v203
.Lmy_fft_kj:
	v_mov_b32 v66, 0
	v_mov_b32_e32 v68, v1
	v_add_u32_e32 v0, v66, v0
	v_cvt_f32_i32_e32 v70, v0
	v_ashrrev_i32_e32 v66, 5, v0
	v_lshlrev_b32_e32 v69, 3, v0
	v_add_u32_e32 v73, 0x400, v0
	v_add_u32_e32 v75, 0x800, v0
	v_add_u32_e32 v76, 0xc00, v0
	v_add_u32_e32 v78, 0x1000, v0
	v_add_u32_e32 v80, 0x1400, v0
	v_add_u32_e32 v82, 0x1800, v0
	v_add_u32_e32 v85, 0x1c00, v0
	v_add_u32_e32 v87, 0x2000, v0
	v_add_u32_e32 v89, 0x2400, v0
	v_add_u32_e32 v91, 0x2800, v0
	v_add_u32_e32 v92, 0x2c00, v0
	v_add_u32_e32 v95, 0x3000, v0
	v_add_u32_e32 v96, 0x3400, v0
	v_add_u32_e32 v99, 0x3800, v0
	v_add_u32_e32 v0, 0x3c00, v0
	v_lshlrev_b32_e32 v66, 3, v66
	v_ashrrev_i32_e32 v73, 5, v73
	v_ashrrev_i32_e32 v75, 5, v75
	v_ashrrev_i32_e32 v76, 5, v76
	v_ashrrev_i32_e32 v78, 5, v78
	v_ashrrev_i32_e32 v80, 5, v80
	v_ashrrev_i32_e32 v82, 5, v82
	v_ashrrev_i32_e32 v85, 5, v85
	v_ashrrev_i32_e32 v100, 5, v87
	v_ashrrev_i32_e32 v103, 5, v89
	v_ashrrev_i32_e32 v105, 5, v91
	v_ashrrev_i32_e32 v106, 5, v92
	v_ashrrev_i32_e32 v107, 5, v95
	v_ashrrev_i32_e32 v124, 5, v96
	v_ashrrev_i32_e32 v125, 5, v99
	v_ashrrev_i32_e32 v126, 5, v0
	v_lshlrev_b32_e32 v0, 3, v0
	v_add3_u32 v127, 0, v66, v69
	v_lshlrev_b32_e32 v66, 3, v73
	v_lshlrev_b32_e32 v73, 3, v75
	v_lshlrev_b32_e32 v75, 3, v76
	v_lshlrev_b32_e32 v76, 3, v78
	v_lshlrev_b32_e32 v78, 3, v80
	v_lshlrev_b32_e32 v80, 3, v82
	v_lshlrev_b32_e32 v82, 3, v85
	v_lshlrev_b32_e32 v85, 3, v100
	v_lshlrev_b32_e32 v100, 3, v103
	v_lshlrev_b32_e32 v103, 3, v105
	v_lshlrev_b32_e32 v105, 3, v106
	v_lshlrev_b32_e32 v106, 3, v107
	v_lshlrev_b32_e32 v107, 3, v124
	v_lshlrev_b32_e32 v124, 3, v125
	v_lshlrev_b32_e32 v125, 3, v126
	v_lshlrev_b32_e32 v96, 3, v96
	v_add3_u32 v196, 0, v125, v0
	v_mul_f32_e32 v0, 0x38800000, v70
	v_lshlrev_b32_e32 v95, 3, v95
	v_add3_u32 v194, 0, v107, v96
	v_sin_f32_e32 v107, v0
	v_add3_u32 v193, 0, v106, v95
	v_cos_f32_e32 v106, v0
	v_lshlrev_b32_e32 v99, 3, v99
	v_add3_u32 v195, 0, v124, v99
	v_xor_b32_e32 v124, 0x80000000, v107
	v_mov_b32_e32 v125, v107
	v_pk_mul_f32 v[128:129], v[124:125], v[106:107] op_sel:[0,1] op_sel_hi:[1,0]
	v_lshlrev_b32_e32 v87, 3, v87
	v_pk_fma_f32 v[128:129], v[106:107], v[106:107], v[128:129] op_sel_hi:[1,0,1]
	v_add3_u32 v186, 0, v76, v69
	v_pk_mul_f32 v[132:133], v[124:125], v[128:129] op_sel:[0,1] op_sel_hi:[1,0]
	s_waitcnt vmcnt(21)
	v_sub_f32_e32 v70, v112, v120
	v_pk_fma_f32 v[132:133], v[128:129], v[106:107], v[132:133] op_sel_hi:[1,0,1]
	s_waitcnt vmcnt(20)
	v_sub_f32_e32 v76, v113, v121
	v_pk_mul_f32 v[136:137], v[124:125], v[132:133] op_sel:[0,1] op_sel_hi:[1,0]
	v_add3_u32 v171, 0, v66, v69
	v_pk_fma_f32 v[136:137], v[132:133], v[106:107], v[136:137] op_sel_hi:[1,0,1]
	v_add3_u32 v184, 0, v73, v69
	v_pk_mul_f32 v[140:141], v[124:125], v[136:137] op_sel:[0,1] op_sel_hi:[1,0]
	v_add3_u32 v190, 0, v85, v87
	v_pk_fma_f32 v[140:141], v[136:137], v[106:107], v[140:141] op_sel_hi:[1,0,1]
	v_sub_f32_e32 v66, v109, v119
	v_pk_mul_f32 v[144:145], v[124:125], v[140:141] op_sel:[0,1] op_sel_hi:[1,0]
	v_mul_f32_e32 v73, 0xbf3504f3, v70
	v_pk_fma_f32 v[144:145], v[140:141], v[106:107], v[144:145] op_sel_hi:[1,0,1]
	v_mul_f32_e32 v85, 0xbf6c835e, v76
	v_pk_mul_f32 v[148:149], v[124:125], v[144:145] op_sel:[0,1] op_sel_hi:[1,0]
	v_lshlrev_b32_e32 v91, 3, v91
	v_pk_fma_f32 v[148:149], v[144:145], v[106:107], v[148:149] op_sel_hi:[1,0,1]
	v_add3_u32 v185, 0, v75, v69
	v_pk_mul_f32 v[152:153], v[124:125], v[148:149] op_sel:[0,1] op_sel_hi:[1,0]
	v_add3_u32 v187, 0, v78, v69
	v_pk_fma_f32 v[152:153], v[148:149], v[106:107], v[152:153] op_sel_hi:[1,0,1]
	v_add3_u32 v188, 0, v80, v69
	v_pk_mul_f32 v[156:157], v[124:125], v[152:153] op_sel:[0,1] op_sel_hi:[1,0]
	v_add3_u32 v189, 0, v82, v69
	v_pk_fma_f32 v[156:157], v[152:153], v[106:107], v[156:157] op_sel_hi:[1,0,1]
	v_sub_f32_e32 v0, v108, v118
	v_pk_mul_f32 v[160:161], v[124:125], v[156:157] op_sel:[0,1] op_sel_hi:[1,0]
	v_pk_add_f32 v[108:109], v[108:109], v[118:119]
	v_pk_fma_f32 v[160:161], v[156:157], v[106:107], v[160:161] op_sel_hi:[1,0,1]
	v_mul_f32_e32 v69, 0xbec3ef15, v66
	v_pk_mul_f32 v[164:165], v[124:125], v[160:161] op_sel:[0,1] op_sel_hi:[1,0]
	v_pk_fma_f32 v[70:71], v[70:71], s[10:11], v[72:73] op_sel_hi:[1,0,1]
	v_pk_fma_f32 v[72:73], v[76:77], s[14:15], v[84:85] op_sel_hi:[1,0,1]
	s_waitcnt vmcnt(18)
	v_sub_f32_e32 v82, v115, v123
	v_pk_add_f32 v[76:77], v[114:115], v[122:123]
	v_mov_b32_e32 v83, v1
	v_mov_b32_e32 v90, v1
	s_movk_i32 s5, 0x200
	v_lshlrev_b32_e32 v89, 3, v89
	v_add3_u32 v192, 0, v103, v91
	v_pk_fma_f32 v[164:165], v[160:161], v[106:107], v[164:165] op_sel_hi:[1,0,1]
	v_pk_fma_f32 v[66:67], v[66:67], s[6:7], v[68:69] op_sel_hi:[1,0,1]
	v_pk_add_f32 v[68:69], v[112:113], v[120:121]
	v_mul_f32_e32 v91, 0xbf6c835e, v82
	s_waitcnt vmcnt(17)
	v_sub_f32_e32 v80, v116, v110
	v_pk_add_f32 v[112:113], v[108:109], v[76:77] neg_lo:[0,1] neg_hi:[0,1]
	v_mov_b32_e32 v81, v1
	v_mov_b32_e32 v88, v1
	v_mov_b32_e32 v101, v1
	v_mov_b32_e32 v102, v1
	v_add3_u32 v191, 0, v100, v89
	v_pk_mul_f32 v[168:169], v[124:125], v[164:165] op_sel:[0,1] op_sel_hi:[1,0]
	v_pk_fma_f32 v[82:83], v[82:83], s[4:5], v[90:91] op_sel_hi:[1,0,1]
	v_mul_f32_e32 v89, 0xbf3504f3, v80
	s_waitcnt vmcnt(16)
	v_sub_f32_e32 v78, v117, v111
	v_pk_add_f32 v[90:91], v[116:117], v[110:111]
	v_mov_b32_e32 v100, v113
	v_mul_f32_e32 v103, 0xbf3504f3, v113
	v_mov_b32_e32 v79, v1
	v_mov_b32_e32 v86, v1
	v_pk_fma_f32 v[168:169], v[164:165], v[106:107], v[168:169] op_sel_hi:[1,0,1]
	v_sub_f32_e32 v75, v114, v122
	v_pk_fma_f32 v[80:81], v[80:81], s[8:9], v[88:89] op_sel_hi:[1,0,1]
	v_mul_f32_e32 v87, 0xbec3ef15, v78
	v_pk_add_f32 v[88:89], v[66:67], v[82:83]
	v_pk_add_f32 v[66:67], v[66:67], v[82:83] neg_lo:[0,1] neg_hi:[0,1]
	v_pk_fma_f32 v[82:83], v[100:101], s[10:11], v[102:103] op_sel_hi:[1,0,1]
	v_pk_add_f32 v[100:101], v[68:69], v[90:91] neg_lo:[0,1] neg_hi:[0,1]
	v_mov_b32_e32 v74, v1
	v_mov_b32_e32 v97, v1
	v_mov_b32_e32 v98, v1
	v_pk_mul_f32 v[174:175], v[124:125], v[168:169] op_sel:[0,1] op_sel_hi:[1,0]
	v_xor_b32_e32 v75, 0x80000000, v75
	v_pk_add_f32 v[76:77], v[108:109], v[76:77]
	v_pk_add_f32 v[68:69], v[68:69], v[90:91]
	v_pk_fma_f32 v[78:79], v[78:79], s[12:13], v[86:87] op_sel_hi:[1,0,1]
	v_pk_add_f32 v[90:91], v[70:71], v[80:81]
	v_pk_add_f32 v[70:71], v[70:71], v[80:81] neg_lo:[0,1] neg_hi:[0,1]
	v_mov_b32_e32 v96, v101
	v_mul_f32_e32 v99, 0xbf3504f3, v101
	v_lshlrev_b32_e32 v92, 3, v92
	v_pk_fma_f32 v[174:175], v[168:169], v[106:107], v[174:175] op_sel_hi:[1,0,1]
	v_pk_add_f32 v[84:85], v[0:1], v[74:75]
	v_pk_add_f32 v[80:81], v[76:77], v[68:69] neg_lo:[0,1] neg_hi:[0,1]
	v_pk_add_f32 v[68:69], v[76:77], v[68:69]
	v_xor_b32_e32 v77, 0x80000000, v70
	v_mov_b32_e32 v76, v71
	v_pk_add_f32 v[70:71], v[72:73], v[78:79]
	v_pk_add_f32 v[72:73], v[72:73], v[78:79] neg_lo:[0,1] neg_hi:[0,1]
	v_pk_fma_f32 v[78:79], v[96:97], s[8:9], v[98:99] op_sel_hi:[1,0,1]
	v_mov_b32_e32 v94, v1
	v_add3_u32 v105, 0, v105, v92
	v_pk_mul_f32 v[178:179], v[124:125], v[174:175] op_sel:[0,1] op_sel_hi:[1,0]
	v_pk_add_f32 v[74:75], v[0:1], v[74:75] neg_lo:[0,1] neg_hi:[0,1]
	v_mov_b32_e32 v0, v112
	v_pk_mul_f32 v[86:87], v[66:67], s[16:17]
	v_xor_b32_e32 v95, 0x80000000, v100
	v_mov_b32_e32 v92, v80
	v_pk_add_f32 v[80:81], v[80:81], 0 neg_lo:[1,1] neg_hi:[1,1]
	v_pk_add_f32 v[96:97], v[84:85], v[90:91]
	v_pk_add_f32 v[84:85], v[84:85], v[90:91] neg_lo:[0,1] neg_hi:[0,1]
	v_pk_add_f32 v[90:91], v[68:69], v[68:69] op_sel:[0,1] op_sel_hi:[1,0]
	v_pk_mul_f32 v[98:99], v[72:73], s[16:17]
	v_pk_add_f32 v[100:101], v[82:83], v[78:79]
	v_pk_add_f32 v[78:79], v[82:83], v[78:79] neg_lo:[0,1] neg_hi:[0,1]
	v_pk_add_f32 v[82:83], v[88:89], v[70:71]
	v_pk_add_f32 v[70:71], v[88:89], v[70:71] neg_lo:[0,1] neg_hi:[0,1]
	v_mov_b32_e32 v93, v1
	v_mov_b32_e32 v126, v107
	v_pk_add_f32 v[130:131], v[128:129], 0 neg_lo:[1,1] neg_hi:[1,1]
	v_pk_add_f32 v[158:159], v[156:157], 0 neg_lo:[1,1] neg_hi:[1,1]
	v_pk_fma_f32 v[178:179], v[174:175], v[106:107], v[178:179] op_sel_hi:[1,0,1]
	v_pk_fma_f32 v[66:67], v[66:67], s[10:11], v[86:87] op_sel:[0,0,1] op_sel_hi:[1,0,0]
	v_pk_add_f32 v[86:87], v[0:1], v[94:95]
	v_pk_add_f32 v[94:95], v[0:1], v[94:95] neg_lo:[0,1] neg_hi:[0,1]
	v_mov_b32_e32 v80, v1
	v_pk_add_f32 v[88:89], v[74:75], v[76:77]
	v_pk_add_f32 v[74:75], v[74:75], v[76:77] neg_lo:[0,1] neg_hi:[0,1]
	v_mov_b32_e32 v91, v1
	v_pk_fma_f32 v[72:73], v[72:73], s[8:9], v[98:99] op_sel:[0,0,1] op_sel_hi:[1,0,0]
	v_xor_b32_e32 v77, 0x80000000, v78
	v_mov_b32_e32 v76, v79
	v_xor_b32_e32 v79, 0x80000000, v70
	v_mov_b32_e32 v78, v71
	v_pk_add_f32 v[98:99], v[96:97], v[82:83]
	v_mov_b32_e32 v130, v129
	v_pk_add_f32 v[134:135], v[132:133], 0 neg_lo:[1,1] neg_hi:[1,1]
	v_pk_add_f32 v[142:143], v[140:141], 0 neg_lo:[1,1] neg_hi:[1,1]
	v_mov_b32_e32 v158, v157
	v_pk_mul_f32 v[124:125], v[124:125], v[178:179] op_sel:[0,1] op_sel_hi:[1,0]
	v_pk_add_f32 v[70:71], v[92:93], v[80:81]
	v_pk_add_f32 v[80:81], v[92:93], v[80:81] neg_lo:[0,1] neg_hi:[0,1]
	v_pk_add_f32 v[92:93], v[86:87], v[100:101]
	v_pk_add_f32 v[82:83], v[96:97], v[82:83] neg_lo:[0,1] neg_hi:[0,1]
	ds_write_b64 v127, v[90:91]
	v_pk_add_f32 v[90:91], v[66:67], v[72:73]
	v_pk_add_f32 v[66:67], v[66:67], v[72:73] neg_lo:[0,1] neg_hi:[0,1]
	v_pk_add_f32 v[72:73], v[94:95], v[76:77]
	v_pk_add_f32 v[76:77], v[94:95], v[76:77] neg_lo:[0,1] neg_hi:[0,1]
	v_pk_add_f32 v[94:95], v[84:85], v[78:79]
	v_pk_add_f32 v[78:79], v[84:85], v[78:79] neg_lo:[0,1] neg_hi:[0,1]
	v_pk_mul_f32 v[84:85], v[126:127], v[98:99] op_sel:[0,1] op_sel_hi:[0,0] neg_hi:[1,0]
	v_mov_b32_e32 v134, v133
	v_pk_add_f32 v[138:139], v[136:137], 0 neg_lo:[1,1] neg_hi:[1,1]
	v_mov_b32_e32 v142, v141
	v_pk_add_f32 v[146:147], v[144:145], 0 neg_lo:[1,1] neg_hi:[1,1]
	v_pk_add_f32 v[150:151], v[148:149], 0 neg_lo:[1,1] neg_hi:[1,1]
	v_pk_add_f32 v[166:167], v[164:165], 0 neg_lo:[1,1] neg_hi:[1,1]
	v_pk_fma_f32 v[124:125], v[178:179], v[106:107], v[124:125] op_sel_hi:[1,0,1]
	v_pk_mul_f32 v[96:97], v[92:93], v[130:131] op_sel:[1,0] op_sel_hi:[0,1]
	v_pk_mul_f32 v[102:103], v[82:83], v[158:159] op_sel:[1,0] op_sel_hi:[0,1]
	v_xor_b32_e32 v113, 0x80000000, v66
	v_mov_b32_e32 v112, v67
	v_pk_add_f32 v[66:67], v[88:89], v[90:91]
	v_pk_fma_f32 v[84:85], v[98:99], v[106:107], v[84:85] op_sel_hi:[1,0,1]
	v_mov_b32_e32 v138, v137
	v_mov_b32_e32 v146, v145
	v_mov_b32_e32 v150, v149
	v_pk_add_f32 v[154:155], v[152:153], 0 neg_lo:[1,1] neg_hi:[1,1]
	v_pk_add_f32 v[162:163], v[160:161], 0 neg_lo:[1,1] neg_hi:[1,1]
	v_mov_b32_e32 v166, v165
	v_pk_add_f32 v[172:173], v[168:169], 0 neg_lo:[1,1] neg_hi:[1,1]
	v_pk_add_f32 v[176:177], v[174:175], 0 neg_lo:[1,1] neg_hi:[1,1]
	v_pk_add_f32 v[180:181], v[178:179], 0 neg_lo:[1,1] neg_hi:[1,1]
	v_pk_add_f32 v[182:183], v[124:125], 0 neg_lo:[1,1] neg_hi:[1,1]
	v_pk_add_f32 v[68:69], v[68:69], v[68:69] op_sel:[0,1] op_sel_hi:[1,0] neg_lo:[0,1] neg_hi:[0,1]
	v_pk_add_f32 v[88:89], v[88:89], v[90:91] neg_lo:[0,1] neg_hi:[0,1]
	v_pk_fma_f32 v[90:91], v[92:93], v[128:129], v[96:97] op_sel_hi:[1,0,1]
	v_pk_mul_f32 v[92:93], v[94:95], v[142:143] op_sel:[1,0] op_sel_hi:[0,1]
	v_pk_fma_f32 v[82:83], v[82:83], v[156:157], v[102:103] op_sel_hi:[1,0,1]
	v_pk_add_f32 v[102:103], v[74:75], v[112:113]
	ds_write_b64 v171, v[84:85] offset:8192
	ds_write_b64 v184, v[90:91] offset:16384
	v_pk_mul_f32 v[84:85], v[66:67], v[134:135] op_sel:[1,0] op_sel_hi:[0,1]
	v_mov_b32_e32 v154, v153
	v_mov_b32_e32 v162, v161
	v_mov_b32_e32 v172, v169
	v_mov_b32_e32 v176, v175
	v_mov_b32_e32 v180, v179
	v_mov_b32_e32 v182, v125
	v_mov_b32_e32 v0, v68
	v_pk_mov_b32 v[68:69], s[2:3], v[68:69] op_sel:[1,0]
	v_pk_add_f32 v[86:87], v[86:87], v[100:101] neg_lo:[0,1] neg_hi:[0,1]
	v_pk_mul_f32 v[100:101], v[70:71], v[138:139] op_sel:[1,0] op_sel_hi:[0,1]
	v_pk_mul_f32 v[96:97], v[72:73], v[146:147] op_sel:[1,0] op_sel_hi:[0,1]
	v_pk_add_f32 v[74:75], v[74:75], v[112:113] neg_lo:[0,1] neg_hi:[0,1]
	v_pk_fma_f32 v[90:91], v[94:95], v[140:141], v[92:93] op_sel_hi:[1,0,1]
	v_pk_mul_f32 v[92:93], v[88:89], v[166:167] op_sel:[1,0] op_sel_hi:[0,1]
	v_pk_fma_f32 v[66:67], v[66:67], v[132:133], v[84:85] op_sel_hi:[1,0,1]
	v_pk_mul_f32 v[84:85], v[102:103], v[150:151] op_sel:[1,0] op_sel_hi:[0,1]
	s_mov_b64 s[46:47], 0
	s_and_b64 vcc, exec, s[0:1]
	v_pk_mul_f32 v[68:69], v[68:69], v[154:155]
	v_pk_mul_f32 v[108:109], v[86:87], v[162:163] op_sel:[1,0] op_sel_hi:[0,1]
	v_pk_mul_f32 v[110:111], v[80:81], v[172:173] op_sel:[1,0] op_sel_hi:[0,1]
	v_pk_fma_f32 v[70:71], v[70:71], v[136:137], v[100:101] op_sel_hi:[1,0,1]
	v_pk_mul_f32 v[98:99], v[78:79], v[176:177] op_sel:[1,0] op_sel_hi:[0,1]
	v_pk_mul_f32 v[100:101], v[76:77], v[180:181] op_sel:[1,0] op_sel_hi:[0,1]
	v_pk_fma_f32 v[72:73], v[72:73], v[144:145], v[96:97] op_sel_hi:[1,0,1]
	v_pk_fma_f32 v[88:89], v[88:89], v[164:165], v[92:93] op_sel_hi:[1,0,1]
	v_pk_mul_f32 v[92:93], v[74:75], v[182:183] op_sel:[1,0] op_sel_hi:[0,1]
	ds_write_b64 v185, v[66:67] offset:24576
	ds_write_b64 v186, v[70:71] offset:32768
	ds_write_b64 v187, v[90:91] offset:40960
	ds_write_b64 v188, v[72:73] offset:49152
	v_pk_fma_f32 v[66:67], v[102:103], v[148:149], v[84:85] op_sel_hi:[1,0,1]
	v_pk_fma_f32 v[68:69], v[0:1], v[152:153], v[68:69] op_sel_hi:[1,0,1]
	v_pk_fma_f32 v[86:87], v[86:87], v[160:161], v[108:109] op_sel_hi:[1,0,1]
	v_pk_fma_f32 v[80:81], v[80:81], v[168:169], v[110:111] op_sel_hi:[1,0,1]
	v_pk_fma_f32 v[78:79], v[78:79], v[174:175], v[98:99] op_sel_hi:[1,0,1]
	v_pk_fma_f32 v[76:77], v[76:77], v[178:179], v[100:101] op_sel_hi:[1,0,1]
	v_pk_fma_f32 v[70:71], v[74:75], v[124:125], v[92:93] op_sel_hi:[1,0,1]
	ds_write_b64 v189, v[66:67] offset:57344
	ds_write_b64 v190, v[68:69]
	ds_write_b64 v191, v[82:83]
	ds_write_b64 v192, v[86:87]
	ds_write_b64 v105, v[88:89]
	ds_write_b64 v193, v[80:81]
	ds_write_b64 v194, v[78:79]
	ds_write_b64 v195, v[76:77]
	ds_write_b64 v196, v[70:71]
	s_cbranch_vccz .LBB0_359
	s_waitcnt lgkmcnt(0)
	s_barrier
	v_mov_b32 v0, 0
	s_mov_b32 s5, s14
	v_add_u32_e32 v74, v0, v170
	v_lshlrev_b32_e32 v0, 5, v74
	v_and_b32_e32 v71, 0xfffffc00, v0
	v_or_b32_e32 v75, 0x80, v71
	v_and_b32_e32 v70, 31, v74
	v_ashrrev_i32_e32 v75, 2, v75
	v_lshlrev_b32_e32 v78, 3, v71
	v_lshlrev_b32_e32 v79, 3, v70
	v_add_u32_e32 v75, 0, v75
	v_add3_u32 v111, v75, v78, v79
	v_or_b32_e32 v75, 0xa0, v71
	v_ashrrev_i32_e32 v75, 2, v75
	v_add_u32_e32 v75, 0, v75
	v_add3_u32 v110, v75, v78, v79
	v_or_b32_e32 v75, 0xc0, v71
	v_ashrrev_i32_e32 v75, 2, v75
	v_add_u32_e32 v75, 0, v75
	v_add3_u32 v109, v75, v78, v79
	v_or_b32_e32 v75, 0xe0, v71
	v_ashrrev_i32_e32 v75, 2, v75
	v_add_u32_e32 v75, 0, v75
	v_add3_u32 v108, v75, v78, v79
	v_or_b32_e32 v75, 0x100, v71
	v_ashrrev_i32_e32 v75, 2, v75
	v_add_u32_e32 v75, 0, v75
	v_add3_u32 v107, v75, v78, v79
	v_or_b32_e32 v75, 0x120, v71
	v_ashrrev_i32_e32 v75, 2, v75
	v_add_u32_e32 v75, 0, v75
	v_add3_u32 v106, v75, v78, v79
	v_or_b32_e32 v75, 0x140, v71
	v_ashrrev_i32_e32 v75, 2, v75
	v_add_u32_e32 v75, 0, v75
	v_add3_u32 v105, v75, v78, v79
	v_or_b32_e32 v75, 0x160, v71
	v_ashrrev_i32_e32 v75, 2, v75
	v_add_u32_e32 v75, 0, v75
	v_add3_u32 v103, v75, v78, v79
	v_or_b32_e32 v75, 0x180, v71
	v_ashrrev_i32_e32 v75, 2, v75
	v_add_u32_e32 v75, 0, v75
	v_add3_u32 v102, v75, v78, v79
	v_or_b32_e32 v75, 0x1a0, v71
	v_ashrrev_i32_e32 v75, 2, v75
	v_add_u32_e32 v75, 0, v75
	v_add3_u32 v101, v75, v78, v79
	v_or_b32_e32 v75, 0x1c0, v71
	v_ashrrev_i32_e32 v75, 2, v75
	v_add_u32_e32 v75, 0, v75
	v_add3_u32 v100, v75, v78, v79
	v_or_b32_e32 v75, 0x1e0, v71
	v_ashrrev_i32_e32 v75, 2, v75
	v_add_u32_e32 v75, 0, v75
	v_add3_u32 v99, v75, v78, v79
	v_or_b32_e32 v75, 0x200, v71
	v_ashrrev_i32_e32 v75, 2, v75
	v_add_u32_e32 v75, 0, v75
	v_add3_u32 v98, v75, v78, v79
	v_or_b32_e32 v75, 0x220, v71
	v_ashrrev_i32_e32 v75, 2, v75
	v_add_u32_e32 v75, 0, v75
	v_add3_u32 v97, v75, v78, v79
	v_or_b32_e32 v75, 0x240, v71
	v_ashrrev_i32_e32 v75, 2, v75
	v_add_u32_e32 v75, 0, v75
	v_add3_u32 v96, v75, v78, v79
	v_or_b32_e32 v75, 0x260, v71
	v_ashrrev_i32_e32 v75, 2, v75
	v_add_u32_e32 v75, 0, v75
	v_add3_u32 v95, v75, v78, v79
	v_or_b32_e32 v75, 0x280, v71
	v_or_b32_e32 v67, 32, v71
	v_ashrrev_i32_e32 v75, 2, v75
	v_ashrrev_i32_e32 v67, 2, v67
	v_add_u32_e32 v75, 0, v75
	v_add_u32_e32 v67, 0, v67
	v_add3_u32 v94, v75, v78, v79
	v_or_b32_e32 v75, 0x2a0, v71
	v_add3_u32 v114, v67, v78, v79
	v_or_b32_e32 v67, 64, v71
	v_ashrrev_i32_e32 v75, 2, v75
	v_ashrrev_i32_e32 v67, 2, v67
	v_add_u32_e32 v75, 0, v75
	v_add_u32_e32 v67, 0, v67
	v_add3_u32 v93, v75, v78, v79
	v_or_b32_e32 v75, 0x2c0, v71
	v_ashrrev_i32_e32 v66, 2, v71
	v_add3_u32 v113, v67, v78, v79
	v_or_b32_e32 v67, 0x60, v71
	v_ashrrev_i32_e32 v75, 2, v75
	v_add_u32_e32 v66, 0, v66
	v_ashrrev_i32_e32 v67, 2, v67
	v_add_u32_e32 v75, 0, v75
	v_add3_u32 v66, v66, v78, v79
	v_add_u32_e32 v67, 0, v67
	v_add3_u32 v92, v75, v78, v79
	v_or_b32_e32 v75, 0x2e0, v71
	v_add3_u32 v112, v67, v78, v79
	ds_read_b64 v[66:67], v66
	ds_read_b64 v[68:69], v114 offset:256
	ds_read_b64 v[72:73], v113 offset:512
	ds_read_b64 v[76:77], v112 offset:768
	ds_read_b64 v[80:81], v111 offset:1024
	ds_read_b64 v[82:83], v110 offset:1280
	ds_read_b64 v[116:117], v109 offset:1536
	ds_read_b64 v[118:119], v108 offset:1792
	ds_read_b64 v[120:121], v107 offset:2048
	ds_read_b64 v[122:123], v106 offset:2304
	ds_read_b64 v[124:125], v105 offset:2560
	ds_read_b64 v[126:127], v103 offset:2816
	ds_read_b64 v[128:129], v102 offset:3072
	ds_read_b64 v[130:131], v101 offset:3328
	ds_read_b64 v[132:133], v100 offset:3584
	ds_read_b64 v[134:135], v99 offset:3840
	ds_read_b64 v[136:137], v98 offset:4096
	ds_read_b64 v[138:139], v97 offset:4352
	ds_read_b64 v[140:141], v96 offset:4608
	ds_read_b64 v[142:143], v95 offset:4864
	v_ashrrev_i32_e32 v75, 2, v75
	v_add_u32_e32 v75, 0, v75
	v_add3_u32 v91, v75, v78, v79
	v_or_b32_e32 v75, 0x300, v71
	v_ashrrev_i32_e32 v75, 2, v75
	s_waitcnt lgkmcnt(3)
	v_pk_add_f32 v[168:169], v[66:67], v[136:137]
	v_pk_add_f32 v[66:67], v[66:67], v[136:137] neg_lo:[0,1] neg_hi:[0,1]
	s_waitcnt lgkmcnt(2)
	v_pk_add_f32 v[136:137], v[68:69], v[138:139]
	v_pk_add_f32 v[68:69], v[68:69], v[138:139] neg_lo:[0,1] neg_hi:[0,1]
	v_add_u32_e32 v75, 0, v75
	v_pk_mul_f32 v[138:139], v[68:69], s[18:19]
	v_add3_u32 v90, v75, v78, v79
	v_or_b32_e32 v75, 0x320, v71
	v_pk_fma_f32 v[68:69], v[68:69], s[20:21], v[138:139] op_sel:[0,0,1] op_sel_hi:[1,0,0]
	s_waitcnt lgkmcnt(1)
	v_pk_add_f32 v[138:139], v[72:73], v[140:141]
	v_pk_add_f32 v[72:73], v[72:73], v[140:141] neg_lo:[0,1] neg_hi:[0,1]
	v_ashrrev_i32_e32 v75, 2, v75
	v_pk_mul_f32 v[140:141], v[72:73], s[4:5]
	ds_read_b64 v[144:145], v94 offset:5120
	ds_read_b64 v[146:147], v93 offset:5376
	ds_read_b64 v[148:149], v92 offset:5632
	ds_read_b64 v[150:151], v91 offset:5888
	v_add_u32_e32 v75, 0, v75
	v_pk_fma_f32 v[72:73], v[72:73], s[6:7], v[140:141] op_sel:[0,0,1] op_sel_hi:[1,0,0]
	s_waitcnt lgkmcnt(4)
	v_pk_add_f32 v[140:141], v[76:77], v[142:143]
	v_pk_add_f32 v[76:77], v[76:77], v[142:143] neg_lo:[0,1] neg_hi:[0,1]
	v_add3_u32 v89, v75, v78, v79
	v_or_b32_e32 v75, 0x340, v71
	v_pk_mul_f32 v[142:143], v[76:77], s[22:23]
	v_ashrrev_i32_e32 v75, 2, v75
	v_pk_fma_f32 v[76:77], v[76:77], s[24:25], v[142:143] op_sel:[0,0,1] op_sel_hi:[1,0,0]
	s_waitcnt lgkmcnt(3)
	v_pk_add_f32 v[142:143], v[80:81], v[144:145]
	v_pk_add_f32 v[80:81], v[80:81], v[144:145] neg_lo:[0,1] neg_hi:[0,1]
	s_mov_b32 s9, s10
	v_add_u32_e32 v75, 0, v75
	v_pk_mul_f32 v[144:145], v[80:81], s[8:9]
	v_add3_u32 v88, v75, v78, v79
	v_or_b32_e32 v75, 0x360, v71
	v_pk_fma_f32 v[80:81], v[80:81], s[10:11], v[144:145] op_sel:[0,0,1] op_sel_hi:[1,0,0]
	s_waitcnt lgkmcnt(2)
	v_pk_add_f32 v[144:145], v[82:83], v[146:147]
	v_pk_add_f32 v[82:83], v[82:83], v[146:147] neg_lo:[0,1] neg_hi:[0,1]
	s_mov_b32 s27, s24
	v_ashrrev_i32_e32 v75, 2, v75
	v_pk_mul_f32 v[146:147], v[82:83], s[26:27]
	s_mov_b32 s0, s23
	v_add_u32_e32 v75, 0, v75
	v_pk_fma_f32 v[82:83], v[82:83], s[0:1], v[146:147] op_sel:[0,0,1] op_sel_hi:[1,0,0]
	s_waitcnt lgkmcnt(1)
	v_pk_add_f32 v[146:147], v[116:117], v[148:149]
	v_pk_add_f32 v[116:117], v[116:117], v[148:149] neg_lo:[0,1] neg_hi:[0,1]
	s_mov_b32 s13, s6
	v_add3_u32 v87, v75, v78, v79
	v_or_b32_e32 v75, 0x380, v71
	v_pk_mul_f32 v[148:149], v[116:117], s[12:13]
	ds_read_b64 v[152:153], v90 offset:6144
	ds_read_b64 v[154:155], v89 offset:6400
	ds_read_b64 v[156:157], v88 offset:6656
	ds_read_b64 v[158:159], v87 offset:6912
	v_ashrrev_i32_e32 v75, 2, v75
	v_pk_fma_f32 v[116:117], v[116:117], s[14:15], v[148:149] op_sel:[0,0,1] op_sel_hi:[1,0,0]
	s_waitcnt lgkmcnt(4)
	v_pk_add_f32 v[148:149], v[118:119], v[150:151]
	v_pk_add_f32 v[118:119], v[118:119], v[150:151] neg_lo:[0,1] neg_hi:[0,1]
	s_mov_b32 s35, s20
	v_add_u32_e32 v75, 0, v75
	v_pk_mul_f32 v[150:151], v[118:119], s[34:35]
	s_mov_b32 s44, s19
	v_add3_u32 v86, v75, v78, v79
	v_or_b32_e32 v75, 0x3a0, v71
	v_or_b32_e32 v71, 0x3c0, v71
	v_pk_fma_f32 v[118:119], v[118:119], s[44:45], v[150:151] op_sel:[0,0,1] op_sel_hi:[1,0,0]
	s_waitcnt lgkmcnt(3)
	v_pk_add_f32 v[150:151], v[120:121], v[152:153]
	v_pk_add_f32 v[120:121], v[120:121], v[152:153] neg_lo:[0,1] neg_hi:[0,1]
	v_ashrrev_i32_e32 v71, 2, v71
	v_xor_b32_e32 v153, 0x80000000, v120
	v_mov_b32_e32 v152, v121
	s_waitcnt lgkmcnt(2)
	v_pk_add_f32 v[120:121], v[122:123], v[154:155]
	v_pk_add_f32 v[122:123], v[122:123], v[154:155] neg_lo:[0,1] neg_hi:[0,1]
	v_add_u32_e32 v71, 0, v71
	v_or_b32_e32 v0, 0x3e0, v0
	v_pk_mul_f32 v[154:155], v[122:123], s[34:35]
	v_ashrrev_i32_e32 v75, 2, v75
	v_add3_u32 v84, v71, v78, v79
	v_ashrrev_i32_e32 v71, 2, v0
	v_pk_fma_f32 v[122:123], v[122:123], s[18:19], v[154:155] op_sel:[0,0,1] op_sel_hi:[1,0,0]
	s_waitcnt lgkmcnt(1)
	v_pk_add_f32 v[154:155], v[124:125], v[156:157]
	v_pk_add_f32 v[124:125], v[124:125], v[156:157] neg_lo:[0,1] neg_hi:[0,1]
	v_add_u32_e32 v75, 0, v75
	v_add_u32_e32 v71, 0, v71
	v_lshlrev_b32_e32 v0, 3, v0
	v_pk_mul_f32 v[156:157], v[124:125], s[12:13]
	v_add3_u32 v85, v75, v78, v79
	v_add3_u32 v0, v71, v0, v79
	ds_read_b64 v[160:161], v86 offset:7168
	ds_read_b64 v[162:163], v85 offset:7424
	ds_read_b64 v[164:165], v84 offset:7680
	ds_read_b64 v[166:167], v0
	v_pk_fma_f32 v[124:125], v[124:125], s[4:5], v[156:157] op_sel:[0,0,1] op_sel_hi:[1,0,0]
	s_waitcnt lgkmcnt(4)
	v_pk_add_f32 v[156:157], v[126:127], v[158:159]
	v_pk_add_f32 v[126:127], v[126:127], v[158:159] neg_lo:[0,1] neg_hi:[0,1]
	v_lshlrev_b32_e32 v70, 4, v70
	v_pk_mul_f32 v[158:159], v[126:127], s[26:27]
	v_cvt_f32_u32_e32 v75, v70
	v_pk_fma_f32 v[126:127], v[126:127], s[22:23], v[158:159] op_sel:[0,0,1] op_sel_hi:[1,0,0]
	s_waitcnt lgkmcnt(3)
	v_pk_add_f32 v[158:159], v[128:129], v[160:161]
	v_pk_add_f32 v[128:129], v[128:129], v[160:161] neg_lo:[0,1] neg_hi:[0,1]
	v_and_b32_e32 v74, 0x1fffffe0, v74
	v_pk_mul_f32 v[160:161], v[128:129], s[8:9]
	v_mul_f32_e32 v115, 0x38800000, v75
	v_pk_fma_f32 v[128:129], v[128:129], s[8:9], v[160:161] op_sel:[0,0,1] op_sel_hi:[1,0,0]
	s_waitcnt lgkmcnt(2)
	v_pk_add_f32 v[160:161], v[130:131], v[162:163]
	v_pk_add_f32 v[130:131], v[130:131], v[162:163] neg_lo:[0,1] neg_hi:[0,1]
	v_lshl_add_u32 v74, v74, 3, 0
	v_pk_mul_f32 v[162:163], v[130:131], s[22:23]
	v_sin_f32_e32 v75, v115
	v_pk_fma_f32 v[130:131], v[130:131], s[26:27], v[162:163] op_sel:[0,0,1] op_sel_hi:[1,0,0]
	s_waitcnt lgkmcnt(1)
	v_pk_add_f32 v[162:163], v[132:133], v[164:165]
	v_pk_add_f32 v[132:133], v[132:133], v[164:165] neg_lo:[0,1] neg_hi:[0,1]
	v_add3_u32 v74, v74, v78, v79
	v_pk_mul_f32 v[164:165], v[132:133], s[4:5]
	v_xor_b32_e32 v78, 0x80000000, v75
	v_pk_fma_f32 v[132:133], v[132:133], s[12:13], v[164:165] op_sel:[0,0,1] op_sel_hi:[1,0,0]
	s_waitcnt lgkmcnt(0)
	v_pk_add_f32 v[164:165], v[134:135], v[166:167]
	v_pk_add_f32 v[134:135], v[134:135], v[166:167] neg_lo:[0,1] neg_hi:[0,1]
	v_mov_b32_e32 v79, v75
	v_pk_mul_f32 v[166:167], v[134:135], s[18:19]
	s_add_u32 s41, s56, s42
	v_pk_fma_f32 v[134:135], v[134:135], s[34:35], v[166:167] op_sel:[0,0,1] op_sel_hi:[1,0,0]
	v_pk_add_f32 v[166:167], v[168:169], v[150:151]
	v_pk_add_f32 v[150:151], v[168:169], v[150:151] neg_lo:[0,1] neg_hi:[0,1]
	v_pk_add_f32 v[168:169], v[136:137], v[120:121]
	v_pk_add_f32 v[120:121], v[136:137], v[120:121] neg_lo:[0,1] neg_hi:[0,1]
	s_addc_u32 s61, s57, s43
	v_pk_mul_f32 v[136:137], v[120:121], s[4:5]
	s_nop 0
	v_pk_fma_f32 v[120:121], v[120:121], s[6:7], v[136:137] op_sel:[0,0,1] op_sel_hi:[1,0,0]
	v_pk_add_f32 v[136:137], v[138:139], v[154:155]
	v_pk_add_f32 v[138:139], v[138:139], v[154:155] neg_lo:[0,1] neg_hi:[0,1]
	s_nop 0
	v_pk_mul_f32 v[154:155], v[138:139], s[8:9]
	s_nop 0
	v_pk_fma_f32 v[138:139], v[138:139], s[10:11], v[154:155] op_sel:[0,0,1] op_sel_hi:[1,0,0]
	v_pk_add_f32 v[154:155], v[140:141], v[156:157]
	v_pk_add_f32 v[140:141], v[140:141], v[156:157] neg_lo:[0,1] neg_hi:[0,1]
	s_nop 0
	v_pk_mul_f32 v[156:157], v[140:141], s[12:13]
	s_nop 0
	v_pk_fma_f32 v[140:141], v[140:141], s[14:15], v[156:157] op_sel:[0,0,1] op_sel_hi:[1,0,0]
	v_pk_add_f32 v[156:157], v[142:143], v[158:159]
	v_pk_add_f32 v[142:143], v[142:143], v[158:159] neg_lo:[0,1] neg_hi:[0,1]
	s_nop 0
	v_xor_b32_e32 v159, 0x80000000, v142
	v_mov_b32_e32 v158, v143
	v_pk_add_f32 v[142:143], v[144:145], v[160:161]
	v_pk_add_f32 v[144:145], v[144:145], v[160:161] neg_lo:[0,1] neg_hi:[0,1]
	s_nop 0
	v_pk_mul_f32 v[160:161], v[144:145], s[12:13]
	s_nop 0
	v_pk_fma_f32 v[144:145], v[144:145], s[4:5], v[160:161] op_sel:[0,0,1] op_sel_hi:[1,0,0]
	v_pk_add_f32 v[160:161], v[146:147], v[162:163]
	v_pk_add_f32 v[146:147], v[146:147], v[162:163] neg_lo:[0,1] neg_hi:[0,1]
	s_nop 0
	v_pk_mul_f32 v[162:163], v[146:147], s[8:9]
	s_nop 0
	v_pk_fma_f32 v[146:147], v[146:147], s[8:9], v[162:163] op_sel:[0,0,1] op_sel_hi:[1,0,0]
	v_pk_add_f32 v[162:163], v[148:149], v[164:165]
	v_pk_add_f32 v[148:149], v[148:149], v[164:165] neg_lo:[0,1] neg_hi:[0,1]
	s_nop 0
	v_pk_mul_f32 v[164:165], v[148:149], s[4:5]
	s_nop 0
	v_pk_fma_f32 v[148:149], v[148:149], s[12:13], v[164:165] op_sel:[0,0,1] op_sel_hi:[1,0,0]
	v_pk_add_f32 v[164:165], v[66:67], v[152:153]
	v_pk_add_f32 v[66:67], v[66:67], v[152:153] neg_lo:[0,1] neg_hi:[0,1]
	v_pk_add_f32 v[152:153], v[68:69], v[122:123]
	v_pk_add_f32 v[68:69], v[68:69], v[122:123] neg_lo:[0,1] neg_hi:[0,1]
	s_nop 0
	v_pk_mul_f32 v[122:123], v[68:69], s[4:5]
	s_nop 0
	v_pk_fma_f32 v[68:69], v[68:69], s[6:7], v[122:123] op_sel:[0,0,1] op_sel_hi:[1,0,0]
	v_pk_add_f32 v[122:123], v[72:73], v[124:125]
	v_pk_add_f32 v[72:73], v[72:73], v[124:125] neg_lo:[0,1] neg_hi:[0,1]
	s_nop 0
	v_pk_mul_f32 v[124:125], v[72:73], s[8:9]
	s_nop 0
	v_pk_fma_f32 v[72:73], v[72:73], s[10:11], v[124:125] op_sel:[0,0,1] op_sel_hi:[1,0,0]
	v_pk_add_f32 v[124:125], v[76:77], v[126:127]
	v_pk_add_f32 v[76:77], v[76:77], v[126:127] neg_lo:[0,1] neg_hi:[0,1]
	s_nop 0
	v_pk_mul_f32 v[126:127], v[76:77], s[12:13]
	s_nop 0
	v_pk_fma_f32 v[76:77], v[76:77], s[14:15], v[126:127] op_sel:[0,0,1] op_sel_hi:[1,0,0]
	v_pk_add_f32 v[126:127], v[80:81], v[128:129]
	v_pk_add_f32 v[80:81], v[80:81], v[128:129] neg_lo:[0,1] neg_hi:[0,1]
	s_nop 0
	v_xor_b32_e32 v129, 0x80000000, v80
	v_mov_b32_e32 v128, v81
	v_pk_add_f32 v[80:81], v[82:83], v[130:131]
	v_pk_add_f32 v[82:83], v[82:83], v[130:131] neg_lo:[0,1] neg_hi:[0,1]
	s_nop 0
	v_pk_mul_f32 v[130:131], v[82:83], s[12:13]
	s_nop 0
	v_pk_fma_f32 v[82:83], v[82:83], s[4:5], v[130:131] op_sel:[0,0,1] op_sel_hi:[1,0,0]
	v_pk_add_f32 v[130:131], v[116:117], v[132:133]
	v_pk_add_f32 v[116:117], v[116:117], v[132:133] neg_lo:[0,1] neg_hi:[0,1]
	s_nop 0
	v_pk_mul_f32 v[132:133], v[116:117], s[8:9]
	s_nop 0
	v_pk_fma_f32 v[116:117], v[116:117], s[8:9], v[132:133] op_sel:[0,0,1] op_sel_hi:[1,0,0]
	v_pk_add_f32 v[132:133], v[118:119], v[134:135]
	v_pk_add_f32 v[118:119], v[118:119], v[134:135] neg_lo:[0,1] neg_hi:[0,1]
	s_nop 0
	v_pk_mul_f32 v[134:135], v[118:119], s[4:5]
	s_nop 0
	v_pk_fma_f32 v[118:119], v[118:119], s[12:13], v[134:135] op_sel:[0,0,1] op_sel_hi:[1,0,0]
	v_pk_add_f32 v[134:135], v[166:167], v[156:157]
	v_pk_add_f32 v[156:157], v[166:167], v[156:157] neg_lo:[0,1] neg_hi:[0,1]
	v_pk_add_f32 v[166:167], v[168:169], v[142:143]
	v_pk_add_f32 v[142:143], v[168:169], v[142:143] neg_lo:[0,1] neg_hi:[0,1]
	s_nop 0
	v_pk_mul_f32 v[168:169], v[142:143], s[8:9]
	s_nop 0
	v_pk_fma_f32 v[142:143], v[142:143], s[10:11], v[168:169] op_sel:[0,0,1] op_sel_hi:[1,0,0]
	v_pk_add_f32 v[168:169], v[136:137], v[160:161]
	v_pk_add_f32 v[136:137], v[136:137], v[160:161] neg_lo:[0,1] neg_hi:[0,1]
	s_nop 0
	v_xor_b32_e32 v161, 0x80000000, v136
	v_mov_b32_e32 v160, v137
	v_pk_add_f32 v[136:137], v[154:155], v[162:163]
	v_pk_add_f32 v[154:155], v[154:155], v[162:163] neg_lo:[0,1] neg_hi:[0,1]
	s_nop 0
	v_pk_mul_f32 v[162:163], v[154:155], s[8:9]
	s_nop 0
	v_pk_fma_f32 v[154:155], v[154:155], s[8:9], v[162:163] op_sel:[0,0,1] op_sel_hi:[1,0,0]
	v_pk_add_f32 v[162:163], v[150:151], v[158:159]
	v_pk_add_f32 v[150:151], v[150:151], v[158:159] neg_lo:[0,1] neg_hi:[0,1]
	v_pk_add_f32 v[158:159], v[120:121], v[144:145]
	v_pk_add_f32 v[120:121], v[120:121], v[144:145] neg_lo:[0,1] neg_hi:[0,1]
	s_nop 0
	v_pk_mul_f32 v[144:145], v[120:121], s[8:9]
	s_nop 0
	v_pk_fma_f32 v[120:121], v[120:121], s[10:11], v[144:145] op_sel:[0,0,1] op_sel_hi:[1,0,0]
	v_pk_add_f32 v[144:145], v[138:139], v[146:147]
	v_pk_add_f32 v[138:139], v[138:139], v[146:147] neg_lo:[0,1] neg_hi:[0,1]
	s_nop 0
	v_xor_b32_e32 v147, 0x80000000, v138
	v_mov_b32_e32 v146, v139
	v_pk_add_f32 v[138:139], v[140:141], v[148:149]
	v_pk_add_f32 v[140:141], v[140:141], v[148:149] neg_lo:[0,1] neg_hi:[0,1]
	s_nop 0
	v_pk_mul_f32 v[148:149], v[140:141], s[8:9]
	s_nop 0
	v_pk_fma_f32 v[140:141], v[140:141], s[8:9], v[148:149] op_sel:[0,0,1] op_sel_hi:[1,0,0]
	v_pk_add_f32 v[148:149], v[164:165], v[126:127]
	v_pk_add_f32 v[126:127], v[164:165], v[126:127] neg_lo:[0,1] neg_hi:[0,1]
	v_pk_add_f32 v[164:165], v[152:153], v[80:81]
	v_pk_add_f32 v[80:81], v[152:153], v[80:81] neg_lo:[0,1] neg_hi:[0,1]
	s_nop 0
	v_pk_mul_f32 v[152:153], v[80:81], s[8:9]
	s_nop 0
	v_pk_fma_f32 v[80:81], v[80:81], s[10:11], v[152:153] op_sel:[0,0,1] op_sel_hi:[1,0,0]
	v_pk_add_f32 v[152:153], v[122:123], v[130:131]
	v_pk_add_f32 v[122:123], v[122:123], v[130:131] neg_lo:[0,1] neg_hi:[0,1]
	s_nop 0
	v_xor_b32_e32 v131, 0x80000000, v122
	v_mov_b32_e32 v130, v123
	v_pk_add_f32 v[122:123], v[124:125], v[132:133]
	v_pk_add_f32 v[124:125], v[124:125], v[132:133] neg_lo:[0,1] neg_hi:[0,1]
	s_nop 0
	v_pk_mul_f32 v[132:133], v[124:125], s[8:9]
	s_nop 0
	v_pk_fma_f32 v[124:125], v[124:125], s[8:9], v[132:133] op_sel:[0,0,1] op_sel_hi:[1,0,0]
	v_pk_add_f32 v[132:133], v[66:67], v[128:129]
	v_pk_add_f32 v[66:67], v[66:67], v[128:129] neg_lo:[0,1] neg_hi:[0,1]
	v_pk_add_f32 v[128:129], v[68:69], v[82:83]
	v_pk_add_f32 v[68:69], v[68:69], v[82:83] neg_lo:[0,1] neg_hi:[0,1]
	s_nop 0
	v_pk_mul_f32 v[82:83], v[68:69], s[8:9]
	s_nop 0
	v_pk_fma_f32 v[68:69], v[68:69], s[10:11], v[82:83] op_sel:[0,0,1] op_sel_hi:[1,0,0]
	v_pk_add_f32 v[82:83], v[72:73], v[116:117]
	v_pk_add_f32 v[72:73], v[72:73], v[116:117] neg_lo:[0,1] neg_hi:[0,1]
	s_nop 0
	v_xor_b32_e32 v117, 0x80000000, v72
	v_mov_b32_e32 v116, v73
	v_pk_add_f32 v[72:73], v[76:77], v[118:119]
	v_pk_add_f32 v[76:77], v[76:77], v[118:119] neg_lo:[0,1] neg_hi:[0,1]
	v_pk_add_f32 v[174:175], v[66:67], v[116:117]
	v_pk_mul_f32 v[118:119], v[76:77], s[8:9]
	v_pk_add_f32 v[116:117], v[66:67], v[116:117] neg_lo:[0,1] neg_hi:[0,1]
	v_pk_fma_f32 v[76:77], v[76:77], s[8:9], v[118:119] op_sel:[0,0,1] op_sel_hi:[1,0,0]
	v_pk_add_f32 v[118:119], v[134:135], v[168:169]
	v_pk_add_f32 v[134:135], v[134:135], v[168:169] neg_lo:[0,1] neg_hi:[0,1]
	v_pk_add_f32 v[168:169], v[166:167], v[136:137]
	v_pk_add_f32 v[136:137], v[166:167], v[136:137] neg_lo:[0,1] neg_hi:[0,1]
	v_pk_add_f32 v[180:181], v[118:119], v[168:169]
	v_xor_b32_e32 v167, 0x80000000, v136
	v_mov_b32_e32 v166, v137
	v_pk_add_f32 v[136:137], v[156:157], v[160:161]
	v_pk_add_f32 v[156:157], v[156:157], v[160:161] neg_lo:[0,1] neg_hi:[0,1]
	v_pk_add_f32 v[160:161], v[142:143], v[154:155]
	v_pk_add_f32 v[142:143], v[142:143], v[154:155] neg_lo:[0,1] neg_hi:[0,1]
	v_pk_add_f32 v[66:67], v[68:69], v[76:77] neg_lo:[0,1] neg_hi:[0,1]
	v_xor_b32_e32 v155, 0x80000000, v142
	v_mov_b32_e32 v154, v143
	v_pk_add_f32 v[142:143], v[162:163], v[144:145]
	v_pk_add_f32 v[144:145], v[162:163], v[144:145] neg_lo:[0,1] neg_hi:[0,1]
	v_pk_add_f32 v[162:163], v[158:159], v[138:139]
	v_pk_add_f32 v[138:139], v[158:159], v[138:139] neg_lo:[0,1] neg_hi:[0,1]
	ds_write_b64 v74, v[180:181]
	v_xor_b32_e32 v159, 0x80000000, v138
	v_mov_b32_e32 v158, v139
	v_pk_add_f32 v[138:139], v[150:151], v[146:147]
	v_pk_add_f32 v[146:147], v[150:151], v[146:147] neg_lo:[0,1] neg_hi:[0,1]
	v_pk_add_f32 v[150:151], v[120:121], v[140:141]
	v_pk_add_f32 v[120:121], v[120:121], v[140:141] neg_lo:[0,1] neg_hi:[0,1]
	v_cos_f32_e32 v74, v115
	v_xor_b32_e32 v141, 0x80000000, v120
	v_mov_b32_e32 v140, v121
	v_pk_add_f32 v[120:121], v[148:149], v[152:153]
	v_pk_add_f32 v[148:149], v[148:149], v[152:153] neg_lo:[0,1] neg_hi:[0,1]
	v_pk_add_f32 v[152:153], v[164:165], v[122:123]
	v_pk_add_f32 v[122:123], v[164:165], v[122:123] neg_lo:[0,1] neg_hi:[0,1]
	v_xor_b32_e32 v179, 0x80000000, v66
	v_xor_b32_e32 v165, 0x80000000, v122
	v_mov_b32_e32 v164, v123
	v_pk_add_f32 v[122:123], v[126:127], v[130:131]
	v_pk_add_f32 v[126:127], v[126:127], v[130:131] neg_lo:[0,1] neg_hi:[0,1]
	v_pk_add_f32 v[130:131], v[80:81], v[124:125]
	v_pk_add_f32 v[80:81], v[80:81], v[124:125] neg_lo:[0,1] neg_hi:[0,1]
	v_mov_b32_e32 v178, v67
	v_xor_b32_e32 v125, 0x80000000, v80
	v_mov_b32_e32 v124, v81
	v_pk_add_f32 v[80:81], v[132:133], v[82:83]
	v_pk_add_f32 v[132:133], v[132:133], v[82:83] neg_lo:[0,1] neg_hi:[0,1]
	v_pk_add_f32 v[176:177], v[68:69], v[76:77]
	v_pk_add_f32 v[118:119], v[118:119], v[168:169] neg_lo:[0,1] neg_hi:[0,1]
	v_pk_add_f32 v[168:169], v[134:135], v[166:167]
	v_pk_add_f32 v[82:83], v[134:135], v[166:167] neg_lo:[0,1] neg_hi:[0,1]
	v_pk_add_f32 v[134:135], v[136:137], v[160:161]
	v_pk_add_f32 v[136:137], v[136:137], v[160:161] neg_lo:[0,1] neg_hi:[0,1]
	v_pk_add_f32 v[160:161], v[156:157], v[154:155]
	v_pk_add_f32 v[68:69], v[156:157], v[154:155] neg_lo:[0,1] neg_hi:[0,1]
	v_pk_add_f32 v[154:155], v[142:143], v[162:163]
	v_pk_add_f32 v[142:143], v[142:143], v[162:163] neg_lo:[0,1] neg_hi:[0,1]
	v_pk_add_f32 v[156:157], v[144:145], v[158:159]
	v_pk_add_f32 v[76:77], v[144:145], v[158:159] neg_lo:[0,1] neg_hi:[0,1]
	v_pk_add_f32 v[144:145], v[138:139], v[150:151]
	v_pk_add_f32 v[138:139], v[138:139], v[150:151] neg_lo:[0,1] neg_hi:[0,1]
	v_pk_add_f32 v[150:151], v[146:147], v[140:141]
	v_pk_add_f32 v[66:67], v[146:147], v[140:141] neg_lo:[0,1] neg_hi:[0,1]
	v_pk_add_f32 v[140:141], v[120:121], v[152:153]
	v_pk_add_f32 v[162:163], v[116:117], v[178:179]
	v_pk_add_f32 v[70:71], v[116:117], v[178:179] neg_lo:[0,1] neg_hi:[0,1]
	v_mov_b32_e32 v116, v75
	v_pk_mul_f32 v[116:117], v[116:117], v[140:141] op_sel:[0,1] op_sel_hi:[0,0] neg_hi:[1,0]
	v_pk_fma_f32 v[116:117], v[140:141], v[74:75], v[116:117] op_sel_hi:[1,0,1]
	ds_write_b64 v114, v[116:117] offset:256
	v_pk_mul_f32 v[114:115], v[78:79], v[74:75] op_sel:[0,1] op_sel_hi:[1,0]
	v_pk_add_f32 v[172:173], v[128:129], v[72:73]
	v_pk_fma_f32 v[114:115], v[74:75], v[74:75], v[114:115] op_sel_hi:[1,0,1]
	v_pk_add_f32 v[72:73], v[128:129], v[72:73] neg_lo:[0,1] neg_hi:[0,1]
	v_pk_add_f32 v[116:117], v[114:115], 0 neg_lo:[1,1] neg_hi:[1,1]
	v_xor_b32_e32 v129, 0x80000000, v72
	v_mov_b32_e32 v116, v115
	v_pk_mul_f32 v[116:117], v[116:117], v[154:155] op_sel:[0,1] op_sel_hi:[1,0]
	v_mov_b32_e32 v128, v73
	v_pk_fma_f32 v[116:117], v[154:155], v[114:115], v[116:117] op_sel_hi:[1,0,1]
	ds_write_b64 v113, v[116:117] offset:512
	v_pk_mul_f32 v[116:117], v[78:79], v[114:115] op_sel:[0,1] op_sel_hi:[1,0]
	v_pk_add_f32 v[120:121], v[120:121], v[152:153] neg_lo:[0,1] neg_hi:[0,1]
	v_pk_fma_f32 v[114:115], v[114:115], v[74:75], v[116:117] op_sel_hi:[1,0,1]
	v_pk_add_f32 v[152:153], v[122:123], v[130:131]
	v_pk_add_f32 v[116:117], v[114:115], 0 neg_lo:[1,1] neg_hi:[1,1]
	v_pk_add_f32 v[122:123], v[122:123], v[130:131] neg_lo:[0,1] neg_hi:[0,1]
	v_pk_add_f32 v[130:131], v[126:127], v[124:125]
	v_pk_add_f32 v[72:73], v[126:127], v[124:125] neg_lo:[0,1] neg_hi:[0,1]
	v_pk_add_f32 v[124:125], v[80:81], v[172:173]
	v_mov_b32_e32 v116, v115
	v_pk_mul_f32 v[116:117], v[116:117], v[124:125] op_sel:[0,1] op_sel_hi:[1,0]
	v_pk_add_f32 v[126:127], v[80:81], v[172:173] neg_lo:[0,1] neg_hi:[0,1]
	v_pk_fma_f32 v[116:117], v[124:125], v[114:115], v[116:117] op_sel_hi:[1,0,1]
	ds_write_b64 v112, v[116:117] offset:768
	v_pk_mul_f32 v[112:113], v[78:79], v[114:115] op_sel:[0,1] op_sel_hi:[1,0]
	v_pk_add_f32 v[158:159], v[132:133], v[128:129]
	v_pk_fma_f32 v[112:113], v[114:115], v[74:75], v[112:113] op_sel_hi:[1,0,1]
	v_pk_add_f32 v[80:81], v[132:133], v[128:129] neg_lo:[0,1] neg_hi:[0,1]
	v_pk_add_f32 v[114:115], v[112:113], 0 neg_lo:[1,1] neg_hi:[1,1]
	v_pk_add_f32 v[128:129], v[174:175], v[176:177]
	v_mov_b32_e32 v114, v113
	v_pk_mul_f32 v[114:115], v[114:115], v[134:135] op_sel:[0,1] op_sel_hi:[1,0]
	v_pk_add_f32 v[146:147], v[148:149], v[164:165]
	v_pk_fma_f32 v[114:115], v[134:135], v[112:113], v[114:115] op_sel_hi:[1,0,1]
	ds_write_b64 v111, v[114:115] offset:1024
	v_pk_mul_f32 v[114:115], v[78:79], v[112:113] op_sel:[0,1] op_sel_hi:[1,0]
	v_pk_add_f32 v[132:133], v[174:175], v[176:177] neg_lo:[0,1] neg_hi:[0,1]
	v_pk_fma_f32 v[112:113], v[112:113], v[74:75], v[114:115] op_sel_hi:[1,0,1]
	v_pk_add_f32 v[148:149], v[148:149], v[164:165] neg_lo:[0,1] neg_hi:[0,1]
	v_pk_add_f32 v[114:115], v[112:113], 0 neg_lo:[1,1] neg_hi:[1,1]
	s_nop 0
	v_mov_b32_e32 v114, v113
	v_pk_mul_f32 v[114:115], v[114:115], v[152:153] op_sel:[0,1] op_sel_hi:[1,0]
	s_nop 0
	v_pk_fma_f32 v[114:115], v[152:153], v[112:113], v[114:115] op_sel_hi:[1,0,1]
	ds_write_b64 v110, v[114:115] offset:1280
	v_pk_mul_f32 v[110:111], v[78:79], v[112:113] op_sel:[0,1] op_sel_hi:[1,0]
	s_nop 0
	v_pk_fma_f32 v[110:111], v[112:113], v[74:75], v[110:111] op_sel_hi:[1,0,1]
	s_nop 0
	v_pk_add_f32 v[112:113], v[110:111], 0 neg_lo:[1,1] neg_hi:[1,1]
	s_nop 0
	v_mov_b32_e32 v112, v111
	v_pk_mul_f32 v[112:113], v[112:113], v[144:145] op_sel:[0,1] op_sel_hi:[1,0]
	s_nop 0
	v_pk_fma_f32 v[112:113], v[144:145], v[110:111], v[112:113] op_sel_hi:[1,0,1]
	ds_write_b64 v109, v[112:113] offset:1536
	v_pk_mul_f32 v[112:113], v[78:79], v[110:111] op_sel:[0,1] op_sel_hi:[1,0]
	s_nop 0
	v_pk_fma_f32 v[110:111], v[110:111], v[74:75], v[112:113] op_sel_hi:[1,0,1]
	s_nop 0
	v_pk_add_f32 v[112:113], v[110:111], 0 neg_lo:[1,1] neg_hi:[1,1]
	s_nop 0
	v_mov_b32_e32 v112, v111
	v_pk_mul_f32 v[112:113], v[112:113], v[128:129] op_sel:[0,1] op_sel_hi:[1,0]
	s_nop 0
	v_pk_fma_f32 v[112:113], v[128:129], v[110:111], v[112:113] op_sel_hi:[1,0,1]
	ds_write_b64 v108, v[112:113] offset:1792
	v_pk_mul_f32 v[108:109], v[78:79], v[110:111] op_sel:[0,1] op_sel_hi:[1,0]
	s_nop 0
	v_pk_fma_f32 v[108:109], v[110:111], v[74:75], v[108:109] op_sel_hi:[1,0,1]
	s_nop 0
	v_pk_add_f32 v[110:111], v[108:109], 0 neg_lo:[1,1] neg_hi:[1,1]
	s_nop 0
	v_mov_b32_e32 v110, v109
	v_pk_mul_f32 v[110:111], v[110:111], v[168:169] op_sel:[0,1] op_sel_hi:[1,0]
	s_nop 0
	v_pk_fma_f32 v[110:111], v[168:169], v[108:109], v[110:111] op_sel_hi:[1,0,1]
	ds_write_b64 v107, v[110:111] offset:2048
	v_pk_mul_f32 v[110:111], v[78:79], v[108:109] op_sel:[0,1] op_sel_hi:[1,0]
	s_nop 0
	v_pk_fma_f32 v[108:109], v[108:109], v[74:75], v[110:111] op_sel_hi:[1,0,1]
	s_nop 0
	v_pk_add_f32 v[110:111], v[108:109], 0 neg_lo:[1,1] neg_hi:[1,1]
	s_nop 0
	v_mov_b32_e32 v110, v109
	v_pk_mul_f32 v[110:111], v[110:111], v[146:147] op_sel:[0,1] op_sel_hi:[1,0]
	s_nop 0
	v_pk_fma_f32 v[110:111], v[146:147], v[108:109], v[110:111] op_sel_hi:[1,0,1]
	ds_write_b64 v106, v[110:111] offset:2304
	v_pk_mul_f32 v[106:107], v[78:79], v[108:109] op_sel:[0,1] op_sel_hi:[1,0]
	s_nop 0
	v_pk_fma_f32 v[106:107], v[108:109], v[74:75], v[106:107] op_sel_hi:[1,0,1]
	s_nop 0
	v_pk_add_f32 v[108:109], v[106:107], 0 neg_lo:[1,1] neg_hi:[1,1]
	s_nop 0
	v_mov_b32_e32 v108, v107
	v_pk_mul_f32 v[108:109], v[108:109], v[156:157] op_sel:[0,1] op_sel_hi:[1,0]
	s_nop 0
	v_pk_fma_f32 v[108:109], v[156:157], v[106:107], v[108:109] op_sel_hi:[1,0,1]
	ds_write_b64 v105, v[108:109] offset:2560
	v_pk_mul_f32 v[108:109], v[78:79], v[106:107] op_sel:[0,1] op_sel_hi:[1,0]
	s_nop 0
	v_pk_fma_f32 v[106:107], v[106:107], v[74:75], v[108:109] op_sel_hi:[1,0,1]
	s_nop 0
	v_pk_add_f32 v[108:109], v[106:107], 0 neg_lo:[1,1] neg_hi:[1,1]
	s_nop 0
	v_mov_b32_e32 v108, v107
	v_pk_mul_f32 v[108:109], v[108:109], v[158:159] op_sel:[0,1] op_sel_hi:[1,0]
	s_nop 0
	v_pk_fma_f32 v[108:109], v[158:159], v[106:107], v[108:109] op_sel_hi:[1,0,1]
	ds_write_b64 v103, v[108:109] offset:2816
	v_pk_mul_f32 v[108:109], v[78:79], v[106:107] op_sel:[0,1] op_sel_hi:[1,0]
	s_nop 0
	v_pk_fma_f32 v[106:107], v[106:107], v[74:75], v[108:109] op_sel_hi:[1,0,1]
	s_nop 0
	v_pk_add_f32 v[108:109], v[106:107], 0 neg_lo:[1,1] neg_hi:[1,1]
	s_nop 0
	v_mov_b32_e32 v108, v107
	v_pk_mul_f32 v[108:109], v[108:109], v[160:161] op_sel:[0,1] op_sel_hi:[1,0]
	s_nop 0
	v_pk_fma_f32 v[108:109], v[160:161], v[106:107], v[108:109] op_sel_hi:[1,0,1]
	ds_write_b64 v102, v[108:109] offset:3072
	v_pk_mul_f32 v[102:103], v[78:79], v[106:107] op_sel:[0,1] op_sel_hi:[1,0]
	s_nop 0
	v_pk_fma_f32 v[102:103], v[106:107], v[74:75], v[102:103] op_sel_hi:[1,0,1]
	s_nop 0
	v_pk_add_f32 v[106:107], v[102:103], 0 neg_lo:[1,1] neg_hi:[1,1]
	s_nop 0
	v_mov_b32_e32 v106, v103
	v_pk_mul_f32 v[106:107], v[106:107], v[130:131] op_sel:[0,1] op_sel_hi:[1,0]
	s_nop 0
	v_pk_fma_f32 v[106:107], v[130:131], v[102:103], v[106:107] op_sel_hi:[1,0,1]
	ds_write_b64 v101, v[106:107] offset:3328
	v_pk_mul_f32 v[106:107], v[78:79], v[102:103] op_sel:[0,1] op_sel_hi:[1,0]
	s_nop 0
	v_pk_fma_f32 v[102:103], v[102:103], v[74:75], v[106:107] op_sel_hi:[1,0,1]
	s_nop 0
	v_pk_add_f32 v[106:107], v[102:103], 0 neg_lo:[1,1] neg_hi:[1,1]
	s_nop 0
	v_mov_b32_e32 v106, v103
	v_pk_mul_f32 v[106:107], v[150:151], v[106:107] op_sel:[1,0] op_sel_hi:[0,1]
	v_pk_fma_f32 v[106:107], v[150:151], v[102:103], v[106:107] op_sel_hi:[1,0,1]
	ds_write_b64 v100, v[106:107] offset:3584
	v_pk_mul_f32 v[100:101], v[78:79], v[102:103] op_sel:[0,1] op_sel_hi:[1,0]
	s_nop 0
	v_pk_fma_f32 v[100:101], v[102:103], v[74:75], v[100:101] op_sel_hi:[1,0,1]
	s_nop 0
	v_pk_add_f32 v[102:103], v[100:101], 0 neg_lo:[1,1] neg_hi:[1,1]
	s_nop 0
	v_mov_b32_e32 v102, v101
	v_pk_mul_f32 v[102:103], v[162:163], v[102:103] op_sel:[1,0] op_sel_hi:[0,1]
	v_pk_fma_f32 v[102:103], v[162:163], v[100:101], v[102:103] op_sel_hi:[1,0,1]
	ds_write_b64 v99, v[102:103] offset:3840
	v_pk_mul_f32 v[102:103], v[78:79], v[100:101] op_sel:[0,1] op_sel_hi:[1,0]
	s_nop 0
	v_pk_fma_f32 v[100:101], v[100:101], v[74:75], v[102:103] op_sel_hi:[1,0,1]
	s_nop 0
	v_pk_add_f32 v[102:103], v[100:101], 0 neg_lo:[1,1] neg_hi:[1,1]
	s_nop 0
	v_mov_b32_e32 v102, v101
	v_pk_mul_f32 v[102:103], v[118:119], v[102:103] op_sel:[1,0] op_sel_hi:[0,1]
	v_pk_fma_f32 v[102:103], v[118:119], v[100:101], v[102:103] op_sel_hi:[1,0,1]
	ds_write_b64 v98, v[102:103] offset:4096
	v_pk_mul_f32 v[98:99], v[78:79], v[100:101] op_sel:[0,1] op_sel_hi:[1,0]
	s_nop 0
	v_pk_fma_f32 v[98:99], v[100:101], v[74:75], v[98:99] op_sel_hi:[1,0,1]
	s_nop 0
	v_pk_add_f32 v[100:101], v[98:99], 0 neg_lo:[1,1] neg_hi:[1,1]
	s_nop 0
	v_mov_b32_e32 v100, v99
	v_pk_mul_f32 v[100:101], v[120:121], v[100:101] op_sel:[1,0] op_sel_hi:[0,1]
	v_pk_fma_f32 v[100:101], v[120:121], v[98:99], v[100:101] op_sel_hi:[1,0,1]
	ds_write_b64 v97, v[100:101] offset:4352
	v_pk_mul_f32 v[100:101], v[78:79], v[98:99] op_sel:[0,1] op_sel_hi:[1,0]
	s_nop 0
	v_pk_fma_f32 v[98:99], v[98:99], v[74:75], v[100:101] op_sel_hi:[1,0,1]
	s_nop 0
	v_pk_add_f32 v[100:101], v[98:99], 0 neg_lo:[1,1] neg_hi:[1,1]
	s_nop 0
	v_mov_b32_e32 v100, v99
	v_pk_mul_f32 v[100:101], v[142:143], v[100:101] op_sel:[1,0] op_sel_hi:[0,1]
	v_pk_fma_f32 v[100:101], v[142:143], v[98:99], v[100:101] op_sel_hi:[1,0,1]
	ds_write_b64 v96, v[100:101] offset:4608
	v_pk_mul_f32 v[96:97], v[78:79], v[98:99] op_sel:[0,1] op_sel_hi:[1,0]
	s_nop 0
	v_pk_fma_f32 v[96:97], v[98:99], v[74:75], v[96:97] op_sel_hi:[1,0,1]
	s_nop 0
	v_pk_add_f32 v[98:99], v[96:97], 0 neg_lo:[1,1] neg_hi:[1,1]
	s_nop 0
	v_mov_b32_e32 v98, v97
	v_pk_mul_f32 v[98:99], v[126:127], v[98:99] op_sel:[1,0] op_sel_hi:[0,1]
	v_pk_fma_f32 v[98:99], v[126:127], v[96:97], v[98:99] op_sel_hi:[1,0,1]
	ds_write_b64 v95, v[98:99] offset:4864
	v_pk_mul_f32 v[98:99], v[78:79], v[96:97] op_sel:[0,1] op_sel_hi:[1,0]
	s_nop 0
	v_pk_fma_f32 v[96:97], v[96:97], v[74:75], v[98:99] op_sel_hi:[1,0,1]
	s_nop 0
	v_pk_add_f32 v[98:99], v[96:97], 0 neg_lo:[1,1] neg_hi:[1,1]
	s_nop 0
	v_mov_b32_e32 v98, v97
	v_pk_mul_f32 v[98:99], v[136:137], v[98:99] op_sel:[1,0] op_sel_hi:[0,1]
	v_pk_fma_f32 v[98:99], v[136:137], v[96:97], v[98:99] op_sel_hi:[1,0,1]
	ds_write_b64 v94, v[98:99] offset:5120
	v_pk_mul_f32 v[94:95], v[78:79], v[96:97] op_sel:[0,1] op_sel_hi:[1,0]
	s_nop 0
	v_pk_fma_f32 v[94:95], v[96:97], v[74:75], v[94:95] op_sel_hi:[1,0,1]
	s_nop 0
	v_pk_add_f32 v[96:97], v[94:95], 0 neg_lo:[1,1] neg_hi:[1,1]
	s_nop 0
	v_mov_b32_e32 v96, v95
	v_pk_mul_f32 v[96:97], v[122:123], v[96:97] op_sel:[1,0] op_sel_hi:[0,1]
	v_pk_fma_f32 v[96:97], v[122:123], v[94:95], v[96:97] op_sel_hi:[1,0,1]
	ds_write_b64 v93, v[96:97] offset:5376
	v_pk_mul_f32 v[96:97], v[78:79], v[94:95] op_sel:[0,1] op_sel_hi:[1,0]
	s_nop 0
	v_pk_fma_f32 v[94:95], v[94:95], v[74:75], v[96:97] op_sel_hi:[1,0,1]
	s_nop 0
	v_pk_add_f32 v[96:97], v[94:95], 0 neg_lo:[1,1] neg_hi:[1,1]
	s_nop 0
	v_mov_b32_e32 v96, v95
	v_pk_mul_f32 v[96:97], v[138:139], v[96:97] op_sel:[1,0] op_sel_hi:[0,1]
	v_pk_fma_f32 v[96:97], v[138:139], v[94:95], v[96:97] op_sel_hi:[1,0,1]
	ds_write_b64 v92, v[96:97] offset:5632
	v_pk_mul_f32 v[92:93], v[78:79], v[94:95] op_sel:[0,1] op_sel_hi:[1,0]
	s_nop 0
	v_pk_fma_f32 v[92:93], v[94:95], v[74:75], v[92:93] op_sel_hi:[1,0,1]
	s_nop 0
	v_pk_add_f32 v[94:95], v[92:93], 0 neg_lo:[1,1] neg_hi:[1,1]
	s_nop 0
	v_mov_b32_e32 v94, v93
	v_pk_mul_f32 v[94:95], v[132:133], v[94:95] op_sel:[1,0] op_sel_hi:[0,1]
	v_pk_fma_f32 v[94:95], v[132:133], v[92:93], v[94:95] op_sel_hi:[1,0,1]
	ds_write_b64 v91, v[94:95] offset:5888
	v_pk_mul_f32 v[94:95], v[78:79], v[92:93] op_sel:[0,1] op_sel_hi:[1,0]
	s_nop 0
	v_pk_fma_f32 v[92:93], v[92:93], v[74:75], v[94:95] op_sel_hi:[1,0,1]
	s_nop 0
	v_pk_add_f32 v[94:95], v[92:93], 0 neg_lo:[1,1] neg_hi:[1,1]
	s_nop 0
	v_mov_b32_e32 v94, v93
	v_pk_mul_f32 v[94:95], v[82:83], v[94:95] op_sel:[1,0] op_sel_hi:[0,1]
	v_pk_fma_f32 v[82:83], v[82:83], v[92:93], v[94:95] op_sel_hi:[1,0,1]
	ds_write_b64 v90, v[82:83] offset:6144
	v_pk_mul_f32 v[82:83], v[78:79], v[92:93] op_sel:[0,1] op_sel_hi:[1,0]
	s_nop 0
	v_pk_fma_f32 v[82:83], v[92:93], v[74:75], v[82:83] op_sel_hi:[1,0,1]
	s_nop 0
	v_pk_add_f32 v[90:91], v[82:83], 0 neg_lo:[1,1] neg_hi:[1,1]
	s_nop 0
	v_mov_b32_e32 v90, v83
	v_pk_mul_f32 v[90:91], v[148:149], v[90:91] op_sel:[1,0] op_sel_hi:[0,1]
	v_pk_fma_f32 v[90:91], v[148:149], v[82:83], v[90:91] op_sel_hi:[1,0,1]
	ds_write_b64 v89, v[90:91] offset:6400
	v_pk_mul_f32 v[90:91], v[78:79], v[82:83] op_sel:[0,1] op_sel_hi:[1,0]
	s_nop 0
	v_pk_fma_f32 v[82:83], v[82:83], v[74:75], v[90:91] op_sel_hi:[1,0,1]
	s_nop 0
	v_pk_add_f32 v[90:91], v[82:83], 0 neg_lo:[1,1] neg_hi:[1,1]
	s_nop 0
	v_mov_b32_e32 v90, v83
	v_pk_mul_f32 v[90:91], v[76:77], v[90:91] op_sel:[1,0] op_sel_hi:[0,1]
	v_pk_fma_f32 v[76:77], v[76:77], v[82:83], v[90:91] op_sel_hi:[1,0,1]
	ds_write_b64 v88, v[76:77] offset:6656
	v_pk_mul_f32 v[76:77], v[78:79], v[82:83] op_sel:[0,1] op_sel_hi:[1,0]
	s_nop 0
	v_pk_fma_f32 v[76:77], v[82:83], v[74:75], v[76:77] op_sel_hi:[1,0,1]
	s_nop 0
	v_pk_add_f32 v[82:83], v[76:77], 0 neg_lo:[1,1] neg_hi:[1,1]
	s_nop 0
	v_mov_b32_e32 v82, v77
	v_pk_mul_f32 v[82:83], v[80:81], v[82:83] op_sel:[1,0] op_sel_hi:[0,1]
	v_pk_fma_f32 v[80:81], v[80:81], v[76:77], v[82:83] op_sel_hi:[1,0,1]
	ds_write_b64 v87, v[80:81] offset:6912
	v_pk_mul_f32 v[80:81], v[78:79], v[76:77] op_sel:[0,1] op_sel_hi:[1,0]
	s_nop 0
	v_pk_fma_f32 v[76:77], v[76:77], v[74:75], v[80:81] op_sel_hi:[1,0,1]
	s_nop 0
	v_pk_add_f32 v[80:81], v[76:77], 0 neg_lo:[1,1] neg_hi:[1,1]
	s_nop 0
	v_mov_b32_e32 v80, v77
	v_pk_mul_f32 v[80:81], v[68:69], v[80:81] op_sel:[1,0] op_sel_hi:[0,1]
	v_pk_fma_f32 v[68:69], v[68:69], v[76:77], v[80:81] op_sel_hi:[1,0,1]
	ds_write_b64 v86, v[68:69] offset:7168
	v_pk_mul_f32 v[68:69], v[78:79], v[76:77] op_sel:[0,1] op_sel_hi:[1,0]
	s_nop 0
	v_pk_fma_f32 v[68:69], v[76:77], v[74:75], v[68:69] op_sel_hi:[1,0,1]
	s_nop 0
	v_pk_add_f32 v[76:77], v[68:69], 0 neg_lo:[1,1] neg_hi:[1,1]
	s_nop 0
	v_mov_b32_e32 v76, v69
	v_pk_mul_f32 v[76:77], v[72:73], v[76:77] op_sel:[1,0] op_sel_hi:[0,1]
	v_pk_fma_f32 v[72:73], v[72:73], v[68:69], v[76:77] op_sel_hi:[1,0,1]
	ds_write_b64 v85, v[72:73] offset:7424
	v_pk_mul_f32 v[72:73], v[78:79], v[68:69] op_sel:[0,1] op_sel_hi:[1,0]
	s_nop 0
	v_pk_fma_f32 v[68:69], v[68:69], v[74:75], v[72:73] op_sel_hi:[1,0,1]
	s_nop 0
	v_pk_add_f32 v[72:73], v[68:69], 0 neg_lo:[1,1] neg_hi:[1,1]
	s_nop 0
	v_mov_b32_e32 v72, v69
	v_pk_mul_f32 v[72:73], v[66:67], v[72:73] op_sel:[1,0] op_sel_hi:[0,1]
	v_pk_fma_f32 v[66:67], v[66:67], v[68:69], v[72:73] op_sel_hi:[1,0,1]
	ds_write_b64 v84, v[66:67] offset:7680
	v_pk_mul_f32 v[66:67], v[78:79], v[68:69] op_sel:[0,1] op_sel_hi:[1,0]
	s_nop 0
	v_pk_fma_f32 v[66:67], v[68:69], v[74:75], v[66:67] op_sel_hi:[1,0,1]
	s_nop 0
	v_pk_add_f32 v[68:69], v[66:67], 0 neg_lo:[1,1] neg_hi:[1,1]
	s_nop 0
	v_mov_b32_e32 v68, v67
	v_pk_mul_f32 v[68:69], v[70:71], v[68:69] op_sel:[1,0] op_sel_hi:[0,1]
	v_pk_fma_f32 v[66:67], v[70:71], v[66:67], v[68:69] op_sel_hi:[1,0,1]
	ds_write_b64 v0, v[66:67]
	s_waitcnt lgkmcnt(0)
	s_barrier
	ds_read2_b64 v[66:69], v104 offset1:1
	ds_read2_b64 v[70:73], v104 offset0:2 offset1:3
	ds_read2_b64 v[74:77], v104 offset0:4 offset1:5
	ds_read2_b64 v[78:81], v104 offset0:6 offset1:7
	ds_read2_b64 v[82:85], v104 offset0:8 offset1:9
	ds_read2_b64 v[86:89], v104 offset0:10 offset1:11
	ds_read2_b64 v[90:93], v104 offset0:12 offset1:13
	ds_read2_b64 v[94:97], v104 offset0:14 offset1:15
	ds_read2_b64 v[98:101], v104 offset0:16 offset1:17
	ds_read2_b64 v[106:109], v104 offset0:18 offset1:19
	ds_read2_b64 v[110:113], v104 offset0:20 offset1:21
	ds_read2_b64 v[114:117], v104 offset0:22 offset1:23
	ds_read2_b64 v[118:121], v104 offset0:24 offset1:25
	ds_read2_b64 v[122:125], v104 offset0:26 offset1:27
	ds_read2_b64 v[126:129], v104 offset0:28 offset1:29
	ds_read2_b64 v[130:133], v104 offset0:30 offset1:31
	s_waitcnt lgkmcnt(7)
	v_pk_add_f32 v[102:103], v[66:67], v[98:99]
	v_pk_add_f32 v[66:67], v[66:67], v[98:99] neg_lo:[0,1] neg_hi:[0,1]
	v_pk_add_f32 v[98:99], v[68:69], v[100:101]
	v_pk_add_f32 v[68:69], v[68:69], v[100:101] neg_lo:[0,1] neg_hi:[0,1]
	s_nop 0
	v_pk_mul_f32 v[100:101], v[68:69], s[18:19]
	s_nop 0
	v_pk_fma_f32 v[68:69], v[68:69], s[20:21], v[100:101] op_sel:[0,0,1] op_sel_hi:[1,0,0]
	s_waitcnt lgkmcnt(6)
	v_pk_add_f32 v[100:101], v[70:71], v[106:107]
	v_pk_add_f32 v[70:71], v[70:71], v[106:107] neg_lo:[0,1] neg_hi:[0,1]
	s_nop 0
	v_pk_mul_f32 v[106:107], v[70:71], s[4:5]
	s_nop 0
	v_pk_fma_f32 v[70:71], v[70:71], s[6:7], v[106:107] op_sel:[0,0,1] op_sel_hi:[1,0,0]
	v_pk_add_f32 v[106:107], v[72:73], v[108:109]
	v_pk_add_f32 v[72:73], v[72:73], v[108:109] neg_lo:[0,1] neg_hi:[0,1]
	s_nop 0
	v_pk_mul_f32 v[108:109], v[72:73], s[22:23]
	s_nop 0
	v_pk_fma_f32 v[72:73], v[72:73], s[24:25], v[108:109] op_sel:[0,0,1] op_sel_hi:[1,0,0]
	s_waitcnt lgkmcnt(5)
	v_pk_add_f32 v[108:109], v[74:75], v[110:111]
	v_pk_add_f32 v[74:75], v[74:75], v[110:111] neg_lo:[0,1] neg_hi:[0,1]
	s_nop 0
	v_pk_mul_f32 v[110:111], v[74:75], s[8:9]
	s_nop 0
	v_pk_fma_f32 v[74:75], v[74:75], s[10:11], v[110:111] op_sel:[0,0,1] op_sel_hi:[1,0,0]
	v_pk_add_f32 v[110:111], v[76:77], v[112:113]
	v_pk_add_f32 v[76:77], v[76:77], v[112:113] neg_lo:[0,1] neg_hi:[0,1]
	s_nop 0
	v_pk_mul_f32 v[112:113], v[76:77], s[26:27]
	s_nop 0
	v_pk_fma_f32 v[76:77], v[76:77], s[0:1], v[112:113] op_sel:[0,0,1] op_sel_hi:[1,0,0]
	s_waitcnt lgkmcnt(4)
	v_pk_add_f32 v[112:113], v[78:79], v[114:115]
	v_pk_add_f32 v[78:79], v[78:79], v[114:115] neg_lo:[0,1] neg_hi:[0,1]
	s_mov_b64 s[0:1], 0
	v_pk_mul_f32 v[114:115], v[78:79], s[12:13]
	s_nop 0
	v_pk_fma_f32 v[78:79], v[78:79], s[14:15], v[114:115] op_sel:[0,0,1] op_sel_hi:[1,0,0]
	v_pk_add_f32 v[114:115], v[80:81], v[116:117]
	v_pk_add_f32 v[80:81], v[80:81], v[116:117] neg_lo:[0,1] neg_hi:[0,1]
	s_nop 0
	v_pk_mul_f32 v[116:117], v[80:81], s[34:35]
	s_nop 0
	v_pk_fma_f32 v[80:81], v[80:81], s[44:45], v[116:117] op_sel:[0,0,1] op_sel_hi:[1,0,0]
	s_waitcnt lgkmcnt(3)
	v_pk_add_f32 v[116:117], v[82:83], v[118:119]
	v_pk_add_f32 v[82:83], v[82:83], v[118:119] neg_lo:[0,1] neg_hi:[0,1]
	s_mov_b64 s[44:45], -1
	v_xor_b32_e32 v119, 0x80000000, v82
	v_mov_b32_e32 v118, v83
	v_pk_add_f32 v[82:83], v[84:85], v[120:121]
	v_pk_add_f32 v[84:85], v[84:85], v[120:121] neg_lo:[0,1] neg_hi:[0,1]
	s_nop 0
	v_pk_mul_f32 v[120:121], v[84:85], s[34:35]
	s_nop 0
	v_pk_fma_f32 v[84:85], v[84:85], s[18:19], v[120:121] op_sel:[0,0,1] op_sel_hi:[1,0,0]
	s_waitcnt lgkmcnt(2)
	v_pk_add_f32 v[120:121], v[86:87], v[122:123]
	v_pk_add_f32 v[86:87], v[86:87], v[122:123] neg_lo:[0,1] neg_hi:[0,1]
	s_nop 0
	v_pk_mul_f32 v[122:123], v[86:87], s[12:13]
	s_nop 0
	v_pk_fma_f32 v[86:87], v[86:87], s[4:5], v[122:123] op_sel:[0,0,1] op_sel_hi:[1,0,0]
	v_pk_add_f32 v[122:123], v[88:89], v[124:125]
	v_pk_add_f32 v[88:89], v[88:89], v[124:125] neg_lo:[0,1] neg_hi:[0,1]
	s_nop 0
	v_pk_mul_f32 v[124:125], v[88:89], s[26:27]
	s_nop 0
	v_pk_fma_f32 v[88:89], v[88:89], s[22:23], v[124:125] op_sel:[0,0,1] op_sel_hi:[1,0,0]
	s_waitcnt lgkmcnt(1)
	v_pk_add_f32 v[124:125], v[90:91], v[126:127]
	v_pk_add_f32 v[90:91], v[90:91], v[126:127] neg_lo:[0,1] neg_hi:[0,1]
	s_nop 0
	v_pk_mul_f32 v[126:127], v[90:91], s[8:9]
	s_nop 0
	v_pk_fma_f32 v[90:91], v[90:91], s[8:9], v[126:127] op_sel:[0,0,1] op_sel_hi:[1,0,0]
	v_pk_add_f32 v[126:127], v[92:93], v[128:129]
	v_pk_add_f32 v[92:93], v[92:93], v[128:129] neg_lo:[0,1] neg_hi:[0,1]
	s_nop 0
	v_pk_mul_f32 v[128:129], v[92:93], s[22:23]
	s_nop 0
	v_pk_fma_f32 v[92:93], v[92:93], s[26:27], v[128:129] op_sel:[0,0,1] op_sel_hi:[1,0,0]
	s_waitcnt lgkmcnt(0)
	v_pk_add_f32 v[128:129], v[94:95], v[130:131]
	v_pk_add_f32 v[94:95], v[94:95], v[130:131] neg_lo:[0,1] neg_hi:[0,1]
	s_nop 0
	v_pk_mul_f32 v[130:131], v[94:95], s[4:5]
	s_nop 0
	v_pk_fma_f32 v[94:95], v[94:95], s[12:13], v[130:131] op_sel:[0,0,1] op_sel_hi:[1,0,0]
	v_pk_add_f32 v[130:131], v[96:97], v[132:133]
	v_pk_add_f32 v[96:97], v[96:97], v[132:133] neg_lo:[0,1] neg_hi:[0,1]
	s_nop 0
	v_pk_mul_f32 v[132:133], v[96:97], s[18:19]
	s_nop 0
	v_pk_fma_f32 v[96:97], v[96:97], s[34:35], v[132:133] op_sel:[0,0,1] op_sel_hi:[1,0,0]
	v_pk_add_f32 v[132:133], v[102:103], v[116:117]
	v_pk_add_f32 v[102:103], v[102:103], v[116:117] neg_lo:[0,1] neg_hi:[0,1]
	v_pk_add_f32 v[116:117], v[98:99], v[82:83]
	v_pk_add_f32 v[82:83], v[98:99], v[82:83] neg_lo:[0,1] neg_hi:[0,1]
	s_nop 0
	v_pk_mul_f32 v[98:99], v[82:83], s[4:5]
	s_nop 0
	v_pk_fma_f32 v[82:83], v[82:83], s[6:7], v[98:99] op_sel:[0,0,1] op_sel_hi:[1,0,0]
	v_pk_add_f32 v[98:99], v[100:101], v[120:121]
	v_pk_add_f32 v[100:101], v[100:101], v[120:121] neg_lo:[0,1] neg_hi:[0,1]
	s_nop 0
	v_pk_mul_f32 v[120:121], v[100:101], s[8:9]
	s_nop 0
	v_pk_fma_f32 v[100:101], v[100:101], s[10:11], v[120:121] op_sel:[0,0,1] op_sel_hi:[1,0,0]
	v_pk_add_f32 v[120:121], v[106:107], v[122:123]
	v_pk_add_f32 v[106:107], v[106:107], v[122:123] neg_lo:[0,1] neg_hi:[0,1]
	s_nop 0
	v_pk_mul_f32 v[122:123], v[106:107], s[12:13]
	s_nop 0
	v_pk_fma_f32 v[106:107], v[106:107], s[14:15], v[122:123] op_sel:[0,0,1] op_sel_hi:[1,0,0]
	v_pk_add_f32 v[122:123], v[108:109], v[124:125]
	v_pk_add_f32 v[108:109], v[108:109], v[124:125] neg_lo:[0,1] neg_hi:[0,1]
	s_nop 0
	v_xor_b32_e32 v125, 0x80000000, v108
	v_mov_b32_e32 v124, v109
	v_pk_add_f32 v[108:109], v[110:111], v[126:127]
	v_pk_add_f32 v[110:111], v[110:111], v[126:127] neg_lo:[0,1] neg_hi:[0,1]
	s_nop 0
	v_pk_mul_f32 v[126:127], v[110:111], s[12:13]
	s_nop 0
	v_pk_fma_f32 v[110:111], v[110:111], s[4:5], v[126:127] op_sel:[0,0,1] op_sel_hi:[1,0,0]
	v_pk_add_f32 v[126:127], v[112:113], v[128:129]
	v_pk_add_f32 v[112:113], v[112:113], v[128:129] neg_lo:[0,1] neg_hi:[0,1]
	s_nop 0
	v_pk_mul_f32 v[128:129], v[112:113], s[8:9]
	s_nop 0
	v_pk_fma_f32 v[112:113], v[112:113], s[8:9], v[128:129] op_sel:[0,0,1] op_sel_hi:[1,0,0]
	v_pk_add_f32 v[128:129], v[114:115], v[130:131]
	v_pk_add_f32 v[114:115], v[114:115], v[130:131] neg_lo:[0,1] neg_hi:[0,1]
	s_nop 0
	v_pk_mul_f32 v[130:131], v[114:115], s[4:5]
	s_nop 0
	v_pk_fma_f32 v[114:115], v[114:115], s[12:13], v[130:131] op_sel:[0,0,1] op_sel_hi:[1,0,0]
	v_pk_add_f32 v[130:131], v[66:67], v[118:119]
	v_pk_add_f32 v[66:67], v[66:67], v[118:119] neg_lo:[0,1] neg_hi:[0,1]
	v_pk_add_f32 v[118:119], v[68:69], v[84:85]
	v_pk_add_f32 v[68:69], v[68:69], v[84:85] neg_lo:[0,1] neg_hi:[0,1]
	s_nop 0
	v_pk_mul_f32 v[84:85], v[68:69], s[4:5]
	s_nop 0
	v_pk_fma_f32 v[68:69], v[68:69], s[6:7], v[84:85] op_sel:[0,0,1] op_sel_hi:[1,0,0]
	v_pk_add_f32 v[84:85], v[70:71], v[86:87]
	v_pk_add_f32 v[70:71], v[70:71], v[86:87] neg_lo:[0,1] neg_hi:[0,1]
	s_nop 0
	v_pk_mul_f32 v[86:87], v[70:71], s[8:9]
	s_nop 0
	v_pk_fma_f32 v[70:71], v[70:71], s[10:11], v[86:87] op_sel:[0,0,1] op_sel_hi:[1,0,0]
	v_pk_add_f32 v[86:87], v[72:73], v[88:89]
	v_pk_add_f32 v[72:73], v[72:73], v[88:89] neg_lo:[0,1] neg_hi:[0,1]
	s_nop 0
	v_pk_mul_f32 v[88:89], v[72:73], s[12:13]
	s_nop 0
	v_pk_fma_f32 v[72:73], v[72:73], s[14:15], v[88:89] op_sel:[0,0,1] op_sel_hi:[1,0,0]
	v_pk_add_f32 v[88:89], v[74:75], v[90:91]
	v_pk_add_f32 v[74:75], v[74:75], v[90:91] neg_lo:[0,1] neg_hi:[0,1]
	s_nop 0
	v_xor_b32_e32 v91, 0x80000000, v74
	v_mov_b32_e32 v90, v75
	v_pk_add_f32 v[74:75], v[76:77], v[92:93]
	v_pk_add_f32 v[76:77], v[76:77], v[92:93] neg_lo:[0,1] neg_hi:[0,1]
	s_nop 0
	v_pk_mul_f32 v[92:93], v[76:77], s[12:13]
	s_nop 0
	v_pk_fma_f32 v[76:77], v[76:77], s[4:5], v[92:93] op_sel:[0,0,1] op_sel_hi:[1,0,0]
	v_pk_add_f32 v[92:93], v[78:79], v[94:95]
	v_pk_add_f32 v[78:79], v[78:79], v[94:95] neg_lo:[0,1] neg_hi:[0,1]
	s_nop 0
	v_pk_mul_f32 v[94:95], v[78:79], s[8:9]
	s_nop 0
	v_pk_fma_f32 v[78:79], v[78:79], s[8:9], v[94:95] op_sel:[0,0,1] op_sel_hi:[1,0,0]
	v_pk_add_f32 v[94:95], v[80:81], v[96:97]
	v_pk_add_f32 v[80:81], v[80:81], v[96:97] neg_lo:[0,1] neg_hi:[0,1]
	s_nop 0
	v_pk_mul_f32 v[96:97], v[80:81], s[4:5]
	s_nop 0
	v_pk_fma_f32 v[80:81], v[80:81], s[12:13], v[96:97] op_sel:[0,0,1] op_sel_hi:[1,0,0]
	v_pk_add_f32 v[96:97], v[132:133], v[122:123]
	v_pk_add_f32 v[122:123], v[132:133], v[122:123] neg_lo:[0,1] neg_hi:[0,1]
	v_pk_add_f32 v[132:133], v[116:117], v[108:109]
	v_pk_add_f32 v[108:109], v[116:117], v[108:109] neg_lo:[0,1] neg_hi:[0,1]
	s_nop 0
	v_pk_mul_f32 v[116:117], v[108:109], s[8:9]
	s_nop 0
	v_pk_fma_f32 v[108:109], v[108:109], s[10:11], v[116:117] op_sel:[0,0,1] op_sel_hi:[1,0,0]
	v_pk_add_f32 v[116:117], v[98:99], v[126:127]
	v_pk_add_f32 v[98:99], v[98:99], v[126:127] neg_lo:[0,1] neg_hi:[0,1]
	s_nop 0
	v_xor_b32_e32 v127, 0x80000000, v98
	v_mov_b32_e32 v126, v99
	v_pk_add_f32 v[98:99], v[120:121], v[128:129]
	v_pk_add_f32 v[120:121], v[120:121], v[128:129] neg_lo:[0,1] neg_hi:[0,1]
	s_nop 0
	v_pk_mul_f32 v[128:129], v[120:121], s[8:9]
	s_nop 0
	v_pk_fma_f32 v[120:121], v[120:121], s[8:9], v[128:129] op_sel:[0,0,1] op_sel_hi:[1,0,0]
	v_pk_add_f32 v[128:129], v[102:103], v[124:125]
	v_pk_add_f32 v[102:103], v[102:103], v[124:125] neg_lo:[0,1] neg_hi:[0,1]
	v_pk_add_f32 v[124:125], v[82:83], v[110:111]
	v_pk_add_f32 v[82:83], v[82:83], v[110:111] neg_lo:[0,1] neg_hi:[0,1]
	s_nop 0
	v_pk_mul_f32 v[110:111], v[82:83], s[8:9]
	s_nop 0
	v_pk_fma_f32 v[82:83], v[82:83], s[10:11], v[110:111] op_sel:[0,0,1] op_sel_hi:[1,0,0]
	v_pk_add_f32 v[110:111], v[100:101], v[112:113]
	v_pk_add_f32 v[100:101], v[100:101], v[112:113] neg_lo:[0,1] neg_hi:[0,1]
	s_nop 0
	v_xor_b32_e32 v113, 0x80000000, v100
	v_mov_b32_e32 v112, v101
	v_pk_add_f32 v[100:101], v[106:107], v[114:115]
	v_pk_add_f32 v[106:107], v[106:107], v[114:115] neg_lo:[0,1] neg_hi:[0,1]
	s_nop 0
	v_pk_mul_f32 v[114:115], v[106:107], s[8:9]
	s_nop 0
	v_pk_fma_f32 v[106:107], v[106:107], s[8:9], v[114:115] op_sel:[0,0,1] op_sel_hi:[1,0,0]
	v_pk_add_f32 v[114:115], v[130:131], v[88:89]
	v_pk_add_f32 v[88:89], v[130:131], v[88:89] neg_lo:[0,1] neg_hi:[0,1]
	v_pk_add_f32 v[130:131], v[118:119], v[74:75]
	v_pk_add_f32 v[74:75], v[118:119], v[74:75] neg_lo:[0,1] neg_hi:[0,1]
	s_nop 0
	v_pk_mul_f32 v[118:119], v[74:75], s[8:9]
	s_nop 0
	v_pk_fma_f32 v[74:75], v[74:75], s[10:11], v[118:119] op_sel:[0,0,1] op_sel_hi:[1,0,0]
	v_pk_add_f32 v[118:119], v[84:85], v[92:93]
	v_pk_add_f32 v[84:85], v[84:85], v[92:93] neg_lo:[0,1] neg_hi:[0,1]
	s_nop 0
	v_xor_b32_e32 v93, 0x80000000, v84
	v_mov_b32_e32 v92, v85
	v_pk_add_f32 v[84:85], v[86:87], v[94:95]
	v_pk_add_f32 v[86:87], v[86:87], v[94:95] neg_lo:[0,1] neg_hi:[0,1]
	s_nop 0
	v_pk_mul_f32 v[94:95], v[86:87], s[8:9]
	s_nop 0
	v_pk_fma_f32 v[86:87], v[86:87], s[8:9], v[94:95] op_sel:[0,0,1] op_sel_hi:[1,0,0]
	v_pk_add_f32 v[94:95], v[66:67], v[90:91]
	v_pk_add_f32 v[66:67], v[66:67], v[90:91] neg_lo:[0,1] neg_hi:[0,1]
	v_pk_add_f32 v[90:91], v[68:69], v[76:77]
	v_pk_add_f32 v[68:69], v[68:69], v[76:77] neg_lo:[0,1] neg_hi:[0,1]
	s_nop 0
	v_pk_mul_f32 v[76:77], v[68:69], s[8:9]
	s_nop 0
	v_pk_fma_f32 v[68:69], v[68:69], s[10:11], v[76:77] op_sel:[0,0,1] op_sel_hi:[1,0,0]
	v_pk_add_f32 v[76:77], v[70:71], v[78:79]
	v_pk_add_f32 v[70:71], v[70:71], v[78:79] neg_lo:[0,1] neg_hi:[0,1]
	s_nop 0
	v_xor_b32_e32 v79, 0x80000000, v70
	v_mov_b32_e32 v78, v71
	v_pk_add_f32 v[70:71], v[72:73], v[80:81]
	v_pk_add_f32 v[72:73], v[72:73], v[80:81] neg_lo:[0,1] neg_hi:[0,1]
	s_nop 0
	v_pk_mul_f32 v[80:81], v[72:73], s[8:9]
	s_nop 0
	v_pk_fma_f32 v[72:73], v[72:73], s[8:9], v[80:81] op_sel:[0,0,1] op_sel_hi:[1,0,0]
	v_pk_add_f32 v[80:81], v[96:97], v[116:117]
	v_pk_add_f32 v[96:97], v[96:97], v[116:117] neg_lo:[0,1] neg_hi:[0,1]
	v_pk_add_f32 v[116:117], v[132:133], v[98:99]
	v_pk_add_f32 v[98:99], v[132:133], v[98:99] neg_lo:[0,1] neg_hi:[0,1]
	s_nop 0
	v_xor_b32_e32 v133, 0x80000000, v98
	v_mov_b32_e32 v132, v99
	v_pk_add_f32 v[98:99], v[122:123], v[126:127]
	v_pk_add_f32 v[122:123], v[122:123], v[126:127] neg_lo:[0,1] neg_hi:[0,1]
	v_pk_add_f32 v[126:127], v[108:109], v[120:121]
	v_pk_add_f32 v[108:109], v[108:109], v[120:121] neg_lo:[0,1] neg_hi:[0,1]
	s_nop 0
	v_xor_b32_e32 v121, 0x80000000, v108
	v_mov_b32_e32 v120, v109
	v_pk_add_f32 v[108:109], v[128:129], v[110:111]
	v_pk_add_f32 v[110:111], v[128:129], v[110:111] neg_lo:[0,1] neg_hi:[0,1]
	v_pk_add_f32 v[128:129], v[124:125], v[100:101]
	v_pk_add_f32 v[100:101], v[124:125], v[100:101] neg_lo:[0,1] neg_hi:[0,1]
	s_nop 0
	v_xor_b32_e32 v125, 0x80000000, v100
	v_mov_b32_e32 v124, v101
	v_pk_add_f32 v[100:101], v[102:103], v[112:113]
	v_pk_add_f32 v[102:103], v[102:103], v[112:113] neg_lo:[0,1] neg_hi:[0,1]
	v_pk_add_f32 v[112:113], v[82:83], v[106:107]
	v_pk_add_f32 v[82:83], v[82:83], v[106:107] neg_lo:[0,1] neg_hi:[0,1]
	s_nop 0
	v_xor_b32_e32 v107, 0x80000000, v82
	v_mov_b32_e32 v106, v83
	v_pk_add_f32 v[82:83], v[114:115], v[118:119]
	v_pk_add_f32 v[114:115], v[114:115], v[118:119] neg_lo:[0,1] neg_hi:[0,1]
	v_pk_add_f32 v[118:119], v[130:131], v[84:85]
	v_pk_add_f32 v[84:85], v[130:131], v[84:85] neg_lo:[0,1] neg_hi:[0,1]
	s_nop 0
	v_xor_b32_e32 v131, 0x80000000, v84
	v_mov_b32_e32 v130, v85
	v_pk_add_f32 v[84:85], v[88:89], v[92:93]
	v_pk_add_f32 v[88:89], v[88:89], v[92:93] neg_lo:[0,1] neg_hi:[0,1]
	v_pk_add_f32 v[92:93], v[74:75], v[86:87]
	v_pk_add_f32 v[74:75], v[74:75], v[86:87] neg_lo:[0,1] neg_hi:[0,1]
	s_nop 0
	v_xor_b32_e32 v87, 0x80000000, v74
	v_mov_b32_e32 v86, v75
	v_pk_add_f32 v[74:75], v[94:95], v[76:77]
	v_pk_add_f32 v[76:77], v[94:95], v[76:77] neg_lo:[0,1] neg_hi:[0,1]
	v_pk_add_f32 v[94:95], v[90:91], v[70:71]
	v_pk_add_f32 v[70:71], v[90:91], v[70:71] neg_lo:[0,1] neg_hi:[0,1]
	s_nop 0
	v_xor_b32_e32 v91, 0x80000000, v70
	v_mov_b32_e32 v90, v71
	v_pk_add_f32 v[70:71], v[66:67], v[78:79]
	v_pk_add_f32 v[66:67], v[66:67], v[78:79] neg_lo:[0,1] neg_hi:[0,1]
	v_pk_add_f32 v[78:79], v[68:69], v[72:73]
	v_pk_add_f32 v[68:69], v[68:69], v[72:73] neg_lo:[0,1] neg_hi:[0,1]
	s_nop 0
	v_xor_b32_e32 v73, 0x80000000, v68
	v_mov_b32_e32 v72, v69
	v_pk_add_f32 v[68:69], v[80:81], v[116:117]
	v_pk_add_f32 v[80:81], v[80:81], v[116:117] neg_lo:[0,1] neg_hi:[0,1]
	v_pk_add_f32 v[116:117], v[96:97], v[132:133]
	v_pk_add_f32 v[96:97], v[96:97], v[132:133] neg_lo:[0,1] neg_hi:[0,1]
	v_pk_add_f32 v[132:133], v[98:99], v[126:127]
	v_pk_add_f32 v[98:99], v[98:99], v[126:127] neg_lo:[0,1] neg_hi:[0,1]
	v_pk_add_f32 v[126:127], v[122:123], v[120:121]
	v_pk_add_f32 v[120:121], v[122:123], v[120:121] neg_lo:[0,1] neg_hi:[0,1]
	v_pk_add_f32 v[122:123], v[108:109], v[128:129]
	v_pk_add_f32 v[108:109], v[108:109], v[128:129] neg_lo:[0,1] neg_hi:[0,1]
	v_pk_add_f32 v[128:129], v[110:111], v[124:125]
	v_pk_add_f32 v[110:111], v[110:111], v[124:125] neg_lo:[0,1] neg_hi:[0,1]
	v_pk_add_f32 v[124:125], v[100:101], v[112:113]
	v_pk_add_f32 v[100:101], v[100:101], v[112:113] neg_lo:[0,1] neg_hi:[0,1]
	v_pk_add_f32 v[112:113], v[102:103], v[106:107]
	v_pk_add_f32 v[102:103], v[102:103], v[106:107] neg_lo:[0,1] neg_hi:[0,1]
	v_pk_add_f32 v[106:107], v[82:83], v[118:119]
	v_pk_mul_f32 v[68:69], v[68:69], s[2:3] op_sel_hi:[1,0]
	global_store_dwordx2 v[2:3], v[68:69], off
	v_pk_mul_f32 v[68:69], v[106:107], s[2:3] op_sel_hi:[1,0]
	v_pk_add_f32 v[82:83], v[82:83], v[118:119] neg_lo:[0,1] neg_hi:[0,1]
	v_pk_add_f32 v[118:119], v[114:115], v[130:131]
	v_pk_add_f32 v[114:115], v[114:115], v[130:131] neg_lo:[0,1] neg_hi:[0,1]
	v_pk_add_f32 v[130:131], v[84:85], v[92:93]
	v_pk_add_f32 v[84:85], v[84:85], v[92:93] neg_lo:[0,1] neg_hi:[0,1]
	v_pk_add_f32 v[92:93], v[88:89], v[86:87]
	v_pk_add_f32 v[86:87], v[88:89], v[86:87] neg_lo:[0,1] neg_hi:[0,1]
	v_pk_add_f32 v[88:89], v[74:75], v[94:95]
	global_store_dwordx2 v[4:5], v[68:69], off
	v_pk_mul_f32 v[68:69], v[122:123], s[2:3] op_sel_hi:[1,0]
	global_store_dwordx2 v[6:7], v[68:69], off
	v_pk_mul_f32 v[68:69], v[88:89], s[2:3] op_sel_hi:[1,0]
	global_store_dwordx2 v[8:9], v[68:69], off
	v_pk_mul_f32 v[68:69], v[132:133], s[2:3] op_sel_hi:[1,0]
	global_store_dwordx2 v[10:11], v[68:69], off
	v_pk_mul_f32 v[68:69], v[130:131], s[2:3] op_sel_hi:[1,0]
	v_pk_add_f32 v[74:75], v[74:75], v[94:95] neg_lo:[0,1] neg_hi:[0,1]
	v_pk_add_f32 v[94:95], v[76:77], v[90:91]
	v_pk_add_f32 v[76:77], v[76:77], v[90:91] neg_lo:[0,1] neg_hi:[0,1]
	v_pk_add_f32 v[90:91], v[70:71], v[78:79]
	global_store_dwordx2 v[12:13], v[68:69], off
	v_pk_mul_f32 v[68:69], v[124:125], s[2:3] op_sel_hi:[1,0]
	global_store_dwordx2 v[14:15], v[68:69], off
	v_pk_mul_f32 v[68:69], v[90:91], s[2:3] op_sel_hi:[1,0]
	global_store_dwordx2 v[16:17], v[68:69], off
	v_pk_mul_f32 v[68:69], v[116:117], s[2:3] op_sel_hi:[1,0]
	global_store_dwordx2 v[18:19], v[68:69], off
	v_pk_mul_f32 v[68:69], v[118:119], s[2:3] op_sel_hi:[1,0]
	global_store_dwordx2 v[20:21], v[68:69], off
	v_pk_mul_f32 v[68:69], v[128:129], s[2:3] op_sel_hi:[1,0]
	global_store_dwordx2 v[22:23], v[68:69], off
	v_pk_mul_f32 v[68:69], v[94:95], s[2:3] op_sel_hi:[1,0]
	global_store_dwordx2 v[24:25], v[68:69], off
	v_pk_mul_f32 v[68:69], v[126:127], s[2:3] op_sel_hi:[1,0]
	global_store_dwordx2 v[26:27], v[68:69], off
	v_pk_mul_f32 v[68:69], v[92:93], s[2:3] op_sel_hi:[1,0]
	v_pk_add_f32 v[70:71], v[70:71], v[78:79] neg_lo:[0,1] neg_hi:[0,1]
	v_pk_add_f32 v[78:79], v[66:67], v[72:73]
	global_store_dwordx2 v[28:29], v[68:69], off
	v_pk_mul_f32 v[68:69], v[112:113], s[2:3] op_sel_hi:[1,0]
	global_store_dwordx2 v[30:31], v[68:69], off
	v_pk_mul_f32 v[68:69], v[78:79], s[2:3] op_sel_hi:[1,0]
	global_store_dwordx2 v[32:33], v[68:69], off
	v_pk_mul_f32 v[68:69], v[80:81], s[2:3] op_sel_hi:[1,0]
	global_store_dwordx2 v[34:35], v[68:69], off
	v_pk_mul_f32 v[68:69], v[82:83], s[2:3] op_sel_hi:[1,0]
	global_store_dwordx2 v[36:37], v[68:69], off
	v_pk_mul_f32 v[68:69], v[108:109], s[2:3] op_sel_hi:[1,0]
	global_store_dwordx2 v[38:39], v[68:69], off
	v_pk_mul_f32 v[68:69], v[74:75], s[2:3] op_sel_hi:[1,0]
	global_store_dwordx2 v[40:41], v[68:69], off
	v_pk_mul_f32 v[68:69], v[98:99], s[2:3] op_sel_hi:[1,0]
	global_store_dwordx2 v[42:43], v[68:69], off
	v_pk_mul_f32 v[68:69], v[84:85], s[2:3] op_sel_hi:[1,0]
	global_store_dwordx2 v[44:45], v[68:69], off
	v_pk_mul_f32 v[68:69], v[100:101], s[2:3] op_sel_hi:[1,0]
	global_store_dwordx2 v[46:47], v[68:69], off
	v_pk_mul_f32 v[68:69], v[70:71], s[2:3] op_sel_hi:[1,0]
	global_store_dwordx2 v[48:49], v[68:69], off
	v_pk_mul_f32 v[68:69], v[96:97], s[2:3] op_sel_hi:[1,0]
	global_store_dwordx2 v[50:51], v[68:69], off
	v_pk_mul_f32 v[68:69], v[114:115], s[2:3] op_sel_hi:[1,0]
	global_store_dwordx2 v[52:53], v[68:69], off
	v_pk_mul_f32 v[68:69], v[110:111], s[2:3] op_sel_hi:[1,0]
	global_store_dwordx2 v[54:55], v[68:69], off
	v_pk_mul_f32 v[68:69], v[76:77], s[2:3] op_sel_hi:[1,0]
	global_store_dwordx2 v[56:57], v[68:69], off
	v_pk_mul_f32 v[68:69], v[120:121], s[2:3] op_sel_hi:[1,0]
	v_pk_add_f32 v[66:67], v[66:67], v[72:73] neg_lo:[0,1] neg_hi:[0,1]
	global_store_dwordx2 v[58:59], v[68:69], off
	v_pk_mul_f32 v[68:69], v[86:87], s[2:3] op_sel_hi:[1,0]
	global_store_dwordx2 v[60:61], v[68:69], off
	v_pk_mul_f32 v[68:69], v[102:103], s[2:3] op_sel_hi:[1,0]
	v_pk_mul_f32 v[66:67], v[66:67], s[2:3] op_sel_hi:[1,0]
	global_store_dwordx2 v[62:63], v[68:69], off
	global_store_dwordx2 v[64:65], v[66:67], off
	s_barrier

.LBB0_362:
	v_add_u32_e32 v0, s5, v170
	v_lshlrev_b64 v[72:73], 1, v[0:1]
	v_lshl_add_u64 v[74:75], s[44:45], 0, v[72:73]
	v_add_co_u32_e64 v78, s[0:1], s58, v74
	v_lshl_add_u64 v[72:73], s[46:47], 0, v[72:73]
	s_nop 0
	v_addc_co_u32_e64 v79, s[0:1], 0, v75, s[0:1]
	v_add_co_u32_e64 v80, s[0:1], s58, v72
	v_cndmask_b32_e64 v66, 0, 1, s[48:49]
	s_nop 0
	v_addc_co_u32_e64 v81, s[0:1], 0, v73, s[0:1]
	v_add_co_u32_e64 v84, s[0:1], s59, v74
	v_mov_b32_e32 v67, v1
	s_nop 0
	v_addc_co_u32_e64 v85, s[0:1], 0, v75, s[0:1]
	v_add_co_u32_e64 v86, s[0:1], s59, v72
	v_mov_b32_e32 v69, v1
	s_nop 0
	v_addc_co_u32_e64 v87, s[0:1], 0, v73, s[0:1]
	v_add_co_u32_e64 v90, s[0:1], s60, v74
	v_mov_b32_e32 v71, v1
	v_cmp_ne_u32_e32 vcc, 1, v66
	v_or_b32_e32 v66, 0x800, v0
	v_or_b32_e32 v68, 0x1000, v0
	v_or_b32_e32 v70, 0x1800, v0
	v_addc_co_u32_e64 v91, s[0:1], 0, v75, s[0:1]
	v_lshlrev_b64 v[66:67], 1, v[66:67]
	v_lshlrev_b64 v[68:69], 1, v[68:69]
	v_lshlrev_b64 v[70:71], 1, v[70:71]
	v_add_co_u32_e64 v92, s[0:1], s60, v72
	v_lshl_add_u64 v[76:77], s[44:45], 0, v[66:67]
	v_lshl_add_u64 v[66:67], s[46:47], 0, v[66:67]
	v_lshl_add_u64 v[82:83], s[44:45], 0, v[68:69]
	v_lshl_add_u64 v[68:69], s[46:47], 0, v[68:69]
	v_lshl_add_u64 v[88:89], s[44:45], 0, v[70:71]
	v_lshl_add_u64 v[70:71], s[46:47], 0, v[70:71]
	v_addc_co_u32_e64 v93, s[0:1], 0, v73, s[0:1]
	s_cmp_lg_u32 s5, 0
	s_cbranch_scc1 .Lmy_fft_h1
	global_load_ushort v105, v[74:75], off
	global_load_ushort v127, v[72:73], off
	global_load_ushort v128, v[72:73], off offset:2048
	global_load_ushort v130, v[76:77], off
	global_load_ushort v131, v[66:67], off
	global_load_ushort v132, v[78:79], off offset:2048
	global_load_ushort v133, v[80:81], off offset:2048
	global_load_ushort v134, v[74:75], off offset:2048
	global_load_ushort v136, v[82:83], off
	global_load_ushort v135, v[68:69], off
	global_load_ushort v137, v[84:85], off offset:2048
	global_load_ushort v138, v[86:87], off offset:2048
	global_load_ushort v139, v[88:89], off
	global_load_ushort v140, v[70:71], off
	global_load_ushort v141, v[90:91], off offset:2048
	global_load_ushort v142, v[92:93], off offset:2048
	v_mov_b32_e32 v215, 0
	v_add_u32_e32 v214, 0x200, v170
	v_lshlrev_b64 v[72:73], 1, v[214:215]
	v_lshl_add_u64 v[74:75], s[44:45], 0, v[72:73]
	v_add_co_u32_e64 v78, s[62:63], s58, v74
	v_lshl_add_u64 v[72:73], s[46:47], 0, v[72:73]
	s_nop 0
	v_addc_co_u32_e64 v79, s[62:63], 0, v75, s[62:63]
	v_add_co_u32_e64 v80, s[62:63], s58, v72
	s_nop 0
	v_addc_co_u32_e64 v81, s[62:63], 0, v73, s[62:63]
	v_add_co_u32_e64 v84, s[62:63], s59, v74
	v_mov_b32_e32 v67, v1
	s_nop 0
	v_addc_co_u32_e64 v85, s[62:63], 0, v75, s[62:63]
	v_add_co_u32_e64 v86, s[62:63], s59, v72
	v_mov_b32_e32 v69, v1
	s_nop 0
	v_addc_co_u32_e64 v87, s[62:63], 0, v73, s[62:63]
	v_add_co_u32_e64 v90, s[62:63], s60, v74
	v_mov_b32_e32 v71, v1
	v_or_b32_e32 v66, 0x800, v214
	v_or_b32_e32 v68, 0x1000, v214
	v_or_b32_e32 v70, 0x1800, v214
	v_addc_co_u32_e64 v91, s[62:63], 0, v75, s[62:63]
	v_lshlrev_b64 v[66:67], 1, v[66:67]
	v_lshlrev_b64 v[68:69], 1, v[68:69]
	v_lshlrev_b64 v[70:71], 1, v[70:71]
	v_add_co_u32_e64 v92, s[62:63], s60, v72
	v_lshl_add_u64 v[76:77], s[44:45], 0, v[66:67]
	v_lshl_add_u64 v[66:67], s[46:47], 0, v[66:67]
	v_lshl_add_u64 v[82:83], s[44:45], 0, v[68:69]
	v_lshl_add_u64 v[68:69], s[46:47], 0, v[68:69]
	v_lshl_add_u64 v[88:89], s[44:45], 0, v[70:71]
	v_lshl_add_u64 v[70:71], s[46:47], 0, v[70:71]
	v_addc_co_u32_e64 v93, s[62:63], 0, v73, s[62:63]
	global_load_ushort v197, v[74:75], off
	global_load_ushort v198, v[72:73], off
	global_load_ushort v199, v[72:73], off offset:2048
	global_load_ushort v200, v[76:77], off
	global_load_ushort v201, v[66:67], off
	global_load_ushort v202, v[78:79], off offset:2048
	global_load_ushort v203, v[80:81], off offset:2048
	global_load_ushort v204, v[74:75], off offset:2048
	global_load_ushort v205, v[82:83], off
	global_load_ushort v206, v[68:69], off
	global_load_ushort v207, v[84:85], off offset:2048
	global_load_ushort v208, v[86:87], off offset:2048
	global_load_ushort v209, v[88:89], off
	global_load_ushort v210, v[70:71], off
	global_load_ushort v211, v[90:91], off offset:2048
	global_load_ushort v212, v[92:93], off offset:2048
	s_branch .Lmy_fft_hj
.Lmy_fft_h1:
	s_waitcnt vmcnt(0)
	v_mov_b32_e32 v105, v197
	v_mov_b32_e32 v127, v198
	v_mov_b32_e32 v128, v199
	v_mov_b32_e32 v130, v200
	v_mov_b32_e32 v131, v201
	v_mov_b32_e32 v132, v202
	v_mov_b32_e32 v133, v203
	v_mov_b32_e32 v134, v204
	v_mov_b32_e32 v136, v205
	v_mov_b32_e32 v135, v206
	v_mov_b32_e32 v137, v207
	v_mov_b32_e32 v138, v208
	v_mov_b32_e32 v139, v209
	v_mov_b32_e32 v140, v210
	v_mov_b32_e32 v141, v211
	v_mov_b32_e32 v142, v212
.Lmy_fft_hj:
	v_mov_b32 v66, 0
	s_movk_i32 s5, 0x200
	v_add_u32_e32 v0, v66, v0
	v_cvt_f32_i32_e32 v68, v0
	v_ashrrev_i32_e32 v66, 5, v0
	v_lshlrev_b32_e32 v67, 3, v0
	v_add_u32_e32 v69, 0x400, v0
	v_add_u32_e32 v70, 0x800, v0
	v_add_u32_e32 v71, 0xc00, v0
	v_add_u32_e32 v72, 0x1000, v0
	v_add_u32_e32 v73, 0x1400, v0
	v_add_u32_e32 v74, 0x1800, v0
	v_add_u32_e32 v75, 0x1c00, v0
	v_add_u32_e32 v76, 0x2000, v0
	v_add_u32_e32 v77, 0x2400, v0
	v_add_u32_e32 v78, 0x2800, v0
	v_add_u32_e32 v79, 0x2c00, v0
	v_add_u32_e32 v80, 0x3000, v0
	v_add_u32_e32 v81, 0x3400, v0
	v_add_u32_e32 v82, 0x3800, v0
	v_add_u32_e32 v0, 0x3c00, v0
	v_lshlrev_b32_e32 v66, 3, v66
	v_ashrrev_i32_e32 v69, 5, v69
	v_ashrrev_i32_e32 v70, 5, v70
	v_ashrrev_i32_e32 v71, 5, v71
	v_ashrrev_i32_e32 v72, 5, v72
	v_ashrrev_i32_e32 v73, 5, v73
	v_ashrrev_i32_e32 v74, 5, v74
	v_ashrrev_i32_e32 v75, 5, v75
	v_ashrrev_i32_e32 v83, 5, v76
	v_ashrrev_i32_e32 v84, 5, v77
	v_ashrrev_i32_e32 v85, 5, v78
	v_ashrrev_i32_e32 v86, 5, v79
	v_ashrrev_i32_e32 v87, 5, v80
	v_ashrrev_i32_e32 v88, 5, v81
	v_ashrrev_i32_e32 v89, 5, v82
	v_ashrrev_i32_e32 v90, 5, v0
	v_lshlrev_b32_e32 v0, 3, v0
	v_add3_u32 v171, 0, v66, v67
	v_lshlrev_b32_e32 v66, 3, v69
	v_lshlrev_b32_e32 v69, 3, v70
	v_lshlrev_b32_e32 v70, 3, v71
	v_lshlrev_b32_e32 v71, 3, v72
	v_lshlrev_b32_e32 v72, 3, v73
	v_lshlrev_b32_e32 v73, 3, v74
	v_lshlrev_b32_e32 v74, 3, v75
	v_lshlrev_b32_e32 v75, 3, v83
	v_lshlrev_b32_e32 v83, 3, v84
	v_lshlrev_b32_e32 v84, 3, v85
	v_lshlrev_b32_e32 v85, 3, v86
	v_lshlrev_b32_e32 v86, 3, v87
	v_lshlrev_b32_e32 v87, 3, v88
	v_lshlrev_b32_e32 v88, 3, v89
	v_lshlrev_b32_e32 v89, 3, v90
	v_add3_u32 v186, 0, v89, v0
	v_mul_f32_e32 v0, 0x38800000, v68
	v_add3_u32 v172, 0, v66, v67
	v_add3_u32 v173, 0, v69, v67
	v_add3_u32 v174, 0, v70, v67
	v_add3_u32 v175, 0, v71, v67
	v_add3_u32 v176, 0, v72, v67
	v_add3_u32 v177, 0, v73, v67
	v_add3_u32 v178, 0, v74, v67
	v_sin_f32_e32 v67, v0
	v_cos_f32_e32 v66, v0
	v_lshlrev_b32_e32 v76, 3, v76
	v_add3_u32 v179, 0, v75, v76
	v_xor_b32_e32 v68, 0x80000000, v67
	v_mov_b32_e32 v69, v67
	v_pk_mul_f32 v[70:71], v[68:69], v[66:67] op_sel:[0,1] op_sel_hi:[1,0]
	v_lshlrev_b32_e32 v78, 3, v78
	v_pk_fma_f32 v[70:71], v[66:67], v[66:67], v[70:71] op_sel_hi:[1,0,1]
	v_lshlrev_b32_e32 v79, 3, v79
	v_pk_mul_f32 v[74:75], v[68:69], v[70:71] op_sel:[0,1] op_sel_hi:[1,0]
	v_add3_u32 v181, 0, v84, v78
	v_pk_fma_f32 v[74:75], v[70:71], v[66:67], v[74:75] op_sel_hi:[1,0,1]
	v_add3_u32 v182, 0, v85, v79
	v_pk_mul_f32 v[78:79], v[68:69], v[74:75] op_sel:[0,1] op_sel_hi:[1,0]
	v_lshlrev_b32_e32 v77, 3, v77
	v_lshlrev_b32_e32 v82, 3, v82
	v_pk_fma_f32 v[78:79], v[74:75], v[66:67], v[78:79] op_sel_hi:[1,0,1]
	v_add3_u32 v180, 0, v83, v77
	v_add3_u32 v185, 0, v88, v82
	v_pk_mul_f32 v[82:83], v[68:69], v[78:79] op_sel:[0,1] op_sel_hi:[1,0]
	v_lshlrev_b32_e32 v80, 3, v80
	v_lshlrev_b32_e32 v81, 3, v81
	v_pk_fma_f32 v[82:83], v[78:79], v[66:67], v[82:83] op_sel_hi:[1,0,1]
	v_add3_u32 v183, 0, v86, v80
	v_add3_u32 v184, 0, v87, v81
	v_pk_mul_f32 v[86:87], v[68:69], v[82:83] op_sel:[0,1] op_sel_hi:[1,0]
	s_waitcnt vmcnt(31)
	v_lshlrev_b32_e32 v126, 16, v105
	v_pk_fma_f32 v[86:87], v[82:83], v[66:67], v[86:87] op_sel_hi:[1,0,1]
	s_waitcnt vmcnt(30)
	v_lshlrev_b32_e32 v127, 16, v127
	v_pk_mul_f32 v[90:91], v[68:69], v[86:87] op_sel:[0,1] op_sel_hi:[1,0]
	s_waitcnt vmcnt(29)
	v_lshlrev_b32_e32 v129, 16, v128
	v_pk_fma_f32 v[90:91], v[86:87], v[66:67], v[90:91] op_sel_hi:[1,0,1]
	s_waitcnt vmcnt(24)
	v_lshlrev_b32_e32 v128, 16, v134
	v_pk_mul_f32 v[94:95], v[68:69], v[90:91] op_sel:[0,1] op_sel_hi:[1,0]
	v_lshlrev_b32_e32 v130, 16, v130
	v_pk_fma_f32 v[94:95], v[90:91], v[66:67], v[94:95] op_sel_hi:[1,0,1]
	v_lshlrev_b32_e32 v131, 16, v131
	v_pk_mul_f32 v[98:99], v[68:69], v[94:95] op_sel:[0,1] op_sel_hi:[1,0]
	v_lshlrev_b32_e32 v132, 16, v132
	v_pk_fma_f32 v[98:99], v[94:95], v[66:67], v[98:99] op_sel_hi:[1,0,1]
	v_lshlrev_b32_e32 v133, 16, v133
	v_pk_mul_f32 v[102:103], v[68:69], v[98:99] op_sel:[0,1] op_sel_hi:[1,0]
	s_waitcnt vmcnt(22)
	v_lshlrev_b32_e32 v135, 16, v135
	v_pk_fma_f32 v[102:103], v[98:99], v[66:67], v[102:103] op_sel_hi:[1,0,1]
	v_lshlrev_b32_e32 v134, 16, v136
	v_pk_mul_f32 v[108:109], v[68:69], v[102:103] op_sel:[0,1] op_sel_hi:[1,0]
	s_waitcnt vmcnt(21)
	v_lshlrev_b32_e32 v136, 16, v137
	v_pk_fma_f32 v[108:109], v[102:103], v[66:67], v[108:109] op_sel_hi:[1,0,1]
	s_waitcnt vmcnt(20)
	v_lshlrev_b32_e32 v137, 16, v138
	v_pk_mul_f32 v[112:113], v[68:69], v[108:109] op_sel:[0,1] op_sel_hi:[1,0]
	s_waitcnt vmcnt(19)
	v_lshlrev_b32_e32 v138, 16, v139
	s_waitcnt vmcnt(18)
	v_lshlrev_b32_e32 v139, 16, v140
	s_waitcnt vmcnt(17)
	v_lshlrev_b32_e32 v140, 16, v141
	s_waitcnt vmcnt(16)
	v_lshlrev_b32_e32 v141, 16, v142
	v_pk_fma_f32 v[112:113], v[108:109], v[66:67], v[112:113] op_sel_hi:[1,0,1]
	v_pk_add_f32 v[142:143], v[126:127], 0 op_sel_hi:[1,0]
	v_pk_add_f32 v[144:145], v[128:129], 0 op_sel_hi:[1,0]
	v_pk_mul_f32 v[146:147], v[128:129], s[36:37]
	v_pk_add_f32 v[148:149], v[130:131], 0 op_sel_hi:[1,0]
	v_pk_mul_f32 v[150:151], v[130:131], s[16:17]
	v_pk_add_f32 v[152:153], v[132:133], 0 op_sel_hi:[1,0]
	v_pk_mul_f32 v[154:155], v[132:133], s[38:39]
	v_pk_add_f32 v[156:157], v[134:135], 0 op_sel_hi:[1,0]
	v_xor_b32_e32 v159, 0x80000000, v134
	v_mov_b32_e32 v158, v135
	v_pk_add_f32 v[134:135], v[136:137], 0 op_sel_hi:[1,0]
	v_pk_mul_f32 v[160:161], v[136:137], s[38:39]
	v_pk_add_f32 v[162:163], v[138:139], 0 op_sel_hi:[1,0]
	v_pk_mul_f32 v[164:165], v[138:139], s[16:17]
	v_pk_add_f32 v[166:167], v[140:141], 0 op_sel_hi:[1,0]
	v_pk_mul_f32 v[168:169], v[140:141], s[36:37]
	v_pk_mul_f32 v[116:117], v[68:69], v[112:113] op_sel:[0,1] op_sel_hi:[1,0]
	v_pk_fma_f32 v[128:129], v[128:129], s[6:7], v[146:147] op_sel:[0,0,1] op_sel_hi:[1,0,0]
	v_pk_fma_f32 v[130:131], v[130:131], s[10:11], v[150:151] op_sel:[0,0,1] op_sel_hi:[1,0,0]
	v_pk_fma_f32 v[132:133], v[132:133], s[14:15], v[154:155] op_sel:[0,0,1] op_sel_hi:[1,0,0]
	v_pk_fma_f32 v[136:137], v[136:137], s[4:5], v[160:161] op_sel:[0,0,1] op_sel_hi:[1,0,0]
	v_pk_fma_f32 v[138:139], v[138:139], s[8:9], v[164:165] op_sel:[0,0,1] op_sel_hi:[1,0,0]
	v_pk_fma_f32 v[140:141], v[140:141], s[12:13], v[168:169] op_sel:[0,0,1] op_sel_hi:[1,0,0]
	v_pk_add_f32 v[146:147], v[142:143], v[156:157]
	v_pk_add_f32 v[150:151], v[144:145], v[134:135]
	v_pk_add_f32 v[134:135], v[144:145], v[134:135] neg_lo:[0,1] neg_hi:[0,1]
	v_pk_add_f32 v[144:145], v[148:149], v[162:163]
	v_pk_add_f32 v[148:149], v[148:149], v[162:163] neg_lo:[0,1] neg_hi:[0,1]
	v_pk_add_f32 v[154:155], v[152:153], v[166:167]
	v_pk_add_f32 v[152:153], v[152:153], v[166:167] neg_lo:[0,1] neg_hi:[0,1]
	v_pk_fma_f32 v[116:117], v[112:113], v[66:67], v[116:117] op_sel_hi:[1,0,1]
	v_pk_add_f32 v[142:143], v[142:143], v[156:157] neg_lo:[0,1] neg_hi:[0,1]
	v_pk_add_f32 v[156:157], v[158:159], v[126:127]
	v_pk_add_f32 v[126:127], v[126:127], v[158:159] neg_lo:[0,1] neg_hi:[0,1]
	v_pk_mul_f32 v[158:159], v[134:135], s[16:17]
	v_xor_b32_e32 v161, 0x80000000, v148
	v_mov_b32_e32 v160, v149
	v_pk_mul_f32 v[148:149], v[152:153], s[16:17]
	v_pk_add_f32 v[162:163], v[128:129], v[136:137]
	v_pk_add_f32 v[128:129], v[128:129], v[136:137] neg_lo:[0,1] neg_hi:[0,1]
	v_pk_add_f32 v[136:137], v[130:131], v[138:139]
	v_pk_add_f32 v[130:131], v[130:131], v[138:139] neg_lo:[0,1] neg_hi:[0,1]
	v_pk_add_f32 v[138:139], v[132:133], v[140:141]
	v_pk_add_f32 v[132:133], v[132:133], v[140:141] neg_lo:[0,1] neg_hi:[0,1]
	v_pk_add_f32 v[140:141], v[146:147], v[144:145]
	v_pk_add_f32 v[144:145], v[146:147], v[144:145] neg_lo:[0,1] neg_hi:[0,1]
	v_pk_add_f32 v[146:147], v[150:151], v[154:155]
	v_pk_add_f32 v[150:151], v[150:151], v[154:155] neg_lo:[0,1] neg_hi:[0,1]
	v_pk_add_f32 v[96:97], v[94:95], 0 neg_lo:[1,1] neg_hi:[1,1]
	v_pk_mul_f32 v[120:121], v[68:69], v[116:117] op_sel:[0,1] op_sel_hi:[1,0]
	v_pk_fma_f32 v[134:135], v[134:135], s[10:11], v[158:159] op_sel:[0,0,1] op_sel_hi:[1,0,0]
	v_pk_fma_f32 v[148:149], v[152:153], s[8:9], v[148:149] op_sel:[0,0,1] op_sel_hi:[1,0,0]
	v_pk_mul_f32 v[152:153], v[128:129], s[16:17]
	v_xor_b32_e32 v155, 0x80000000, v130
	v_mov_b32_e32 v154, v131
	v_pk_mul_f32 v[130:131], v[132:133], s[16:17]
	v_xor_b32_e32 v159, 0x80000000, v150
	v_mov_b32_e32 v158, v151
	v_pk_add_f32 v[150:151], v[142:143], v[160:161]
	v_pk_add_f32 v[142:143], v[142:143], v[160:161] neg_lo:[0,1] neg_hi:[0,1]
	v_pk_add_f32 v[160:161], v[156:157], v[136:137]
	v_pk_add_f32 v[136:137], v[156:157], v[136:137] neg_lo:[0,1] neg_hi:[0,1]
	v_pk_add_f32 v[156:157], v[162:163], v[138:139]
	v_pk_add_f32 v[138:139], v[162:163], v[138:139] neg_lo:[0,1] neg_hi:[0,1]
	v_mov_b32_e32 v0, v67
	v_pk_add_f32 v[72:73], v[70:71], 0 neg_lo:[1,1] neg_hi:[1,1]
	v_pk_add_f32 v[80:81], v[78:79], 0 neg_lo:[1,1] neg_hi:[1,1]
	v_mov_b32_e32 v96, v95
	v_pk_add_f32 v[100:101], v[98:99], 0 neg_lo:[1,1] neg_hi:[1,1]
	v_pk_add_f32 v[114:115], v[112:113], 0 neg_lo:[1,1] neg_hi:[1,1]
	v_pk_fma_f32 v[120:121], v[116:117], v[66:67], v[120:121] op_sel_hi:[1,0,1]
	v_pk_add_f32 v[162:163], v[140:141], v[146:147]
	v_pk_add_f32 v[140:141], v[140:141], v[146:147] neg_lo:[0,1] neg_hi:[0,1]
	v_pk_fma_f32 v[128:129], v[128:129], s[10:11], v[152:153] op_sel:[0,0,1] op_sel_hi:[1,0,0]
	v_pk_fma_f32 v[130:131], v[132:133], s[8:9], v[130:131] op_sel:[0,0,1] op_sel_hi:[1,0,0]
	v_pk_add_f32 v[132:133], v[134:135], v[148:149]
	v_pk_add_f32 v[134:135], v[134:135], v[148:149] neg_lo:[0,1] neg_hi:[0,1]
	v_xor_b32_e32 v147, 0x80000000, v138
	v_mov_b32_e32 v146, v139
	v_pk_add_f32 v[152:153], v[160:161], v[156:157]
	v_mov_b32_e32 v72, v71
	v_pk_add_f32 v[76:77], v[74:75], 0 neg_lo:[1,1] neg_hi:[1,1]
	v_mov_b32_e32 v80, v79
	v_pk_add_f32 v[84:85], v[82:83], 0 neg_lo:[1,1] neg_hi:[1,1]
	v_mov_b32_e32 v100, v99
	v_pk_add_f32 v[106:107], v[102:103], 0 neg_lo:[1,1] neg_hi:[1,1]
	v_mov_b32_e32 v114, v113
	v_pk_mul_f32 v[68:69], v[68:69], v[120:121] op_sel:[0,1] op_sel_hi:[1,0]
	v_pk_add_f32 v[138:139], v[126:127], v[154:155]
	v_pk_add_f32 v[126:127], v[126:127], v[154:155] neg_lo:[0,1] neg_hi:[0,1]
	v_pk_add_f32 v[148:149], v[144:145], v[158:159]
	v_pk_add_f32 v[144:145], v[144:145], v[158:159] neg_lo:[0,1] neg_hi:[0,1]
	v_pk_add_f32 v[154:155], v[160:161], v[156:157] neg_lo:[0,1] neg_hi:[0,1]
	v_pk_mul_f32 v[96:97], v[140:141], v[96:97] op_sel:[1,0] op_sel_hi:[0,1]
	v_xor_b32_e32 v157, 0x80000000, v134
	v_mov_b32_e32 v156, v135
	v_pk_add_f32 v[134:135], v[128:129], v[130:131]
	v_pk_add_f32 v[128:129], v[128:129], v[130:131] neg_lo:[0,1] neg_hi:[0,1]
	v_pk_add_f32 v[130:131], v[150:151], v[132:133]
	v_pk_add_f32 v[132:133], v[150:151], v[132:133] neg_lo:[0,1] neg_hi:[0,1]
	v_pk_add_f32 v[150:151], v[136:137], v[146:147]
	v_pk_add_f32 v[136:137], v[136:137], v[146:147] neg_lo:[0,1] neg_hi:[0,1]
	v_pk_mul_f32 v[146:147], v[0:1], v[152:153] op_sel:[0,1] op_sel_hi:[0,0] neg_hi:[1,0]
	v_mov_b32_e32 v76, v75
	v_mov_b32_e32 v84, v83
	v_pk_add_f32 v[88:89], v[86:87], 0 neg_lo:[1,1] neg_hi:[1,1]
	v_pk_add_f32 v[92:93], v[90:91], 0 neg_lo:[1,1] neg_hi:[1,1]
	v_mov_b32_e32 v106, v103
	v_pk_fma_f32 v[68:69], v[120:121], v[66:67], v[68:69] op_sel_hi:[1,0,1]
	v_pk_mul_f32 v[80:81], v[148:149], v[80:81] op_sel:[1,0] op_sel_hi:[0,1]
	v_pk_fma_f32 v[94:95], v[140:141], v[94:95], v[96:97] op_sel_hi:[1,0,1]
	v_pk_mul_f32 v[96:97], v[154:155], v[100:101] op_sel:[1,0] op_sel_hi:[0,1]
	v_pk_mul_f32 v[100:101], v[144:145], v[114:115] op_sel:[1,0] op_sel_hi:[0,1]
	v_xor_b32_e32 v115, 0x80000000, v128
	v_mov_b32_e32 v114, v129
	v_pk_add_f32 v[128:129], v[142:143], v[156:157]
	v_pk_add_f32 v[140:141], v[142:143], v[156:157] neg_lo:[0,1] neg_hi:[0,1]
	v_pk_add_f32 v[142:143], v[138:139], v[134:135]
	v_pk_fma_f32 v[66:67], v[152:153], v[66:67], v[146:147] op_sel_hi:[1,0,1]
	v_pk_mul_f32 v[72:73], v[130:131], v[72:73] op_sel:[1,0] op_sel_hi:[0,1]
	v_mov_b32_e32 v88, v87
	v_mov_b32_e32 v92, v91
	v_pk_add_f32 v[110:111], v[108:109], 0 neg_lo:[1,1] neg_hi:[1,1]
	v_pk_add_f32 v[118:119], v[116:117], 0 neg_lo:[1,1] neg_hi:[1,1]
	v_pk_add_f32 v[122:123], v[120:121], 0 neg_lo:[1,1] neg_hi:[1,1]
	v_pk_add_f32 v[124:125], v[68:69], 0 neg_lo:[1,1] neg_hi:[1,1]
	ds_write_b64 v171, v[162:163]
	v_pk_fma_f32 v[78:79], v[148:149], v[78:79], v[80:81] op_sel_hi:[1,0,1]
	v_pk_mul_f32 v[80:81], v[150:151], v[84:85] op_sel:[1,0] op_sel_hi:[0,1]
	v_pk_fma_f32 v[84:85], v[154:155], v[98:99], v[96:97] op_sel_hi:[1,0,1]
	v_pk_mul_f32 v[96:97], v[132:133], v[106:107] op_sel:[1,0] op_sel_hi:[0,1]
	v_pk_add_f32 v[106:107], v[126:127], v[114:115]
	ds_write_b64 v172, v[66:67] offset:8192
	v_pk_fma_f32 v[66:67], v[130:131], v[70:71], v[72:73] op_sel_hi:[1,0,1]
	v_pk_mul_f32 v[70:71], v[142:143], v[76:77] op_sel:[1,0] op_sel_hi:[0,1]
	v_mov_b32_e32 v110, v109
	v_mov_b32_e32 v118, v117
	v_mov_b32_e32 v122, v121
	v_mov_b32_e32 v124, v69
	v_pk_add_f32 v[134:135], v[138:139], v[134:135] neg_lo:[0,1] neg_hi:[0,1]
	v_pk_fma_f32 v[98:99], v[144:145], v[112:113], v[100:101] op_sel_hi:[1,0,1]
	v_pk_add_f32 v[112:113], v[126:127], v[114:115] neg_lo:[0,1] neg_hi:[0,1]
	v_pk_mul_f32 v[76:77], v[128:129], v[88:89] op_sel:[1,0] op_sel_hi:[0,1]
	ds_write_b64 v173, v[66:67] offset:16384
	v_pk_fma_f32 v[66:67], v[142:143], v[74:75], v[70:71] op_sel_hi:[1,0,1]
	v_pk_mul_f32 v[74:75], v[106:107], v[92:93] op_sel:[1,0] op_sel_hi:[0,1]
	s_mov_b64 s[48:49], 0
	s_and_b64 vcc, exec, vcc
	v_pk_mul_f32 v[100:101], v[136:137], v[118:119] op_sel:[1,0] op_sel_hi:[0,1]
	v_pk_fma_f32 v[72:73], v[150:151], v[82:83], v[80:81] op_sel_hi:[1,0,1]
	v_pk_fma_f32 v[80:81], v[132:133], v[102:103], v[96:97] op_sel_hi:[1,0,1]
	v_pk_mul_f32 v[82:83], v[134:135], v[110:111] op_sel:[1,0] op_sel_hi:[0,1]
	v_pk_mul_f32 v[96:97], v[140:141], v[122:123] op_sel:[1,0] op_sel_hi:[0,1]
	v_pk_fma_f32 v[70:71], v[128:129], v[86:87], v[76:77] op_sel_hi:[1,0,1]
	v_pk_mul_f32 v[86:87], v[112:113], v[124:125] op_sel:[1,0] op_sel_hi:[0,1]
	ds_write_b64 v174, v[66:67] offset:24576
	ds_write_b64 v175, v[78:79] offset:32768
	ds_write_b64 v176, v[72:73] offset:40960
	ds_write_b64 v177, v[70:71] offset:49152
	v_pk_fma_f32 v[66:67], v[106:107], v[90:91], v[74:75] op_sel_hi:[1,0,1]
	v_pk_fma_f32 v[88:89], v[136:137], v[116:117], v[100:101] op_sel_hi:[1,0,1]
	v_pk_fma_f32 v[76:77], v[134:135], v[108:109], v[82:83] op_sel_hi:[1,0,1]
	v_pk_fma_f32 v[82:83], v[140:141], v[120:121], v[96:97] op_sel_hi:[1,0,1]
	v_pk_fma_f32 v[68:69], v[112:113], v[68:69], v[86:87] op_sel_hi:[1,0,1]
	ds_write_b64 v178, v[66:67] offset:57344
	ds_write_b64 v179, v[94:95]
	ds_write_b64 v180, v[84:85]
	ds_write_b64 v181, v[80:81]
	ds_write_b64 v182, v[76:77]
	ds_write_b64 v183, v[98:99]
	ds_write_b64 v184, v[88:89]
	ds_write_b64 v185, v[82:83]
	ds_write_b64 v186, v[68:69]
	s_cbranch_vccz .LBB0_362
	s_waitcnt lgkmcnt(0)
	s_barrier
	v_mov_b32 v0, 0
	s_mov_b32 s5, s14
	v_add_u32_e32 v74, v0, v170
	v_lshlrev_b32_e32 v0, 5, v74
	v_and_b32_e32 v71, 0xfffffc00, v0
	v_or_b32_e32 v75, 0x80, v71
	v_and_b32_e32 v70, 31, v74
	v_ashrrev_i32_e32 v75, 2, v75
	v_lshlrev_b32_e32 v78, 3, v71
	v_lshlrev_b32_e32 v79, 3, v70
	v_add_u32_e32 v75, 0, v75
	v_add3_u32 v111, v75, v78, v79
	v_or_b32_e32 v75, 0xa0, v71
	v_ashrrev_i32_e32 v75, 2, v75
	v_add_u32_e32 v75, 0, v75
	v_add3_u32 v110, v75, v78, v79
	v_or_b32_e32 v75, 0xc0, v71
	v_ashrrev_i32_e32 v75, 2, v75
	v_add_u32_e32 v75, 0, v75
	v_add3_u32 v109, v75, v78, v79
	v_or_b32_e32 v75, 0xe0, v71
	v_ashrrev_i32_e32 v75, 2, v75
	v_add_u32_e32 v75, 0, v75
	v_add3_u32 v108, v75, v78, v79
	v_or_b32_e32 v75, 0x100, v71
	v_ashrrev_i32_e32 v75, 2, v75
	v_add_u32_e32 v75, 0, v75
	v_add3_u32 v107, v75, v78, v79
	v_or_b32_e32 v75, 0x120, v71
	v_ashrrev_i32_e32 v75, 2, v75
	v_add_u32_e32 v75, 0, v75
	v_add3_u32 v106, v75, v78, v79
	v_or_b32_e32 v75, 0x140, v71
	v_ashrrev_i32_e32 v75, 2, v75
	v_add_u32_e32 v75, 0, v75
	v_add3_u32 v105, v75, v78, v79
	v_or_b32_e32 v75, 0x160, v71
	v_ashrrev_i32_e32 v75, 2, v75
	v_add_u32_e32 v75, 0, v75
	v_add3_u32 v103, v75, v78, v79
	v_or_b32_e32 v75, 0x180, v71
	v_ashrrev_i32_e32 v75, 2, v75
	v_add_u32_e32 v75, 0, v75
	v_add3_u32 v102, v75, v78, v79
	v_or_b32_e32 v75, 0x1a0, v71
	v_ashrrev_i32_e32 v75, 2, v75
	v_add_u32_e32 v75, 0, v75
	v_add3_u32 v101, v75, v78, v79
	v_or_b32_e32 v75, 0x1c0, v71
	v_ashrrev_i32_e32 v75, 2, v75
	v_add_u32_e32 v75, 0, v75
	v_add3_u32 v100, v75, v78, v79
	v_or_b32_e32 v75, 0x1e0, v71
	v_ashrrev_i32_e32 v75, 2, v75
	v_add_u32_e32 v75, 0, v75
	v_add3_u32 v99, v75, v78, v79
	v_or_b32_e32 v75, 0x200, v71
	v_ashrrev_i32_e32 v75, 2, v75
	v_add_u32_e32 v75, 0, v75
	v_add3_u32 v98, v75, v78, v79
	v_or_b32_e32 v75, 0x220, v71
	v_ashrrev_i32_e32 v75, 2, v75
	v_add_u32_e32 v75, 0, v75
	v_add3_u32 v97, v75, v78, v79
	v_or_b32_e32 v75, 0x240, v71
	v_ashrrev_i32_e32 v75, 2, v75
	v_add_u32_e32 v75, 0, v75
	v_add3_u32 v96, v75, v78, v79
	v_or_b32_e32 v75, 0x260, v71
	v_ashrrev_i32_e32 v75, 2, v75
	v_add_u32_e32 v75, 0, v75
	v_add3_u32 v95, v75, v78, v79
	v_or_b32_e32 v75, 0x280, v71
	v_or_b32_e32 v67, 32, v71
	v_ashrrev_i32_e32 v75, 2, v75
	v_ashrrev_i32_e32 v67, 2, v67
	v_add_u32_e32 v75, 0, v75
	v_add_u32_e32 v67, 0, v67
	v_add3_u32 v94, v75, v78, v79
	v_or_b32_e32 v75, 0x2a0, v71
	v_add3_u32 v114, v67, v78, v79
	v_or_b32_e32 v67, 64, v71
	v_ashrrev_i32_e32 v75, 2, v75
	v_ashrrev_i32_e32 v67, 2, v67
	v_add_u32_e32 v75, 0, v75
	v_add_u32_e32 v67, 0, v67
	v_add3_u32 v93, v75, v78, v79
	v_or_b32_e32 v75, 0x2c0, v71
	v_ashrrev_i32_e32 v66, 2, v71
	v_add3_u32 v113, v67, v78, v79
	v_or_b32_e32 v67, 0x60, v71
	v_ashrrev_i32_e32 v75, 2, v75
	v_add_u32_e32 v66, 0, v66
	v_ashrrev_i32_e32 v67, 2, v67
	v_add_u32_e32 v75, 0, v75
	v_add3_u32 v66, v66, v78, v79
	v_add_u32_e32 v67, 0, v67
	v_add3_u32 v92, v75, v78, v79
	v_or_b32_e32 v75, 0x2e0, v71
	v_add3_u32 v112, v67, v78, v79
	ds_read_b64 v[66:67], v66
	ds_read_b64 v[68:69], v114 offset:256
	ds_read_b64 v[72:73], v113 offset:512
	ds_read_b64 v[76:77], v112 offset:768
	ds_read_b64 v[80:81], v111 offset:1024
	ds_read_b64 v[82:83], v110 offset:1280
	ds_read_b64 v[116:117], v109 offset:1536
	ds_read_b64 v[118:119], v108 offset:1792
	ds_read_b64 v[120:121], v107 offset:2048
	ds_read_b64 v[122:123], v106 offset:2304
	ds_read_b64 v[124:125], v105 offset:2560
	ds_read_b64 v[126:127], v103 offset:2816
	ds_read_b64 v[128:129], v102 offset:3072
	ds_read_b64 v[130:131], v101 offset:3328
	ds_read_b64 v[132:133], v100 offset:3584
	ds_read_b64 v[134:135], v99 offset:3840
	ds_read_b64 v[136:137], v98 offset:4096
	ds_read_b64 v[138:139], v97 offset:4352
	ds_read_b64 v[140:141], v96 offset:4608
	ds_read_b64 v[142:143], v95 offset:4864
	v_ashrrev_i32_e32 v75, 2, v75
	v_add_u32_e32 v75, 0, v75
	v_add3_u32 v91, v75, v78, v79
	v_or_b32_e32 v75, 0x300, v71
	v_ashrrev_i32_e32 v75, 2, v75
	s_waitcnt lgkmcnt(3)
	v_pk_add_f32 v[168:169], v[66:67], v[136:137]
	v_pk_add_f32 v[66:67], v[66:67], v[136:137] neg_lo:[0,1] neg_hi:[0,1]
	s_waitcnt lgkmcnt(2)
	v_pk_add_f32 v[136:137], v[68:69], v[138:139]
	v_pk_add_f32 v[68:69], v[68:69], v[138:139] neg_lo:[0,1] neg_hi:[0,1]
	v_add_u32_e32 v75, 0, v75
	v_pk_mul_f32 v[138:139], v[68:69], s[18:19]
	v_add3_u32 v90, v75, v78, v79
	v_or_b32_e32 v75, 0x320, v71
	v_pk_fma_f32 v[68:69], v[68:69], s[20:21], v[138:139] op_sel:[0,0,1] op_sel_hi:[1,0,0]
	s_waitcnt lgkmcnt(1)
	v_pk_add_f32 v[138:139], v[72:73], v[140:141]
	v_pk_add_f32 v[72:73], v[72:73], v[140:141] neg_lo:[0,1] neg_hi:[0,1]
	v_ashrrev_i32_e32 v75, 2, v75
	v_pk_mul_f32 v[140:141], v[72:73], s[4:5]
	ds_read_b64 v[144:145], v94 offset:5120
	ds_read_b64 v[146:147], v93 offset:5376
	ds_read_b64 v[148:149], v92 offset:5632
	ds_read_b64 v[150:151], v91 offset:5888
	v_add_u32_e32 v75, 0, v75
	v_pk_fma_f32 v[72:73], v[72:73], s[6:7], v[140:141] op_sel:[0,0,1] op_sel_hi:[1,0,0]
	s_waitcnt lgkmcnt(4)
	v_pk_add_f32 v[140:141], v[76:77], v[142:143]
	v_pk_add_f32 v[76:77], v[76:77], v[142:143] neg_lo:[0,1] neg_hi:[0,1]
	v_add3_u32 v89, v75, v78, v79
	v_or_b32_e32 v75, 0x340, v71
	v_pk_mul_f32 v[142:143], v[76:77], s[22:23]
	v_ashrrev_i32_e32 v75, 2, v75
	v_pk_fma_f32 v[76:77], v[76:77], s[24:25], v[142:143] op_sel:[0,0,1] op_sel_hi:[1,0,0]
	s_waitcnt lgkmcnt(3)
	v_pk_add_f32 v[142:143], v[80:81], v[144:145]
	v_pk_add_f32 v[80:81], v[80:81], v[144:145] neg_lo:[0,1] neg_hi:[0,1]
	s_mov_b32 s9, s10
	v_add_u32_e32 v75, 0, v75
	v_pk_mul_f32 v[144:145], v[80:81], s[8:9]
	v_add3_u32 v88, v75, v78, v79
	v_or_b32_e32 v75, 0x360, v71
	v_pk_fma_f32 v[80:81], v[80:81], s[10:11], v[144:145] op_sel:[0,0,1] op_sel_hi:[1,0,0]
	s_waitcnt lgkmcnt(2)
	v_pk_add_f32 v[144:145], v[82:83], v[146:147]
	v_pk_add_f32 v[82:83], v[82:83], v[146:147] neg_lo:[0,1] neg_hi:[0,1]
	s_mov_b32 s27, s24
	v_ashrrev_i32_e32 v75, 2, v75
	v_pk_mul_f32 v[146:147], v[82:83], s[26:27]
	s_mov_b32 s0, s23
	v_add_u32_e32 v75, 0, v75
	v_pk_fma_f32 v[82:83], v[82:83], s[0:1], v[146:147] op_sel:[0,0,1] op_sel_hi:[1,0,0]
	s_waitcnt lgkmcnt(1)
	v_pk_add_f32 v[146:147], v[116:117], v[148:149]
	v_pk_add_f32 v[116:117], v[116:117], v[148:149] neg_lo:[0,1] neg_hi:[0,1]
	s_mov_b32 s13, s6
	v_add3_u32 v87, v75, v78, v79
	v_or_b32_e32 v75, 0x380, v71
	v_pk_mul_f32 v[148:149], v[116:117], s[12:13]
	ds_read_b64 v[152:153], v90 offset:6144
	ds_read_b64 v[154:155], v89 offset:6400
	ds_read_b64 v[156:157], v88 offset:6656
	ds_read_b64 v[158:159], v87 offset:6912
	v_ashrrev_i32_e32 v75, 2, v75
	v_pk_fma_f32 v[116:117], v[116:117], s[14:15], v[148:149] op_sel:[0,0,1] op_sel_hi:[1,0,0]
	s_waitcnt lgkmcnt(4)
	v_pk_add_f32 v[148:149], v[118:119], v[150:151]
	v_pk_add_f32 v[118:119], v[118:119], v[150:151] neg_lo:[0,1] neg_hi:[0,1]
	s_mov_b32 s35, s20
	v_add_u32_e32 v75, 0, v75
	v_pk_mul_f32 v[150:151], v[118:119], s[34:35]
	s_mov_b32 s48, s19
	v_add3_u32 v86, v75, v78, v79
	v_or_b32_e32 v75, 0x3a0, v71
	v_or_b32_e32 v71, 0x3c0, v71
	v_pk_fma_f32 v[118:119], v[118:119], s[48:49], v[150:151] op_sel:[0,0,1] op_sel_hi:[1,0,0]
	s_waitcnt lgkmcnt(3)
	v_pk_add_f32 v[150:151], v[120:121], v[152:153]
	v_pk_add_f32 v[120:121], v[120:121], v[152:153] neg_lo:[0,1] neg_hi:[0,1]
	v_ashrrev_i32_e32 v71, 2, v71
	v_xor_b32_e32 v153, 0x80000000, v120
	v_mov_b32_e32 v152, v121
	s_waitcnt lgkmcnt(2)
	v_pk_add_f32 v[120:121], v[122:123], v[154:155]
	v_pk_add_f32 v[122:123], v[122:123], v[154:155] neg_lo:[0,1] neg_hi:[0,1]
	v_add_u32_e32 v71, 0, v71
	v_or_b32_e32 v0, 0x3e0, v0
	v_pk_mul_f32 v[154:155], v[122:123], s[34:35]
	v_ashrrev_i32_e32 v75, 2, v75
	v_add3_u32 v84, v71, v78, v79
	v_ashrrev_i32_e32 v71, 2, v0
	v_pk_fma_f32 v[122:123], v[122:123], s[18:19], v[154:155] op_sel:[0,0,1] op_sel_hi:[1,0,0]
	s_waitcnt lgkmcnt(1)
	v_pk_add_f32 v[154:155], v[124:125], v[156:157]
	v_pk_add_f32 v[124:125], v[124:125], v[156:157] neg_lo:[0,1] neg_hi:[0,1]
	v_add_u32_e32 v75, 0, v75
	v_add_u32_e32 v71, 0, v71
	v_lshlrev_b32_e32 v0, 3, v0
	v_pk_mul_f32 v[156:157], v[124:125], s[12:13]
	v_add3_u32 v85, v75, v78, v79
	v_add3_u32 v0, v71, v0, v79
	ds_read_b64 v[160:161], v86 offset:7168
	ds_read_b64 v[162:163], v85 offset:7424
	ds_read_b64 v[164:165], v84 offset:7680
	ds_read_b64 v[166:167], v0
	v_pk_fma_f32 v[124:125], v[124:125], s[4:5], v[156:157] op_sel:[0,0,1] op_sel_hi:[1,0,0]
	s_waitcnt lgkmcnt(4)
	v_pk_add_f32 v[156:157], v[126:127], v[158:159]
	v_pk_add_f32 v[126:127], v[126:127], v[158:159] neg_lo:[0,1] neg_hi:[0,1]
	v_lshlrev_b32_e32 v70, 4, v70
	v_pk_mul_f32 v[158:159], v[126:127], s[26:27]
	v_cvt_f32_u32_e32 v75, v70
	v_pk_fma_f32 v[126:127], v[126:127], s[22:23], v[158:159] op_sel:[0,0,1] op_sel_hi:[1,0,0]
	s_waitcnt lgkmcnt(3)
	v_pk_add_f32 v[158:159], v[128:129], v[160:161]
	v_pk_add_f32 v[128:129], v[128:129], v[160:161] neg_lo:[0,1] neg_hi:[0,1]
	v_and_b32_e32 v74, 0x1fffffe0, v74
	v_pk_mul_f32 v[160:161], v[128:129], s[8:9]
	v_mul_f32_e32 v115, 0x38800000, v75
	v_pk_fma_f32 v[128:129], v[128:129], s[8:9], v[160:161] op_sel:[0,0,1] op_sel_hi:[1,0,0]
	s_waitcnt lgkmcnt(2)
	v_pk_add_f32 v[160:161], v[130:131], v[162:163]
	v_pk_add_f32 v[130:131], v[130:131], v[162:163] neg_lo:[0,1] neg_hi:[0,1]
	v_lshl_add_u32 v74, v74, 3, 0
	v_pk_mul_f32 v[162:163], v[130:131], s[22:23]
	v_sin_f32_e32 v75, v115
	v_pk_fma_f32 v[130:131], v[130:131], s[26:27], v[162:163] op_sel:[0,0,1] op_sel_hi:[1,0,0]
	s_waitcnt lgkmcnt(1)
	v_pk_add_f32 v[162:163], v[132:133], v[164:165]
	v_pk_add_f32 v[132:133], v[132:133], v[164:165] neg_lo:[0,1] neg_hi:[0,1]
	v_add3_u32 v74, v74, v78, v79
	v_pk_mul_f32 v[164:165], v[132:133], s[4:5]
	v_xor_b32_e32 v78, 0x80000000, v75
	v_pk_fma_f32 v[132:133], v[132:133], s[12:13], v[164:165] op_sel:[0,0,1] op_sel_hi:[1,0,0]
	s_waitcnt lgkmcnt(0)
	v_pk_add_f32 v[164:165], v[134:135], v[166:167]
	v_pk_add_f32 v[134:135], v[134:135], v[166:167] neg_lo:[0,1] neg_hi:[0,1]
	v_mov_b32_e32 v79, v75
	v_pk_mul_f32 v[166:167], v[134:135], s[18:19]
	s_mov_b32 s50, s19
	v_pk_fma_f32 v[134:135], v[134:135], s[34:35], v[166:167] op_sel:[0,0,1] op_sel_hi:[1,0,0]
	v_pk_add_f32 v[166:167], v[168:169], v[150:151]
	v_pk_add_f32 v[150:151], v[168:169], v[150:151] neg_lo:[0,1] neg_hi:[0,1]
	v_pk_add_f32 v[168:169], v[136:137], v[120:121]
	v_pk_add_f32 v[120:121], v[136:137], v[120:121] neg_lo:[0,1] neg_hi:[0,1]
	s_mov_b32 s51, s18
	v_pk_mul_f32 v[136:137], v[120:121], s[4:5]
	s_mov_b32 s52, s23
	v_pk_fma_f32 v[120:121], v[120:121], s[6:7], v[136:137] op_sel:[0,0,1] op_sel_hi:[1,0,0]
	v_pk_add_f32 v[136:137], v[138:139], v[154:155]
	v_pk_add_f32 v[138:139], v[138:139], v[154:155] neg_lo:[0,1] neg_hi:[0,1]
	s_mov_b32 s53, s22
	v_pk_mul_f32 v[154:155], v[138:139], s[8:9]
	s_nop 0
	v_pk_fma_f32 v[138:139], v[138:139], s[10:11], v[154:155] op_sel:[0,0,1] op_sel_hi:[1,0,0]
	v_pk_add_f32 v[154:155], v[140:141], v[156:157]
	v_pk_add_f32 v[140:141], v[140:141], v[156:157] neg_lo:[0,1] neg_hi:[0,1]
	s_nop 0
	v_pk_mul_f32 v[156:157], v[140:141], s[12:13]
	s_nop 0
	v_pk_fma_f32 v[140:141], v[140:141], s[14:15], v[156:157] op_sel:[0,0,1] op_sel_hi:[1,0,0]
	v_pk_add_f32 v[156:157], v[142:143], v[158:159]
	v_pk_add_f32 v[142:143], v[142:143], v[158:159] neg_lo:[0,1] neg_hi:[0,1]
	s_nop 0
	v_xor_b32_e32 v159, 0x80000000, v142
	v_mov_b32_e32 v158, v143
	v_pk_add_f32 v[142:143], v[144:145], v[160:161]
	v_pk_add_f32 v[144:145], v[144:145], v[160:161] neg_lo:[0,1] neg_hi:[0,1]
	s_nop 0
	v_pk_mul_f32 v[160:161], v[144:145], s[12:13]
	s_nop 0
	v_pk_fma_f32 v[144:145], v[144:145], s[4:5], v[160:161] op_sel:[0,0,1] op_sel_hi:[1,0,0]
	v_pk_add_f32 v[160:161], v[146:147], v[162:163]
	v_pk_add_f32 v[146:147], v[146:147], v[162:163] neg_lo:[0,1] neg_hi:[0,1]
	s_nop 0
	v_pk_mul_f32 v[162:163], v[146:147], s[8:9]
	s_nop 0
	v_pk_fma_f32 v[146:147], v[146:147], s[8:9], v[162:163] op_sel:[0,0,1] op_sel_hi:[1,0,0]
	v_pk_add_f32 v[162:163], v[148:149], v[164:165]
	v_pk_add_f32 v[148:149], v[148:149], v[164:165] neg_lo:[0,1] neg_hi:[0,1]
	s_nop 0
	v_pk_mul_f32 v[164:165], v[148:149], s[4:5]
	s_nop 0
	v_pk_fma_f32 v[148:149], v[148:149], s[12:13], v[164:165] op_sel:[0,0,1] op_sel_hi:[1,0,0]
	v_pk_add_f32 v[164:165], v[66:67], v[152:153]
	v_pk_add_f32 v[66:67], v[66:67], v[152:153] neg_lo:[0,1] neg_hi:[0,1]
	v_pk_add_f32 v[152:153], v[68:69], v[122:123]
	v_pk_add_f32 v[68:69], v[68:69], v[122:123] neg_lo:[0,1] neg_hi:[0,1]
	s_nop 0
	v_pk_mul_f32 v[122:123], v[68:69], s[4:5]
	s_nop 0
	v_pk_fma_f32 v[68:69], v[68:69], s[6:7], v[122:123] op_sel:[0,0,1] op_sel_hi:[1,0,0]
	v_pk_add_f32 v[122:123], v[72:73], v[124:125]
	v_pk_add_f32 v[72:73], v[72:73], v[124:125] neg_lo:[0,1] neg_hi:[0,1]
	s_nop 0
	v_pk_mul_f32 v[124:125], v[72:73], s[8:9]
	s_nop 0
	v_pk_fma_f32 v[72:73], v[72:73], s[10:11], v[124:125] op_sel:[0,0,1] op_sel_hi:[1,0,0]
	v_pk_add_f32 v[124:125], v[76:77], v[126:127]
	v_pk_add_f32 v[76:77], v[76:77], v[126:127] neg_lo:[0,1] neg_hi:[0,1]
	s_nop 0
	v_pk_mul_f32 v[126:127], v[76:77], s[12:13]
	s_nop 0
	v_pk_fma_f32 v[76:77], v[76:77], s[14:15], v[126:127] op_sel:[0,0,1] op_sel_hi:[1,0,0]
	v_pk_add_f32 v[126:127], v[80:81], v[128:129]
	v_pk_add_f32 v[80:81], v[80:81], v[128:129] neg_lo:[0,1] neg_hi:[0,1]
	s_nop 0
	v_xor_b32_e32 v129, 0x80000000, v80
	v_mov_b32_e32 v128, v81
	v_pk_add_f32 v[80:81], v[82:83], v[130:131]
	v_pk_add_f32 v[82:83], v[82:83], v[130:131] neg_lo:[0,1] neg_hi:[0,1]
	s_nop 0
	v_pk_mul_f32 v[130:131], v[82:83], s[12:13]
	s_nop 0
	v_pk_fma_f32 v[82:83], v[82:83], s[4:5], v[130:131] op_sel:[0,0,1] op_sel_hi:[1,0,0]
	v_pk_add_f32 v[130:131], v[116:117], v[132:133]
	v_pk_add_f32 v[116:117], v[116:117], v[132:133] neg_lo:[0,1] neg_hi:[0,1]
	s_nop 0
	v_pk_mul_f32 v[132:133], v[116:117], s[8:9]
	s_nop 0
	v_pk_fma_f32 v[116:117], v[116:117], s[8:9], v[132:133] op_sel:[0,0,1] op_sel_hi:[1,0,0]
	v_pk_add_f32 v[132:133], v[118:119], v[134:135]
	v_pk_add_f32 v[118:119], v[118:119], v[134:135] neg_lo:[0,1] neg_hi:[0,1]
	s_nop 0
	v_pk_mul_f32 v[134:135], v[118:119], s[4:5]
	s_nop 0
	v_pk_fma_f32 v[118:119], v[118:119], s[12:13], v[134:135] op_sel:[0,0,1] op_sel_hi:[1,0,0]
	v_pk_add_f32 v[134:135], v[166:167], v[156:157]
	v_pk_add_f32 v[156:157], v[166:167], v[156:157] neg_lo:[0,1] neg_hi:[0,1]
	v_pk_add_f32 v[166:167], v[168:169], v[142:143]
	v_pk_add_f32 v[142:143], v[168:169], v[142:143] neg_lo:[0,1] neg_hi:[0,1]
	s_nop 0
	v_pk_mul_f32 v[168:169], v[142:143], s[8:9]
	s_nop 0
	v_pk_fma_f32 v[142:143], v[142:143], s[10:11], v[168:169] op_sel:[0,0,1] op_sel_hi:[1,0,0]
	v_pk_add_f32 v[168:169], v[136:137], v[160:161]
	v_pk_add_f32 v[136:137], v[136:137], v[160:161] neg_lo:[0,1] neg_hi:[0,1]
	s_nop 0
	v_xor_b32_e32 v161, 0x80000000, v136
	v_mov_b32_e32 v160, v137
	v_pk_add_f32 v[136:137], v[154:155], v[162:163]
	v_pk_add_f32 v[154:155], v[154:155], v[162:163] neg_lo:[0,1] neg_hi:[0,1]
	s_nop 0
	v_pk_mul_f32 v[162:163], v[154:155], s[8:9]
	s_nop 0
	v_pk_fma_f32 v[154:155], v[154:155], s[8:9], v[162:163] op_sel:[0,0,1] op_sel_hi:[1,0,0]
	v_pk_add_f32 v[162:163], v[150:151], v[158:159]
	v_pk_add_f32 v[150:151], v[150:151], v[158:159] neg_lo:[0,1] neg_hi:[0,1]
	v_pk_add_f32 v[158:159], v[120:121], v[144:145]
	v_pk_add_f32 v[120:121], v[120:121], v[144:145] neg_lo:[0,1] neg_hi:[0,1]
	s_nop 0
	v_pk_mul_f32 v[144:145], v[120:121], s[8:9]
	s_nop 0
	v_pk_fma_f32 v[120:121], v[120:121], s[10:11], v[144:145] op_sel:[0,0,1] op_sel_hi:[1,0,0]
	v_pk_add_f32 v[144:145], v[138:139], v[146:147]
	v_pk_add_f32 v[138:139], v[138:139], v[146:147] neg_lo:[0,1] neg_hi:[0,1]
	s_nop 0
	v_xor_b32_e32 v147, 0x80000000, v138
	v_mov_b32_e32 v146, v139
	v_pk_add_f32 v[138:139], v[140:141], v[148:149]
	v_pk_add_f32 v[140:141], v[140:141], v[148:149] neg_lo:[0,1] neg_hi:[0,1]
	s_nop 0
	v_pk_mul_f32 v[148:149], v[140:141], s[8:9]
	s_nop 0
	v_pk_fma_f32 v[140:141], v[140:141], s[8:9], v[148:149] op_sel:[0,0,1] op_sel_hi:[1,0,0]
	v_pk_add_f32 v[148:149], v[164:165], v[126:127]
	v_pk_add_f32 v[126:127], v[164:165], v[126:127] neg_lo:[0,1] neg_hi:[0,1]
	v_pk_add_f32 v[164:165], v[152:153], v[80:81]
	v_pk_add_f32 v[80:81], v[152:153], v[80:81] neg_lo:[0,1] neg_hi:[0,1]
	s_nop 0
	v_pk_mul_f32 v[152:153], v[80:81], s[8:9]
	s_nop 0
	v_pk_fma_f32 v[80:81], v[80:81], s[10:11], v[152:153] op_sel:[0,0,1] op_sel_hi:[1,0,0]
	v_pk_add_f32 v[152:153], v[122:123], v[130:131]
	v_pk_add_f32 v[122:123], v[122:123], v[130:131] neg_lo:[0,1] neg_hi:[0,1]
	s_nop 0
	v_xor_b32_e32 v131, 0x80000000, v122
	v_mov_b32_e32 v130, v123
	v_pk_add_f32 v[122:123], v[124:125], v[132:133]
	v_pk_add_f32 v[124:125], v[124:125], v[132:133] neg_lo:[0,1] neg_hi:[0,1]
	s_nop 0
	v_pk_mul_f32 v[132:133], v[124:125], s[8:9]
	s_nop 0
	v_pk_fma_f32 v[124:125], v[124:125], s[8:9], v[132:133] op_sel:[0,0,1] op_sel_hi:[1,0,0]
	v_pk_add_f32 v[132:133], v[66:67], v[128:129]
	v_pk_add_f32 v[66:67], v[66:67], v[128:129] neg_lo:[0,1] neg_hi:[0,1]
	v_pk_add_f32 v[128:129], v[68:69], v[82:83]
	v_pk_add_f32 v[68:69], v[68:69], v[82:83] neg_lo:[0,1] neg_hi:[0,1]
	s_nop 0
	v_pk_mul_f32 v[82:83], v[68:69], s[8:9]
	s_nop 0
	v_pk_fma_f32 v[68:69], v[68:69], s[10:11], v[82:83] op_sel:[0,0,1] op_sel_hi:[1,0,0]
	v_pk_add_f32 v[82:83], v[72:73], v[116:117]
	v_pk_add_f32 v[72:73], v[72:73], v[116:117] neg_lo:[0,1] neg_hi:[0,1]
	s_nop 0
	v_xor_b32_e32 v117, 0x80000000, v72
	v_mov_b32_e32 v116, v73
	v_pk_add_f32 v[72:73], v[76:77], v[118:119]
	v_pk_add_f32 v[76:77], v[76:77], v[118:119] neg_lo:[0,1] neg_hi:[0,1]
	v_pk_add_f32 v[174:175], v[66:67], v[116:117]
	v_pk_mul_f32 v[118:119], v[76:77], s[8:9]
	v_pk_add_f32 v[116:117], v[66:67], v[116:117] neg_lo:[0,1] neg_hi:[0,1]
	v_pk_fma_f32 v[76:77], v[76:77], s[8:9], v[118:119] op_sel:[0,0,1] op_sel_hi:[1,0,0]
	v_pk_add_f32 v[118:119], v[134:135], v[168:169]
	v_pk_add_f32 v[134:135], v[134:135], v[168:169] neg_lo:[0,1] neg_hi:[0,1]
	v_pk_add_f32 v[168:169], v[166:167], v[136:137]
	v_pk_add_f32 v[136:137], v[166:167], v[136:137] neg_lo:[0,1] neg_hi:[0,1]
	v_pk_add_f32 v[180:181], v[118:119], v[168:169]
	v_xor_b32_e32 v167, 0x80000000, v136
	v_mov_b32_e32 v166, v137
	v_pk_add_f32 v[136:137], v[156:157], v[160:161]
	v_pk_add_f32 v[156:157], v[156:157], v[160:161] neg_lo:[0,1] neg_hi:[0,1]
	v_pk_add_f32 v[160:161], v[142:143], v[154:155]
	v_pk_add_f32 v[142:143], v[142:143], v[154:155] neg_lo:[0,1] neg_hi:[0,1]
	v_pk_add_f32 v[66:67], v[68:69], v[76:77] neg_lo:[0,1] neg_hi:[0,1]
	v_xor_b32_e32 v155, 0x80000000, v142
	v_mov_b32_e32 v154, v143
	v_pk_add_f32 v[142:143], v[162:163], v[144:145]
	v_pk_add_f32 v[144:145], v[162:163], v[144:145] neg_lo:[0,1] neg_hi:[0,1]
	v_pk_add_f32 v[162:163], v[158:159], v[138:139]
	v_pk_add_f32 v[138:139], v[158:159], v[138:139] neg_lo:[0,1] neg_hi:[0,1]
	ds_write_b64 v74, v[180:181]
	v_xor_b32_e32 v159, 0x80000000, v138
	v_mov_b32_e32 v158, v139
	v_pk_add_f32 v[138:139], v[150:151], v[146:147]
	v_pk_add_f32 v[146:147], v[150:151], v[146:147] neg_lo:[0,1] neg_hi:[0,1]
	v_pk_add_f32 v[150:151], v[120:121], v[140:141]
	v_pk_add_f32 v[120:121], v[120:121], v[140:141] neg_lo:[0,1] neg_hi:[0,1]
	v_cos_f32_e32 v74, v115
	v_xor_b32_e32 v141, 0x80000000, v120
	v_mov_b32_e32 v140, v121
	v_pk_add_f32 v[120:121], v[148:149], v[152:153]
	v_pk_add_f32 v[148:149], v[148:149], v[152:153] neg_lo:[0,1] neg_hi:[0,1]
	v_pk_add_f32 v[152:153], v[164:165], v[122:123]
	v_pk_add_f32 v[122:123], v[164:165], v[122:123] neg_lo:[0,1] neg_hi:[0,1]
	v_xor_b32_e32 v179, 0x80000000, v66
	v_xor_b32_e32 v165, 0x80000000, v122
	v_mov_b32_e32 v164, v123
	v_pk_add_f32 v[122:123], v[126:127], v[130:131]
	v_pk_add_f32 v[126:127], v[126:127], v[130:131] neg_lo:[0,1] neg_hi:[0,1]
	v_pk_add_f32 v[130:131], v[80:81], v[124:125]
	v_pk_add_f32 v[80:81], v[80:81], v[124:125] neg_lo:[0,1] neg_hi:[0,1]
	v_mov_b32_e32 v178, v67
	v_xor_b32_e32 v125, 0x80000000, v80
	v_mov_b32_e32 v124, v81
	v_pk_add_f32 v[80:81], v[132:133], v[82:83]
	v_pk_add_f32 v[132:133], v[132:133], v[82:83] neg_lo:[0,1] neg_hi:[0,1]
	v_pk_add_f32 v[176:177], v[68:69], v[76:77]
	v_pk_add_f32 v[118:119], v[118:119], v[168:169] neg_lo:[0,1] neg_hi:[0,1]
	v_pk_add_f32 v[168:169], v[134:135], v[166:167]
	v_pk_add_f32 v[82:83], v[134:135], v[166:167] neg_lo:[0,1] neg_hi:[0,1]
	v_pk_add_f32 v[134:135], v[136:137], v[160:161]
	v_pk_add_f32 v[136:137], v[136:137], v[160:161] neg_lo:[0,1] neg_hi:[0,1]
	v_pk_add_f32 v[160:161], v[156:157], v[154:155]
	v_pk_add_f32 v[68:69], v[156:157], v[154:155] neg_lo:[0,1] neg_hi:[0,1]
	v_pk_add_f32 v[154:155], v[142:143], v[162:163]
	v_pk_add_f32 v[142:143], v[142:143], v[162:163] neg_lo:[0,1] neg_hi:[0,1]
	v_pk_add_f32 v[156:157], v[144:145], v[158:159]
	v_pk_add_f32 v[76:77], v[144:145], v[158:159] neg_lo:[0,1] neg_hi:[0,1]
	v_pk_add_f32 v[144:145], v[138:139], v[150:151]
	v_pk_add_f32 v[138:139], v[138:139], v[150:151] neg_lo:[0,1] neg_hi:[0,1]
	v_pk_add_f32 v[150:151], v[146:147], v[140:141]
	v_pk_add_f32 v[66:67], v[146:147], v[140:141] neg_lo:[0,1] neg_hi:[0,1]
	v_pk_add_f32 v[140:141], v[120:121], v[152:153]
	v_pk_add_f32 v[162:163], v[116:117], v[178:179]
	v_pk_add_f32 v[70:71], v[116:117], v[178:179] neg_lo:[0,1] neg_hi:[0,1]
	v_mov_b32_e32 v116, v75
	v_pk_mul_f32 v[116:117], v[116:117], v[140:141] op_sel:[0,1] op_sel_hi:[0,0] neg_hi:[1,0]
	v_pk_fma_f32 v[116:117], v[140:141], v[74:75], v[116:117] op_sel_hi:[1,0,1]
	ds_write_b64 v114, v[116:117] offset:256
	v_pk_mul_f32 v[114:115], v[78:79], v[74:75] op_sel:[0,1] op_sel_hi:[1,0]
	v_pk_add_f32 v[172:173], v[128:129], v[72:73]
	v_pk_fma_f32 v[114:115], v[74:75], v[74:75], v[114:115] op_sel_hi:[1,0,1]
	v_pk_add_f32 v[72:73], v[128:129], v[72:73] neg_lo:[0,1] neg_hi:[0,1]
	v_pk_add_f32 v[116:117], v[114:115], 0 neg_lo:[1,1] neg_hi:[1,1]
	v_xor_b32_e32 v129, 0x80000000, v72
	v_mov_b32_e32 v116, v115
	v_pk_mul_f32 v[116:117], v[116:117], v[154:155] op_sel:[0,1] op_sel_hi:[1,0]
	v_mov_b32_e32 v128, v73
	v_pk_fma_f32 v[116:117], v[154:155], v[114:115], v[116:117] op_sel_hi:[1,0,1]
	ds_write_b64 v113, v[116:117] offset:512
	v_pk_mul_f32 v[116:117], v[78:79], v[114:115] op_sel:[0,1] op_sel_hi:[1,0]
	v_pk_add_f32 v[120:121], v[120:121], v[152:153] neg_lo:[0,1] neg_hi:[0,1]
	v_pk_fma_f32 v[114:115], v[114:115], v[74:75], v[116:117] op_sel_hi:[1,0,1]
	v_pk_add_f32 v[152:153], v[122:123], v[130:131]
	v_pk_add_f32 v[116:117], v[114:115], 0 neg_lo:[1,1] neg_hi:[1,1]
	v_pk_add_f32 v[122:123], v[122:123], v[130:131] neg_lo:[0,1] neg_hi:[0,1]
	v_pk_add_f32 v[130:131], v[126:127], v[124:125]
	v_pk_add_f32 v[72:73], v[126:127], v[124:125] neg_lo:[0,1] neg_hi:[0,1]
	v_pk_add_f32 v[124:125], v[80:81], v[172:173]
	v_mov_b32_e32 v116, v115
	v_pk_mul_f32 v[116:117], v[116:117], v[124:125] op_sel:[0,1] op_sel_hi:[1,0]
	v_pk_add_f32 v[126:127], v[80:81], v[172:173] neg_lo:[0,1] neg_hi:[0,1]
	v_pk_fma_f32 v[116:117], v[124:125], v[114:115], v[116:117] op_sel_hi:[1,0,1]
	ds_write_b64 v112, v[116:117] offset:768
	v_pk_mul_f32 v[112:113], v[78:79], v[114:115] op_sel:[0,1] op_sel_hi:[1,0]
	v_pk_add_f32 v[158:159], v[132:133], v[128:129]
	v_pk_fma_f32 v[112:113], v[114:115], v[74:75], v[112:113] op_sel_hi:[1,0,1]
	v_pk_add_f32 v[80:81], v[132:133], v[128:129] neg_lo:[0,1] neg_hi:[0,1]
	v_pk_add_f32 v[114:115], v[112:113], 0 neg_lo:[1,1] neg_hi:[1,1]
	v_pk_add_f32 v[128:129], v[174:175], v[176:177]
	v_mov_b32_e32 v114, v113
	v_pk_mul_f32 v[114:115], v[114:115], v[134:135] op_sel:[0,1] op_sel_hi:[1,0]
	v_pk_add_f32 v[146:147], v[148:149], v[164:165]
	v_pk_fma_f32 v[114:115], v[134:135], v[112:113], v[114:115] op_sel_hi:[1,0,1]
	ds_write_b64 v111, v[114:115] offset:1024
	v_pk_mul_f32 v[114:115], v[78:79], v[112:113] op_sel:[0,1] op_sel_hi:[1,0]
	v_pk_add_f32 v[132:133], v[174:175], v[176:177] neg_lo:[0,1] neg_hi:[0,1]
	v_pk_fma_f32 v[112:113], v[112:113], v[74:75], v[114:115] op_sel_hi:[1,0,1]
	v_pk_add_f32 v[148:149], v[148:149], v[164:165] neg_lo:[0,1] neg_hi:[0,1]
	v_pk_add_f32 v[114:115], v[112:113], 0 neg_lo:[1,1] neg_hi:[1,1]
	s_nop 0
	v_mov_b32_e32 v114, v113
	v_pk_mul_f32 v[114:115], v[114:115], v[152:153] op_sel:[0,1] op_sel_hi:[1,0]
	s_nop 0
	v_pk_fma_f32 v[114:115], v[152:153], v[112:113], v[114:115] op_sel_hi:[1,0,1]
	ds_write_b64 v110, v[114:115] offset:1280
	v_pk_mul_f32 v[110:111], v[78:79], v[112:113] op_sel:[0,1] op_sel_hi:[1,0]
	s_nop 0
	v_pk_fma_f32 v[110:111], v[112:113], v[74:75], v[110:111] op_sel_hi:[1,0,1]
	s_nop 0
	v_pk_add_f32 v[112:113], v[110:111], 0 neg_lo:[1,1] neg_hi:[1,1]
	s_nop 0
	v_mov_b32_e32 v112, v111
	v_pk_mul_f32 v[112:113], v[112:113], v[144:145] op_sel:[0,1] op_sel_hi:[1,0]
	s_nop 0
	v_pk_fma_f32 v[112:113], v[144:145], v[110:111], v[112:113] op_sel_hi:[1,0,1]
	ds_write_b64 v109, v[112:113] offset:1536
	v_pk_mul_f32 v[112:113], v[78:79], v[110:111] op_sel:[0,1] op_sel_hi:[1,0]
	s_nop 0
	v_pk_fma_f32 v[110:111], v[110:111], v[74:75], v[112:113] op_sel_hi:[1,0,1]
	s_nop 0
	v_pk_add_f32 v[112:113], v[110:111], 0 neg_lo:[1,1] neg_hi:[1,1]
	s_nop 0
	v_mov_b32_e32 v112, v111
	v_pk_mul_f32 v[112:113], v[112:113], v[128:129] op_sel:[0,1] op_sel_hi:[1,0]
	s_nop 0
	v_pk_fma_f32 v[112:113], v[128:129], v[110:111], v[112:113] op_sel_hi:[1,0,1]
	ds_write_b64 v108, v[112:113] offset:1792
	v_pk_mul_f32 v[108:109], v[78:79], v[110:111] op_sel:[0,1] op_sel_hi:[1,0]
	s_nop 0
	v_pk_fma_f32 v[108:109], v[110:111], v[74:75], v[108:109] op_sel_hi:[1,0,1]
	s_nop 0
	v_pk_add_f32 v[110:111], v[108:109], 0 neg_lo:[1,1] neg_hi:[1,1]
	s_nop 0
	v_mov_b32_e32 v110, v109
	v_pk_mul_f32 v[110:111], v[110:111], v[168:169] op_sel:[0,1] op_sel_hi:[1,0]
	s_nop 0
	v_pk_fma_f32 v[110:111], v[168:169], v[108:109], v[110:111] op_sel_hi:[1,0,1]
	ds_write_b64 v107, v[110:111] offset:2048
	v_pk_mul_f32 v[110:111], v[78:79], v[108:109] op_sel:[0,1] op_sel_hi:[1,0]
	s_nop 0
	v_pk_fma_f32 v[108:109], v[108:109], v[74:75], v[110:111] op_sel_hi:[1,0,1]
	s_nop 0
	v_pk_add_f32 v[110:111], v[108:109], 0 neg_lo:[1,1] neg_hi:[1,1]
	s_nop 0
	v_mov_b32_e32 v110, v109
	v_pk_mul_f32 v[110:111], v[110:111], v[146:147] op_sel:[0,1] op_sel_hi:[1,0]
	s_nop 0
	v_pk_fma_f32 v[110:111], v[146:147], v[108:109], v[110:111] op_sel_hi:[1,0,1]
	ds_write_b64 v106, v[110:111] offset:2304
	v_pk_mul_f32 v[106:107], v[78:79], v[108:109] op_sel:[0,1] op_sel_hi:[1,0]
	s_nop 0
	v_pk_fma_f32 v[106:107], v[108:109], v[74:75], v[106:107] op_sel_hi:[1,0,1]
	s_nop 0
	v_pk_add_f32 v[108:109], v[106:107], 0 neg_lo:[1,1] neg_hi:[1,1]
	s_nop 0
	v_mov_b32_e32 v108, v107
	v_pk_mul_f32 v[108:109], v[108:109], v[156:157] op_sel:[0,1] op_sel_hi:[1,0]
	s_nop 0
	v_pk_fma_f32 v[108:109], v[156:157], v[106:107], v[108:109] op_sel_hi:[1,0,1]
	ds_write_b64 v105, v[108:109] offset:2560
	v_pk_mul_f32 v[108:109], v[78:79], v[106:107] op_sel:[0,1] op_sel_hi:[1,0]
	s_nop 0
	v_pk_fma_f32 v[106:107], v[106:107], v[74:75], v[108:109] op_sel_hi:[1,0,1]
	s_nop 0
	v_pk_add_f32 v[108:109], v[106:107], 0 neg_lo:[1,1] neg_hi:[1,1]
	s_nop 0
	v_mov_b32_e32 v108, v107
	v_pk_mul_f32 v[108:109], v[108:109], v[158:159] op_sel:[0,1] op_sel_hi:[1,0]
	s_nop 0
	v_pk_fma_f32 v[108:109], v[158:159], v[106:107], v[108:109] op_sel_hi:[1,0,1]
	ds_write_b64 v103, v[108:109] offset:2816
	v_pk_mul_f32 v[108:109], v[78:79], v[106:107] op_sel:[0,1] op_sel_hi:[1,0]
	s_nop 0
	v_pk_fma_f32 v[106:107], v[106:107], v[74:75], v[108:109] op_sel_hi:[1,0,1]
	s_nop 0
	v_pk_add_f32 v[108:109], v[106:107], 0 neg_lo:[1,1] neg_hi:[1,1]
	s_nop 0
	v_mov_b32_e32 v108, v107
	v_pk_mul_f32 v[108:109], v[108:109], v[160:161] op_sel:[0,1] op_sel_hi:[1,0]
	s_nop 0
	v_pk_fma_f32 v[108:109], v[160:161], v[106:107], v[108:109] op_sel_hi:[1,0,1]
	ds_write_b64 v102, v[108:109] offset:3072
	v_pk_mul_f32 v[102:103], v[78:79], v[106:107] op_sel:[0,1] op_sel_hi:[1,0]
	s_nop 0
	v_pk_fma_f32 v[102:103], v[106:107], v[74:75], v[102:103] op_sel_hi:[1,0,1]
	s_nop 0
	v_pk_add_f32 v[106:107], v[102:103], 0 neg_lo:[1,1] neg_hi:[1,1]
	s_nop 0
	v_mov_b32_e32 v106, v103
	v_pk_mul_f32 v[106:107], v[106:107], v[130:131] op_sel:[0,1] op_sel_hi:[1,0]
	s_nop 0
	v_pk_fma_f32 v[106:107], v[130:131], v[102:103], v[106:107] op_sel_hi:[1,0,1]
	ds_write_b64 v101, v[106:107] offset:3328
	v_pk_mul_f32 v[106:107], v[78:79], v[102:103] op_sel:[0,1] op_sel_hi:[1,0]
	s_nop 0
	v_pk_fma_f32 v[102:103], v[102:103], v[74:75], v[106:107] op_sel_hi:[1,0,1]
	s_nop 0
	v_pk_add_f32 v[106:107], v[102:103], 0 neg_lo:[1,1] neg_hi:[1,1]
	s_nop 0
	v_mov_b32_e32 v106, v103
	v_pk_mul_f32 v[106:107], v[150:151], v[106:107] op_sel:[1,0] op_sel_hi:[0,1]
	v_pk_fma_f32 v[106:107], v[150:151], v[102:103], v[106:107] op_sel_hi:[1,0,1]
	ds_write_b64 v100, v[106:107] offset:3584
	v_pk_mul_f32 v[100:101], v[78:79], v[102:103] op_sel:[0,1] op_sel_hi:[1,0]
	s_nop 0
	v_pk_fma_f32 v[100:101], v[102:103], v[74:75], v[100:101] op_sel_hi:[1,0,1]
	s_nop 0
	v_pk_add_f32 v[102:103], v[100:101], 0 neg_lo:[1,1] neg_hi:[1,1]
	s_nop 0
	v_mov_b32_e32 v102, v101
	v_pk_mul_f32 v[102:103], v[162:163], v[102:103] op_sel:[1,0] op_sel_hi:[0,1]
	v_pk_fma_f32 v[102:103], v[162:163], v[100:101], v[102:103] op_sel_hi:[1,0,1]
	ds_write_b64 v99, v[102:103] offset:3840
	v_pk_mul_f32 v[102:103], v[78:79], v[100:101] op_sel:[0,1] op_sel_hi:[1,0]
	s_nop 0
	v_pk_fma_f32 v[100:101], v[100:101], v[74:75], v[102:103] op_sel_hi:[1,0,1]
	s_nop 0
	v_pk_add_f32 v[102:103], v[100:101], 0 neg_lo:[1,1] neg_hi:[1,1]
	s_nop 0
	v_mov_b32_e32 v102, v101
	v_pk_mul_f32 v[102:103], v[118:119], v[102:103] op_sel:[1,0] op_sel_hi:[0,1]
	v_pk_fma_f32 v[102:103], v[118:119], v[100:101], v[102:103] op_sel_hi:[1,0,1]
	ds_write_b64 v98, v[102:103] offset:4096
	v_pk_mul_f32 v[98:99], v[78:79], v[100:101] op_sel:[0,1] op_sel_hi:[1,0]
	s_nop 0
	v_pk_fma_f32 v[98:99], v[100:101], v[74:75], v[98:99] op_sel_hi:[1,0,1]
	s_nop 0
	v_pk_add_f32 v[100:101], v[98:99], 0 neg_lo:[1,1] neg_hi:[1,1]
	s_nop 0
	v_mov_b32_e32 v100, v99
	v_pk_mul_f32 v[100:101], v[120:121], v[100:101] op_sel:[1,0] op_sel_hi:[0,1]
	v_pk_fma_f32 v[100:101], v[120:121], v[98:99], v[100:101] op_sel_hi:[1,0,1]
	ds_write_b64 v97, v[100:101] offset:4352
	v_pk_mul_f32 v[100:101], v[78:79], v[98:99] op_sel:[0,1] op_sel_hi:[1,0]
	s_nop 0
	v_pk_fma_f32 v[98:99], v[98:99], v[74:75], v[100:101] op_sel_hi:[1,0,1]
	s_nop 0
	v_pk_add_f32 v[100:101], v[98:99], 0 neg_lo:[1,1] neg_hi:[1,1]
	s_nop 0
	v_mov_b32_e32 v100, v99
	v_pk_mul_f32 v[100:101], v[142:143], v[100:101] op_sel:[1,0] op_sel_hi:[0,1]
	v_pk_fma_f32 v[100:101], v[142:143], v[98:99], v[100:101] op_sel_hi:[1,0,1]
	ds_write_b64 v96, v[100:101] offset:4608
	v_pk_mul_f32 v[96:97], v[78:79], v[98:99] op_sel:[0,1] op_sel_hi:[1,0]
	s_nop 0
	v_pk_fma_f32 v[96:97], v[98:99], v[74:75], v[96:97] op_sel_hi:[1,0,1]
	s_nop 0
	v_pk_add_f32 v[98:99], v[96:97], 0 neg_lo:[1,1] neg_hi:[1,1]
	s_nop 0
	v_mov_b32_e32 v98, v97
	v_pk_mul_f32 v[98:99], v[126:127], v[98:99] op_sel:[1,0] op_sel_hi:[0,1]
	v_pk_fma_f32 v[98:99], v[126:127], v[96:97], v[98:99] op_sel_hi:[1,0,1]
	ds_write_b64 v95, v[98:99] offset:4864
	v_pk_mul_f32 v[98:99], v[78:79], v[96:97] op_sel:[0,1] op_sel_hi:[1,0]
	s_nop 0
	v_pk_fma_f32 v[96:97], v[96:97], v[74:75], v[98:99] op_sel_hi:[1,0,1]
	s_nop 0
	v_pk_add_f32 v[98:99], v[96:97], 0 neg_lo:[1,1] neg_hi:[1,1]
	s_nop 0
	v_mov_b32_e32 v98, v97
	v_pk_mul_f32 v[98:99], v[136:137], v[98:99] op_sel:[1,0] op_sel_hi:[0,1]
	v_pk_fma_f32 v[98:99], v[136:137], v[96:97], v[98:99] op_sel_hi:[1,0,1]
	ds_write_b64 v94, v[98:99] offset:5120
	v_pk_mul_f32 v[94:95], v[78:79], v[96:97] op_sel:[0,1] op_sel_hi:[1,0]
	s_nop 0
	v_pk_fma_f32 v[94:95], v[96:97], v[74:75], v[94:95] op_sel_hi:[1,0,1]
	s_nop 0
	v_pk_add_f32 v[96:97], v[94:95], 0 neg_lo:[1,1] neg_hi:[1,1]
	s_nop 0
	v_mov_b32_e32 v96, v95
	v_pk_mul_f32 v[96:97], v[122:123], v[96:97] op_sel:[1,0] op_sel_hi:[0,1]
	v_pk_fma_f32 v[96:97], v[122:123], v[94:95], v[96:97] op_sel_hi:[1,0,1]
	ds_write_b64 v93, v[96:97] offset:5376
	v_pk_mul_f32 v[96:97], v[78:79], v[94:95] op_sel:[0,1] op_sel_hi:[1,0]
	s_nop 0
	v_pk_fma_f32 v[94:95], v[94:95], v[74:75], v[96:97] op_sel_hi:[1,0,1]
	s_nop 0
	v_pk_add_f32 v[96:97], v[94:95], 0 neg_lo:[1,1] neg_hi:[1,1]
	s_nop 0
	v_mov_b32_e32 v96, v95
	v_pk_mul_f32 v[96:97], v[138:139], v[96:97] op_sel:[1,0] op_sel_hi:[0,1]
	v_pk_fma_f32 v[96:97], v[138:139], v[94:95], v[96:97] op_sel_hi:[1,0,1]
	ds_write_b64 v92, v[96:97] offset:5632
	v_pk_mul_f32 v[92:93], v[78:79], v[94:95] op_sel:[0,1] op_sel_hi:[1,0]
	s_nop 0
	v_pk_fma_f32 v[92:93], v[94:95], v[74:75], v[92:93] op_sel_hi:[1,0,1]
	s_nop 0
	v_pk_add_f32 v[94:95], v[92:93], 0 neg_lo:[1,1] neg_hi:[1,1]
	s_nop 0
	v_mov_b32_e32 v94, v93
	v_pk_mul_f32 v[94:95], v[132:133], v[94:95] op_sel:[1,0] op_sel_hi:[0,1]
	v_pk_fma_f32 v[94:95], v[132:133], v[92:93], v[94:95] op_sel_hi:[1,0,1]
	ds_write_b64 v91, v[94:95] offset:5888
	v_pk_mul_f32 v[94:95], v[78:79], v[92:93] op_sel:[0,1] op_sel_hi:[1,0]
	s_nop 0
	v_pk_fma_f32 v[92:93], v[92:93], v[74:75], v[94:95] op_sel_hi:[1,0,1]
	s_nop 0
	v_pk_add_f32 v[94:95], v[92:93], 0 neg_lo:[1,1] neg_hi:[1,1]
	s_nop 0
	v_mov_b32_e32 v94, v93
	v_pk_mul_f32 v[94:95], v[82:83], v[94:95] op_sel:[1,0] op_sel_hi:[0,1]
	v_pk_fma_f32 v[82:83], v[82:83], v[92:93], v[94:95] op_sel_hi:[1,0,1]
	ds_write_b64 v90, v[82:83] offset:6144
	v_pk_mul_f32 v[82:83], v[78:79], v[92:93] op_sel:[0,1] op_sel_hi:[1,0]
	s_nop 0
	v_pk_fma_f32 v[82:83], v[92:93], v[74:75], v[82:83] op_sel_hi:[1,0,1]
	s_nop 0
	v_pk_add_f32 v[90:91], v[82:83], 0 neg_lo:[1,1] neg_hi:[1,1]
	s_nop 0
	v_mov_b32_e32 v90, v83
	v_pk_mul_f32 v[90:91], v[148:149], v[90:91] op_sel:[1,0] op_sel_hi:[0,1]
	v_pk_fma_f32 v[90:91], v[148:149], v[82:83], v[90:91] op_sel_hi:[1,0,1]
	ds_write_b64 v89, v[90:91] offset:6400
	v_pk_mul_f32 v[90:91], v[78:79], v[82:83] op_sel:[0,1] op_sel_hi:[1,0]
	s_nop 0
	v_pk_fma_f32 v[82:83], v[82:83], v[74:75], v[90:91] op_sel_hi:[1,0,1]
	s_nop 0
	v_pk_add_f32 v[90:91], v[82:83], 0 neg_lo:[1,1] neg_hi:[1,1]
	s_nop 0
	v_mov_b32_e32 v90, v83
	v_pk_mul_f32 v[90:91], v[76:77], v[90:91] op_sel:[1,0] op_sel_hi:[0,1]
	v_pk_fma_f32 v[76:77], v[76:77], v[82:83], v[90:91] op_sel_hi:[1,0,1]
	ds_write_b64 v88, v[76:77] offset:6656
	v_pk_mul_f32 v[76:77], v[78:79], v[82:83] op_sel:[0,1] op_sel_hi:[1,0]
	s_nop 0
	v_pk_fma_f32 v[76:77], v[82:83], v[74:75], v[76:77] op_sel_hi:[1,0,1]
	s_nop 0
	v_pk_add_f32 v[82:83], v[76:77], 0 neg_lo:[1,1] neg_hi:[1,1]
	s_nop 0
	v_mov_b32_e32 v82, v77
	v_pk_mul_f32 v[82:83], v[80:81], v[82:83] op_sel:[1,0] op_sel_hi:[0,1]
	v_pk_fma_f32 v[80:81], v[80:81], v[76:77], v[82:83] op_sel_hi:[1,0,1]
	ds_write_b64 v87, v[80:81] offset:6912
	v_pk_mul_f32 v[80:81], v[78:79], v[76:77] op_sel:[0,1] op_sel_hi:[1,0]
	s_nop 0
	v_pk_fma_f32 v[76:77], v[76:77], v[74:75], v[80:81] op_sel_hi:[1,0,1]
	s_nop 0
	v_pk_add_f32 v[80:81], v[76:77], 0 neg_lo:[1,1] neg_hi:[1,1]
	s_nop 0
	v_mov_b32_e32 v80, v77
	v_pk_mul_f32 v[80:81], v[68:69], v[80:81] op_sel:[1,0] op_sel_hi:[0,1]
	v_pk_fma_f32 v[68:69], v[68:69], v[76:77], v[80:81] op_sel_hi:[1,0,1]
	ds_write_b64 v86, v[68:69] offset:7168
	v_pk_mul_f32 v[68:69], v[78:79], v[76:77] op_sel:[0,1] op_sel_hi:[1,0]
	s_nop 0
	v_pk_fma_f32 v[68:69], v[76:77], v[74:75], v[68:69] op_sel_hi:[1,0,1]
	s_nop 0
	v_pk_add_f32 v[76:77], v[68:69], 0 neg_lo:[1,1] neg_hi:[1,1]
	s_nop 0
	v_mov_b32_e32 v76, v69
	v_pk_mul_f32 v[76:77], v[72:73], v[76:77] op_sel:[1,0] op_sel_hi:[0,1]
	v_pk_fma_f32 v[72:73], v[72:73], v[68:69], v[76:77] op_sel_hi:[1,0,1]
	ds_write_b64 v85, v[72:73] offset:7424
	v_pk_mul_f32 v[72:73], v[78:79], v[68:69] op_sel:[0,1] op_sel_hi:[1,0]
	s_nop 0
	v_pk_fma_f32 v[68:69], v[68:69], v[74:75], v[72:73] op_sel_hi:[1,0,1]
	s_nop 0
	v_pk_add_f32 v[72:73], v[68:69], 0 neg_lo:[1,1] neg_hi:[1,1]
	s_nop 0
	v_mov_b32_e32 v72, v69
	v_pk_mul_f32 v[72:73], v[66:67], v[72:73] op_sel:[1,0] op_sel_hi:[0,1]
	v_pk_fma_f32 v[66:67], v[66:67], v[68:69], v[72:73] op_sel_hi:[1,0,1]
	ds_write_b64 v84, v[66:67] offset:7680
	v_pk_mul_f32 v[66:67], v[78:79], v[68:69] op_sel:[0,1] op_sel_hi:[1,0]
	s_nop 0
	v_pk_fma_f32 v[66:67], v[68:69], v[74:75], v[66:67] op_sel_hi:[1,0,1]
	s_nop 0
	v_pk_add_f32 v[68:69], v[66:67], 0 neg_lo:[1,1] neg_hi:[1,1]
	s_nop 0
	v_mov_b32_e32 v68, v67
	v_pk_mul_f32 v[68:69], v[70:71], v[68:69] op_sel:[1,0] op_sel_hi:[0,1]
	v_pk_fma_f32 v[66:67], v[70:71], v[66:67], v[68:69] op_sel_hi:[1,0,1]
	ds_write_b64 v0, v[66:67]
	s_waitcnt lgkmcnt(0)
	s_barrier
	ds_read2_b64 v[66:69], v104 offset1:1
	ds_read2_b64 v[70:73], v104 offset0:2 offset1:3
	ds_read2_b64 v[74:77], v104 offset0:4 offset1:5
	ds_read2_b64 v[78:81], v104 offset0:6 offset1:7
	ds_read2_b64 v[82:85], v104 offset0:8 offset1:9
	ds_read2_b64 v[86:89], v104 offset0:10 offset1:11
	ds_read2_b64 v[90:93], v104 offset0:12 offset1:13
	ds_read2_b64 v[94:97], v104 offset0:14 offset1:15
	ds_read2_b64 v[98:101], v104 offset0:16 offset1:17
	ds_read2_b64 v[106:109], v104 offset0:18 offset1:19
	ds_read2_b64 v[110:113], v104 offset0:20 offset1:21
	ds_read2_b64 v[114:117], v104 offset0:22 offset1:23
	ds_read2_b64 v[118:121], v104 offset0:24 offset1:25
	ds_read2_b64 v[122:125], v104 offset0:26 offset1:27
	ds_read2_b64 v[126:129], v104 offset0:28 offset1:29
	ds_read2_b64 v[130:133], v104 offset0:30 offset1:31
	s_waitcnt lgkmcnt(7)
	v_pk_add_f32 v[102:103], v[66:67], v[98:99]
	v_pk_add_f32 v[66:67], v[66:67], v[98:99] neg_lo:[0,1] neg_hi:[0,1]
	v_pk_add_f32 v[98:99], v[68:69], v[100:101]
	v_pk_add_f32 v[68:69], v[68:69], v[100:101] neg_lo:[0,1] neg_hi:[0,1]
	global_load_dwordx2 v[134:135], v[2:3], off
	global_load_dwordx2 v[136:137], v[4:5], off
	global_load_dwordx2 v[138:139], v[6:7], off
	v_pk_mul_f32 v[100:101], v[68:69], s[18:19]
	global_load_dwordx2 v[148:149], v[14:15], off
	global_load_dwordx2 v[154:155], v[16:17], off
	v_pk_fma_f32 v[68:69], v[68:69], s[20:21], v[100:101] op_sel:[0,0,1] op_sel_hi:[1,0,0]
	s_waitcnt lgkmcnt(6)
	v_pk_add_f32 v[100:101], v[70:71], v[106:107]
	v_pk_add_f32 v[70:71], v[70:71], v[106:107] neg_lo:[0,1] neg_hi:[0,1]
	global_load_dwordx2 v[158:159], v[18:19], off
	v_pk_mul_f32 v[106:107], v[70:71], s[4:5]
	global_load_dwordx2 v[160:161], v[28:29], off
	global_load_dwordx2 v[164:165], v[32:33], off
	v_pk_fma_f32 v[70:71], v[70:71], s[6:7], v[106:107] op_sel:[0,0,1] op_sel_hi:[1,0,0]
	v_pk_add_f32 v[106:107], v[72:73], v[108:109]
	v_pk_add_f32 v[72:73], v[72:73], v[108:109] neg_lo:[0,1] neg_hi:[0,1]
	global_load_dwordx2 v[168:169], v[36:37], off
	v_pk_mul_f32 v[108:109], v[72:73], s[22:23]
	global_load_dwordx2 v[172:173], v[44:45], off
	v_pk_fma_f32 v[72:73], v[72:73], s[24:25], v[108:109] op_sel:[0,0,1] op_sel_hi:[1,0,0]
	s_waitcnt lgkmcnt(5)
	v_pk_add_f32 v[108:109], v[74:75], v[110:111]
	v_pk_add_f32 v[74:75], v[74:75], v[110:111] neg_lo:[0,1] neg_hi:[0,1]
	global_load_dwordx2 v[174:175], v[52:53], off
	v_pk_mul_f32 v[110:111], v[74:75], s[8:9]
	global_load_dwordx2 v[176:177], v[60:61], off
	v_pk_fma_f32 v[74:75], v[74:75], s[10:11], v[110:111] op_sel:[0,0,1] op_sel_hi:[1,0,0]
	v_pk_add_f32 v[110:111], v[76:77], v[112:113]
	v_pk_add_f32 v[76:77], v[76:77], v[112:113] neg_lo:[0,1] neg_hi:[0,1]
	s_nop 0
	v_pk_mul_f32 v[112:113], v[76:77], s[26:27]
	s_nop 0
	v_pk_fma_f32 v[76:77], v[76:77], s[0:1], v[112:113] op_sel:[0,0,1] op_sel_hi:[1,0,0]
	s_waitcnt lgkmcnt(4)
	v_pk_add_f32 v[112:113], v[78:79], v[114:115]
	v_pk_add_f32 v[78:79], v[78:79], v[114:115] neg_lo:[0,1] neg_hi:[0,1]
	s_nop 0
	v_pk_mul_f32 v[114:115], v[78:79], s[12:13]
	s_nop 0
	v_pk_fma_f32 v[78:79], v[78:79], s[14:15], v[114:115] op_sel:[0,0,1] op_sel_hi:[1,0,0]
	v_pk_add_f32 v[114:115], v[80:81], v[116:117]
	v_pk_add_f32 v[80:81], v[80:81], v[116:117] neg_lo:[0,1] neg_hi:[0,1]
	s_nop 0
	v_pk_mul_f32 v[116:117], v[80:81], s[34:35]
	s_nop 0
	v_pk_fma_f32 v[80:81], v[80:81], s[48:49], v[116:117] op_sel:[0,0,1] op_sel_hi:[1,0,0]
	s_waitcnt lgkmcnt(3)
	v_pk_add_f32 v[116:117], v[82:83], v[118:119]
	v_pk_add_f32 v[82:83], v[82:83], v[118:119] neg_lo:[0,1] neg_hi:[0,1]
	s_nop 0
	v_xor_b32_e32 v119, 0x80000000, v82
	v_mov_b32_e32 v118, v83
	v_pk_add_f32 v[82:83], v[84:85], v[120:121]
	v_pk_add_f32 v[84:85], v[84:85], v[120:121] neg_lo:[0,1] neg_hi:[0,1]
	s_nop 0
	v_pk_mul_f32 v[120:121], v[84:85], s[34:35]
	s_nop 0
	v_pk_fma_f32 v[84:85], v[84:85], s[18:19], v[120:121] op_sel:[0,0,1] op_sel_hi:[1,0,0]
	s_waitcnt lgkmcnt(2)
	v_pk_add_f32 v[120:121], v[86:87], v[122:123]
	v_pk_add_f32 v[86:87], v[86:87], v[122:123] neg_lo:[0,1] neg_hi:[0,1]
	s_nop 0
	v_pk_mul_f32 v[122:123], v[86:87], s[12:13]
	s_nop 0
	v_pk_fma_f32 v[86:87], v[86:87], s[4:5], v[122:123] op_sel:[0,0,1] op_sel_hi:[1,0,0]
	v_pk_add_f32 v[122:123], v[88:89], v[124:125]
	v_pk_add_f32 v[88:89], v[88:89], v[124:125] neg_lo:[0,1] neg_hi:[0,1]
	s_nop 0
	v_pk_mul_f32 v[124:125], v[88:89], s[26:27]
	s_nop 0
	v_pk_fma_f32 v[88:89], v[88:89], s[22:23], v[124:125] op_sel:[0,0,1] op_sel_hi:[1,0,0]
	s_waitcnt lgkmcnt(1)
	v_pk_add_f32 v[124:125], v[90:91], v[126:127]
	v_pk_add_f32 v[90:91], v[90:91], v[126:127] neg_lo:[0,1] neg_hi:[0,1]
	s_nop 0
	v_pk_mul_f32 v[126:127], v[90:91], s[8:9]
	s_nop 0
	v_pk_fma_f32 v[90:91], v[90:91], s[8:9], v[126:127] op_sel:[0,0,1] op_sel_hi:[1,0,0]
	v_pk_add_f32 v[126:127], v[92:93], v[128:129]
	v_pk_add_f32 v[92:93], v[92:93], v[128:129] neg_lo:[0,1] neg_hi:[0,1]
	s_nop 0
	v_pk_mul_f32 v[128:129], v[92:93], s[22:23]
	s_nop 0
	v_pk_fma_f32 v[92:93], v[92:93], s[26:27], v[128:129] op_sel:[0,0,1] op_sel_hi:[1,0,0]
	s_waitcnt lgkmcnt(0)
	v_pk_add_f32 v[128:129], v[94:95], v[130:131]
	v_pk_add_f32 v[94:95], v[94:95], v[130:131] neg_lo:[0,1] neg_hi:[0,1]
	s_nop 0
	v_pk_mul_f32 v[130:131], v[94:95], s[4:5]
	s_nop 0
	v_pk_fma_f32 v[94:95], v[94:95], s[12:13], v[130:131] op_sel:[0,0,1] op_sel_hi:[1,0,0]
	v_pk_add_f32 v[130:131], v[96:97], v[132:133]
	v_pk_add_f32 v[96:97], v[96:97], v[132:133] neg_lo:[0,1] neg_hi:[0,1]
	s_nop 0
	v_pk_mul_f32 v[132:133], v[96:97], s[18:19]
	s_nop 0
	v_pk_fma_f32 v[96:97], v[96:97], s[34:35], v[132:133] op_sel:[0,0,1] op_sel_hi:[1,0,0]
	v_pk_add_f32 v[132:133], v[102:103], v[116:117]
	v_pk_add_f32 v[102:103], v[102:103], v[116:117] neg_lo:[0,1] neg_hi:[0,1]
	v_pk_add_f32 v[116:117], v[98:99], v[82:83]
	v_pk_add_f32 v[82:83], v[98:99], v[82:83] neg_lo:[0,1] neg_hi:[0,1]
	s_nop 0
	v_pk_mul_f32 v[98:99], v[82:83], s[4:5]
	s_nop 0
	v_pk_fma_f32 v[82:83], v[82:83], s[6:7], v[98:99] op_sel:[0,0,1] op_sel_hi:[1,0,0]
	v_pk_add_f32 v[98:99], v[100:101], v[120:121]
	v_pk_add_f32 v[100:101], v[100:101], v[120:121] neg_lo:[0,1] neg_hi:[0,1]
	s_nop 0
	v_pk_mul_f32 v[120:121], v[100:101], s[8:9]
	s_nop 0
	v_pk_fma_f32 v[100:101], v[100:101], s[10:11], v[120:121] op_sel:[0,0,1] op_sel_hi:[1,0,0]
	v_pk_add_f32 v[120:121], v[106:107], v[122:123]
	v_pk_add_f32 v[106:107], v[106:107], v[122:123] neg_lo:[0,1] neg_hi:[0,1]
	s_nop 0
	v_pk_mul_f32 v[122:123], v[106:107], s[12:13]
	s_nop 0
	v_pk_fma_f32 v[106:107], v[106:107], s[14:15], v[122:123] op_sel:[0,0,1] op_sel_hi:[1,0,0]
	v_pk_add_f32 v[122:123], v[108:109], v[124:125]
	v_pk_add_f32 v[108:109], v[108:109], v[124:125] neg_lo:[0,1] neg_hi:[0,1]
	s_nop 0
	v_xor_b32_e32 v125, 0x80000000, v108
	v_mov_b32_e32 v124, v109
	v_pk_add_f32 v[108:109], v[110:111], v[126:127]
	v_pk_add_f32 v[110:111], v[110:111], v[126:127] neg_lo:[0,1] neg_hi:[0,1]
	s_nop 0
	v_pk_mul_f32 v[126:127], v[110:111], s[12:13]
	s_nop 0
	v_pk_fma_f32 v[110:111], v[110:111], s[4:5], v[126:127] op_sel:[0,0,1] op_sel_hi:[1,0,0]
	v_pk_add_f32 v[126:127], v[112:113], v[128:129]
	v_pk_add_f32 v[112:113], v[112:113], v[128:129] neg_lo:[0,1] neg_hi:[0,1]
	s_nop 0
	v_pk_mul_f32 v[128:129], v[112:113], s[8:9]
	s_nop 0
	v_pk_fma_f32 v[112:113], v[112:113], s[8:9], v[128:129] op_sel:[0,0,1] op_sel_hi:[1,0,0]
	v_pk_add_f32 v[128:129], v[114:115], v[130:131]
	v_pk_add_f32 v[114:115], v[114:115], v[130:131] neg_lo:[0,1] neg_hi:[0,1]
	s_nop 0
	v_pk_mul_f32 v[130:131], v[114:115], s[4:5]
	s_nop 0
	v_pk_fma_f32 v[114:115], v[114:115], s[12:13], v[130:131] op_sel:[0,0,1] op_sel_hi:[1,0,0]
	v_pk_add_f32 v[130:131], v[66:67], v[118:119]
	v_pk_add_f32 v[66:67], v[66:67], v[118:119] neg_lo:[0,1] neg_hi:[0,1]
	v_pk_add_f32 v[118:119], v[68:69], v[84:85]
	v_pk_add_f32 v[68:69], v[68:69], v[84:85] neg_lo:[0,1] neg_hi:[0,1]
	s_nop 0
	v_pk_mul_f32 v[84:85], v[68:69], s[4:5]
	s_nop 0
	v_pk_fma_f32 v[68:69], v[68:69], s[6:7], v[84:85] op_sel:[0,0,1] op_sel_hi:[1,0,0]
	v_pk_add_f32 v[84:85], v[70:71], v[86:87]
	v_pk_add_f32 v[70:71], v[70:71], v[86:87] neg_lo:[0,1] neg_hi:[0,1]
	s_nop 0
	v_pk_mul_f32 v[86:87], v[70:71], s[8:9]
	s_nop 0
	v_pk_fma_f32 v[70:71], v[70:71], s[10:11], v[86:87] op_sel:[0,0,1] op_sel_hi:[1,0,0]
	v_pk_add_f32 v[86:87], v[72:73], v[88:89]
	v_pk_add_f32 v[72:73], v[72:73], v[88:89] neg_lo:[0,1] neg_hi:[0,1]
	s_nop 0
	v_pk_mul_f32 v[88:89], v[72:73], s[12:13]
	s_nop 0
	v_pk_fma_f32 v[72:73], v[72:73], s[14:15], v[88:89] op_sel:[0,0,1] op_sel_hi:[1,0,0]
	v_pk_add_f32 v[88:89], v[74:75], v[90:91]
	v_pk_add_f32 v[74:75], v[74:75], v[90:91] neg_lo:[0,1] neg_hi:[0,1]
	s_mov_b32 s15, s4
	v_xor_b32_e32 v91, 0x80000000, v74
	v_mov_b32_e32 v90, v75
	v_pk_add_f32 v[74:75], v[76:77], v[92:93]
	v_pk_add_f32 v[76:77], v[76:77], v[92:93] neg_lo:[0,1] neg_hi:[0,1]
	s_nop 0
	v_pk_mul_f32 v[92:93], v[76:77], s[12:13]
	s_nop 0
	v_pk_fma_f32 v[76:77], v[76:77], s[4:5], v[92:93] op_sel:[0,0,1] op_sel_hi:[1,0,0]
	v_pk_add_f32 v[92:93], v[78:79], v[94:95]
	v_pk_add_f32 v[78:79], v[78:79], v[94:95] neg_lo:[0,1] neg_hi:[0,1]
	s_nop 0
	v_pk_mul_f32 v[94:95], v[78:79], s[8:9]
	s_nop 0
	v_pk_fma_f32 v[78:79], v[78:79], s[8:9], v[94:95] op_sel:[0,0,1] op_sel_hi:[1,0,0]
	v_pk_add_f32 v[94:95], v[80:81], v[96:97]
	v_pk_add_f32 v[80:81], v[80:81], v[96:97] neg_lo:[0,1] neg_hi:[0,1]
	s_nop 0
	v_pk_mul_f32 v[96:97], v[80:81], s[4:5]
	s_nop 0
	v_pk_fma_f32 v[80:81], v[80:81], s[12:13], v[96:97] op_sel:[0,0,1] op_sel_hi:[1,0,0]
	v_pk_add_f32 v[96:97], v[132:133], v[122:123]
	v_pk_add_f32 v[122:123], v[132:133], v[122:123] neg_lo:[0,1] neg_hi:[0,1]
	v_pk_add_f32 v[132:133], v[116:117], v[108:109]
	v_pk_add_f32 v[108:109], v[116:117], v[108:109] neg_lo:[0,1] neg_hi:[0,1]
	s_nop 0
	v_pk_mul_f32 v[116:117], v[108:109], s[8:9]
	s_nop 0
	v_pk_fma_f32 v[108:109], v[108:109], s[10:11], v[116:117] op_sel:[0,0,1] op_sel_hi:[1,0,0]
	v_pk_add_f32 v[116:117], v[98:99], v[126:127]
	v_pk_add_f32 v[98:99], v[98:99], v[126:127] neg_lo:[0,1] neg_hi:[0,1]
	s_nop 0
	v_xor_b32_e32 v127, 0x80000000, v98
	v_mov_b32_e32 v126, v99
	v_pk_add_f32 v[98:99], v[120:121], v[128:129]
	v_pk_add_f32 v[120:121], v[120:121], v[128:129] neg_lo:[0,1] neg_hi:[0,1]
	s_nop 0
	v_pk_mul_f32 v[128:129], v[120:121], s[8:9]
	s_nop 0
	v_pk_fma_f32 v[120:121], v[120:121], s[8:9], v[128:129] op_sel:[0,0,1] op_sel_hi:[1,0,0]
	v_pk_add_f32 v[128:129], v[102:103], v[124:125]
	v_pk_add_f32 v[102:103], v[102:103], v[124:125] neg_lo:[0,1] neg_hi:[0,1]
	v_pk_add_f32 v[124:125], v[82:83], v[110:111]
	v_pk_add_f32 v[82:83], v[82:83], v[110:111] neg_lo:[0,1] neg_hi:[0,1]
	s_nop 0
	v_pk_mul_f32 v[110:111], v[82:83], s[8:9]
	s_nop 0
	v_pk_fma_f32 v[82:83], v[82:83], s[10:11], v[110:111] op_sel:[0,0,1] op_sel_hi:[1,0,0]
	v_pk_add_f32 v[110:111], v[100:101], v[112:113]
	v_pk_add_f32 v[100:101], v[100:101], v[112:113] neg_lo:[0,1] neg_hi:[0,1]
	s_nop 0
	v_xor_b32_e32 v113, 0x80000000, v100
	v_mov_b32_e32 v112, v101
	v_pk_add_f32 v[100:101], v[106:107], v[114:115]
	v_pk_add_f32 v[106:107], v[106:107], v[114:115] neg_lo:[0,1] neg_hi:[0,1]
	s_nop 0
	v_pk_mul_f32 v[114:115], v[106:107], s[8:9]
	s_nop 0
	v_pk_fma_f32 v[106:107], v[106:107], s[8:9], v[114:115] op_sel:[0,0,1] op_sel_hi:[1,0,0]
	v_pk_add_f32 v[114:115], v[130:131], v[88:89]
	v_pk_add_f32 v[88:89], v[130:131], v[88:89] neg_lo:[0,1] neg_hi:[0,1]
	v_pk_add_f32 v[130:131], v[118:119], v[74:75]
	v_pk_add_f32 v[74:75], v[118:119], v[74:75] neg_lo:[0,1] neg_hi:[0,1]
	s_nop 0
	v_pk_mul_f32 v[118:119], v[74:75], s[8:9]
	s_nop 0
	v_pk_fma_f32 v[74:75], v[74:75], s[10:11], v[118:119] op_sel:[0,0,1] op_sel_hi:[1,0,0]
	v_pk_add_f32 v[118:119], v[84:85], v[92:93]
	v_pk_add_f32 v[84:85], v[84:85], v[92:93] neg_lo:[0,1] neg_hi:[0,1]
	s_nop 0
	v_xor_b32_e32 v93, 0x80000000, v84
	v_mov_b32_e32 v92, v85
	v_pk_add_f32 v[84:85], v[86:87], v[94:95]
	v_pk_add_f32 v[86:87], v[86:87], v[94:95] neg_lo:[0,1] neg_hi:[0,1]
	v_pk_add_f32 v[140:141], v[88:89], v[92:93]
	v_pk_mul_f32 v[94:95], v[86:87], s[8:9]
	v_pk_add_f32 v[88:89], v[88:89], v[92:93] neg_lo:[0,1] neg_hi:[0,1]
	v_pk_fma_f32 v[86:87], v[86:87], s[8:9], v[94:95] op_sel:[0,0,1] op_sel_hi:[1,0,0]
	v_pk_add_f32 v[94:95], v[66:67], v[90:91]
	v_pk_add_f32 v[66:67], v[66:67], v[90:91] neg_lo:[0,1] neg_hi:[0,1]
	v_pk_add_f32 v[90:91], v[68:69], v[76:77]
	v_pk_add_f32 v[68:69], v[68:69], v[76:77] neg_lo:[0,1] neg_hi:[0,1]
	v_pk_add_f32 v[92:93], v[74:75], v[86:87]
	v_pk_mul_f32 v[76:77], v[68:69], s[8:9]
	v_pk_add_f32 v[74:75], v[74:75], v[86:87] neg_lo:[0,1] neg_hi:[0,1]
	v_pk_fma_f32 v[68:69], v[68:69], s[10:11], v[76:77] op_sel:[0,0,1] op_sel_hi:[1,0,0]
	v_pk_add_f32 v[76:77], v[70:71], v[78:79]
	v_pk_add_f32 v[70:71], v[70:71], v[78:79] neg_lo:[0,1] neg_hi:[0,1]
	global_load_dwordx2 v[86:87], v[10:11], off
	v_xor_b32_e32 v79, 0x80000000, v70
	v_mov_b32_e32 v78, v71
	v_pk_add_f32 v[70:71], v[72:73], v[80:81]
	v_pk_add_f32 v[72:73], v[72:73], v[80:81] neg_lo:[0,1] neg_hi:[0,1]
	v_xor_b32_e32 v143, 0x80000000, v74
	v_pk_mul_f32 v[80:81], v[72:73], s[8:9]
	v_mov_b32_e32 v142, v75
	v_pk_fma_f32 v[72:73], v[72:73], s[8:9], v[80:81] op_sel:[0,0,1] op_sel_hi:[1,0,0]
	v_pk_add_f32 v[80:81], v[96:97], v[116:117]
	v_pk_add_f32 v[96:97], v[96:97], v[116:117] neg_lo:[0,1] neg_hi:[0,1]
	v_pk_add_f32 v[116:117], v[132:133], v[98:99]
	v_pk_add_f32 v[98:99], v[132:133], v[98:99] neg_lo:[0,1] neg_hi:[0,1]
	v_pk_add_f32 v[74:75], v[94:95], v[76:77]
	v_xor_b32_e32 v133, 0x80000000, v98
	v_mov_b32_e32 v132, v99
	v_pk_add_f32 v[98:99], v[122:123], v[126:127]
	v_pk_add_f32 v[122:123], v[122:123], v[126:127] neg_lo:[0,1] neg_hi:[0,1]
	v_pk_add_f32 v[126:127], v[108:109], v[120:121]
	v_pk_add_f32 v[108:109], v[108:109], v[120:121] neg_lo:[0,1] neg_hi:[0,1]
	v_pk_add_f32 v[76:77], v[94:95], v[76:77] neg_lo:[0,1] neg_hi:[0,1]
	v_xor_b32_e32 v121, 0x80000000, v108
	v_mov_b32_e32 v120, v109
	v_pk_add_f32 v[108:109], v[128:129], v[110:111]
	v_pk_add_f32 v[110:111], v[128:129], v[110:111] neg_lo:[0,1] neg_hi:[0,1]
	v_pk_add_f32 v[128:129], v[124:125], v[100:101]
	v_pk_add_f32 v[100:101], v[124:125], v[100:101] neg_lo:[0,1] neg_hi:[0,1]
	global_load_dwordx2 v[94:95], v[12:13], off
	v_xor_b32_e32 v125, 0x80000000, v100
	v_mov_b32_e32 v124, v101
	v_pk_add_f32 v[100:101], v[102:103], v[112:113]
	v_pk_add_f32 v[102:103], v[102:103], v[112:113] neg_lo:[0,1] neg_hi:[0,1]
	v_pk_add_f32 v[112:113], v[82:83], v[106:107]
	v_pk_add_f32 v[82:83], v[82:83], v[106:107] neg_lo:[0,1] neg_hi:[0,1]
	v_pk_add_f32 v[146:147], v[66:67], v[78:79]
	v_xor_b32_e32 v107, 0x80000000, v82
	v_mov_b32_e32 v106, v83
	v_pk_add_f32 v[82:83], v[114:115], v[118:119]
	v_pk_add_f32 v[114:115], v[114:115], v[118:119] neg_lo:[0,1] neg_hi:[0,1]
	v_pk_add_f32 v[118:119], v[130:131], v[84:85]
	v_pk_add_f32 v[84:85], v[130:131], v[84:85] neg_lo:[0,1] neg_hi:[0,1]
	v_pk_add_f32 v[78:79], v[66:67], v[78:79] neg_lo:[0,1] neg_hi:[0,1]
	v_xor_b32_e32 v131, 0x80000000, v84
	v_mov_b32_e32 v130, v85
	global_load_dwordx2 v[84:85], v[8:9], off
	v_pk_add_f32 v[66:67], v[68:69], v[72:73] neg_lo:[0,1] neg_hi:[0,1]
	v_pk_add_f32 v[150:151], v[68:69], v[72:73]
	v_xor_b32_e32 v153, 0x80000000, v66
	v_mov_b32_e32 v152, v67
	v_pk_add_f32 v[156:157], v[80:81], v[116:117]
	v_pk_add_f32 v[80:81], v[80:81], v[116:117] neg_lo:[0,1] neg_hi:[0,1]
	v_pk_add_f32 v[116:117], v[96:97], v[132:133]
	v_pk_add_f32 v[68:69], v[96:97], v[132:133] neg_lo:[0,1] neg_hi:[0,1]
	v_pk_add_f32 v[96:97], v[98:99], v[126:127]
	v_pk_add_f32 v[98:99], v[98:99], v[126:127] neg_lo:[0,1] neg_hi:[0,1]
	v_pk_add_f32 v[126:127], v[122:123], v[120:121]
	v_pk_add_f32 v[66:67], v[122:123], v[120:121] neg_lo:[0,1] neg_hi:[0,1]
	global_load_dwordx2 v[120:121], v[20:21], off
	v_pk_add_f32 v[122:123], v[108:109], v[128:129]
	v_pk_add_f32 v[108:109], v[108:109], v[128:129] neg_lo:[0,1] neg_hi:[0,1]
	v_pk_add_f32 v[128:129], v[110:111], v[124:125]
	v_pk_add_f32 v[72:73], v[110:111], v[124:125] neg_lo:[0,1] neg_hi:[0,1]
	global_load_dwordx2 v[110:111], v[22:23], off
	v_pk_add_f32 v[144:145], v[90:91], v[70:71]
	v_pk_add_f32 v[70:71], v[90:91], v[70:71] neg_lo:[0,1] neg_hi:[0,1]
	v_pk_add_f32 v[124:125], v[100:101], v[112:113]
	v_xor_b32_e32 v91, 0x80000000, v70
	v_mov_b32_e32 v90, v71
	v_pk_add_f32 v[100:101], v[100:101], v[112:113] neg_lo:[0,1] neg_hi:[0,1]
	v_pk_add_f32 v[112:113], v[102:103], v[106:107]
	v_pk_add_f32 v[70:71], v[102:103], v[106:107] neg_lo:[0,1] neg_hi:[0,1]
	global_load_dwordx2 v[102:103], v[24:25], off
	v_pk_add_f32 v[106:107], v[82:83], v[118:119]
	v_pk_add_f32 v[82:83], v[82:83], v[118:119] neg_lo:[0,1] neg_hi:[0,1]
	v_pk_add_f32 v[118:119], v[114:115], v[130:131]
	v_pk_add_f32 v[114:115], v[114:115], v[130:131] neg_lo:[0,1] neg_hi:[0,1]
	global_load_dwordx2 v[130:131], v[26:27], off
	v_pk_add_f32 v[162:163], v[76:77], v[90:91]
	v_pk_add_f32 v[76:77], v[76:77], v[90:91] neg_lo:[0,1] neg_hi:[0,1]
	v_pk_add_f32 v[90:91], v[146:147], v[150:151]
	v_pk_add_f32 v[146:147], v[146:147], v[150:151] neg_lo:[0,1] neg_hi:[0,1]
	v_pk_add_f32 v[150:151], v[78:79], v[152:153]
	v_pk_add_f32 v[78:79], v[78:79], v[152:153] neg_lo:[0,1] neg_hi:[0,1]
	global_load_dwordx2 v[152:153], v[34:35], off
	s_waitcnt vmcnt(19)
	v_xor_b32_e32 v166, 0x80000000, v135
	v_mov_b32_e32 v167, v135
	v_pk_mul_f32 v[166:167], v[166:167], v[156:157] op_sel:[0,1] op_sel_hi:[1,0]
	v_pk_add_f32 v[132:133], v[140:141], v[92:93]
	v_pk_fma_f32 v[134:135], v[156:157], v[134:135], v[166:167] op_sel_hi:[1,0,1]
	s_waitcnt vmcnt(18)
	v_xor_b32_e32 v156, 0x80000000, v137
	v_mov_b32_e32 v157, v137
	global_load_dwordx2 v[166:167], v[38:39], off
	v_pk_mul_f32 v[156:157], v[156:157], v[106:107] op_sel:[0,1] op_sel_hi:[1,0]
	v_pk_add_f32 v[92:93], v[140:141], v[92:93] neg_lo:[0,1] neg_hi:[0,1]
	v_pk_fma_f32 v[106:107], v[106:107], v[136:137], v[156:157] op_sel_hi:[1,0,1]
	s_waitcnt vmcnt(18)
	v_xor_b32_e32 v136, 0x80000000, v139
	global_load_dwordx2 v[156:157], v[40:41], off
	v_mov_b32_e32 v137, v139
	v_pk_mul_f32 v[136:137], v[136:137], v[122:123] op_sel:[0,1] op_sel_hi:[1,0]
	v_pk_add_f32 v[140:141], v[88:89], v[142:143]
	v_pk_fma_f32 v[122:123], v[122:123], v[138:139], v[136:137] op_sel_hi:[1,0,1]
	global_load_dwordx2 v[136:137], v[42:43], off
	v_pk_add_f32 v[88:89], v[88:89], v[142:143] neg_lo:[0,1] neg_hi:[0,1]
	v_pk_add_f32 v[142:143], v[74:75], v[144:145]
	v_pk_add_f32 v[74:75], v[74:75], v[144:145] neg_lo:[0,1] neg_hi:[0,1]
	global_load_dwordx2 v[144:145], v[30:31], off
	s_mov_b32 s11, s8
	s_waitcnt vmcnt(9)
	v_xor_b32_e32 v138, 0x80000000, v85
	v_mov_b32_e32 v139, v85
	v_pk_mul_f32 v[138:139], v[138:139], v[142:143] op_sel:[0,1] op_sel_hi:[1,0]
	s_nop 0
	v_pk_fma_f32 v[84:85], v[142:143], v[84:85], v[138:139] op_sel_hi:[1,0,1]
	v_xor_b32_e32 v138, 0x80000000, v87
	v_mov_b32_e32 v139, v87
	global_load_dwordx2 v[142:143], v[46:47], off
	v_pk_mul_f32 v[138:139], v[138:139], v[96:97] op_sel:[0,1] op_sel_hi:[1,0]
	s_nop 0
	v_pk_fma_f32 v[86:87], v[96:97], v[86:87], v[138:139] op_sel_hi:[1,0,1]
	v_xor_b32_e32 v96, 0x80000000, v95
	global_load_dwordx2 v[138:139], v[48:49], off
	v_mov_b32_e32 v97, v95
	v_pk_mul_f32 v[96:97], v[96:97], v[132:133] op_sel:[0,1] op_sel_hi:[1,0]
	s_nop 0
	v_pk_fma_f32 v[94:95], v[132:133], v[94:95], v[96:97] op_sel_hi:[1,0,1]
	global_load_dwordx2 v[96:97], v[50:51], off
	v_xor_b32_e32 v132, 0x80000000, v149
	v_mov_b32_e32 v133, v149
	v_pk_mul_f32 v[132:133], v[132:133], v[124:125] op_sel:[0,1] op_sel_hi:[1,0]
	s_nop 0
	v_pk_fma_f32 v[124:125], v[124:125], v[148:149], v[132:133] op_sel_hi:[1,0,1]
	v_xor_b32_e32 v132, 0x80000000, v155
	v_mov_b32_e32 v133, v155
	global_load_dwordx2 v[148:149], v[54:55], off
	v_pk_mul_f32 v[132:133], v[132:133], v[90:91] op_sel:[0,1] op_sel_hi:[1,0]
	s_nop 0
	v_pk_fma_f32 v[90:91], v[90:91], v[154:155], v[132:133] op_sel_hi:[1,0,1]
	v_xor_b32_e32 v132, 0x80000000, v159
	global_load_dwordx2 v[154:155], v[56:57], off
	v_mov_b32_e32 v133, v159
	v_pk_mul_f32 v[132:133], v[116:117], v[132:133] op_sel:[1,0] op_sel_hi:[0,1]
	v_pk_fma_f32 v[116:117], v[116:117], v[158:159], v[132:133] op_sel_hi:[1,0,1]
	global_load_dwordx2 v[132:133], v[58:59], off
	s_waitcnt vmcnt(14)
	v_xor_b32_e32 v158, 0x80000000, v121
	v_mov_b32_e32 v159, v121
	v_pk_mul_f32 v[158:159], v[118:119], v[158:159] op_sel:[1,0] op_sel_hi:[0,1]
	v_pk_fma_f32 v[118:119], v[118:119], v[120:121], v[158:159] op_sel_hi:[1,0,1]
	s_waitcnt vmcnt(13)
	v_xor_b32_e32 v120, 0x80000000, v111
	v_mov_b32_e32 v121, v111
	global_load_dwordx2 v[158:159], v[62:63], off
	v_pk_mul_f32 v[120:121], v[128:129], v[120:121] op_sel:[1,0] op_sel_hi:[0,1]
	v_pk_fma_f32 v[110:111], v[128:129], v[110:111], v[120:121] op_sel_hi:[1,0,1]
	global_load_dwordx2 v[128:129], v[64:65], off
	s_waitcnt vmcnt(14)
	v_xor_b32_e32 v120, 0x80000000, v103
	v_mov_b32_e32 v121, v103
	v_pk_mul_f32 v[120:121], v[120:121], v[162:163] op_sel:[0,1] op_sel_hi:[1,0]
	v_mov_b32 v0, 0
	s_nop 0
	v_pk_fma_f32 v[102:103], v[162:163], v[102:103], v[120:121] op_sel_hi:[1,0,1]
	s_waitcnt vmcnt(13)
	v_xor_b32_e32 v120, 0x80000000, v131
	v_mov_b32_e32 v121, v131
	v_pk_mul_f32 v[120:121], v[126:127], v[120:121] op_sel:[1,0] op_sel_hi:[0,1]
	v_pk_fma_f32 v[120:121], v[126:127], v[130:131], v[120:121] op_sel_hi:[1,0,1]
	v_xor_b32_e32 v126, 0x80000000, v161
	v_mov_b32_e32 v127, v161
	v_pk_mul_f32 v[126:127], v[140:141], v[126:127] op_sel:[1,0] op_sel_hi:[0,1]
	v_pk_fma_f32 v[126:127], v[140:141], v[160:161], v[126:127] op_sel_hi:[1,0,1]
	s_waitcnt vmcnt(12)
	v_xor_b32_e32 v140, 0x80000000, v153
	v_mov_b32_e32 v141, v153
	v_pk_mul_f32 v[140:141], v[80:81], v[140:141] op_sel:[1,0] op_sel_hi:[0,1]
	v_pk_fma_f32 v[80:81], v[80:81], v[152:153], v[140:141] op_sel_hi:[1,0,1]
	v_xor_b32_e32 v140, 0x80000000, v169
	v_mov_b32_e32 v141, v169
	v_pk_mul_f32 v[140:141], v[82:83], v[140:141] op_sel:[1,0] op_sel_hi:[0,1]
	v_pk_fma_f32 v[82:83], v[82:83], v[168:169], v[140:141] op_sel_hi:[1,0,1]
	s_waitcnt vmcnt(11)
	v_xor_b32_e32 v140, 0x80000000, v167
	v_mov_b32_e32 v141, v167
	v_pk_mul_f32 v[140:141], v[108:109], v[140:141] op_sel:[1,0] op_sel_hi:[0,1]
	v_pk_fma_f32 v[108:109], v[108:109], v[166:167], v[140:141] op_sel_hi:[1,0,1]
	s_waitcnt vmcnt(10)
	v_xor_b32_e32 v140, 0x80000000, v157
	v_mov_b32_e32 v141, v157
	v_pk_mul_f32 v[140:141], v[74:75], v[140:141] op_sel:[1,0] op_sel_hi:[0,1]
	v_pk_fma_f32 v[74:75], v[74:75], v[156:157], v[140:141] op_sel_hi:[1,0,1]
	s_waitcnt vmcnt(9)
	v_xor_b32_e32 v140, 0x80000000, v137
	v_mov_b32_e32 v141, v137
	v_pk_mul_f32 v[140:141], v[98:99], v[140:141] op_sel:[1,0] op_sel_hi:[0,1]
	v_pk_fma_f32 v[98:99], v[98:99], v[136:137], v[140:141] op_sel_hi:[1,0,1]
	v_xor_b32_e32 v136, 0x80000000, v173
	v_mov_b32_e32 v137, v173
	v_pk_mul_f32 v[136:137], v[92:93], v[136:137] op_sel:[1,0] op_sel_hi:[0,1]
	v_pk_fma_f32 v[92:93], v[92:93], v[172:173], v[136:137] op_sel_hi:[1,0,1]
	s_waitcnt vmcnt(8)
	v_xor_b32_e32 v130, 0x80000000, v145
	v_mov_b32_e32 v131, v145
	v_pk_mul_f32 v[130:131], v[112:113], v[130:131] op_sel:[1,0] op_sel_hi:[0,1]
	v_pk_fma_f32 v[112:113], v[112:113], v[144:145], v[130:131] op_sel_hi:[1,0,1]
	s_waitcnt vmcnt(7)
	v_xor_b32_e32 v136, 0x80000000, v143
	v_mov_b32_e32 v137, v143
	v_pk_mul_f32 v[136:137], v[100:101], v[136:137] op_sel:[1,0] op_sel_hi:[0,1]
	v_pk_fma_f32 v[100:101], v[100:101], v[142:143], v[136:137] op_sel_hi:[1,0,1]
	v_xor_b32_e32 v130, 0x80000000, v165
	s_waitcnt vmcnt(6)
	v_xor_b32_e32 v136, 0x80000000, v139
	v_mov_b32_e32 v137, v139
	v_pk_mul_f32 v[136:137], v[146:147], v[136:137] op_sel:[1,0] op_sel_hi:[0,1]
	v_pk_fma_f32 v[136:137], v[146:147], v[138:139], v[136:137] op_sel_hi:[1,0,1]
	v_mov_b32_e32 v131, v165
	s_waitcnt vmcnt(5)
	v_xor_b32_e32 v138, 0x80000000, v97
	v_mov_b32_e32 v139, v97
	v_pk_mul_f32 v[138:139], v[68:69], v[138:139] op_sel:[1,0] op_sel_hi:[0,1]
	v_pk_fma_f32 v[68:69], v[68:69], v[96:97], v[138:139] op_sel_hi:[1,0,1]
	v_xor_b32_e32 v96, 0x80000000, v175
	v_mov_b32_e32 v97, v175
	v_pk_mul_f32 v[96:97], v[114:115], v[96:97] op_sel:[1,0] op_sel_hi:[0,1]
	v_pk_fma_f32 v[96:97], v[114:115], v[174:175], v[96:97] op_sel_hi:[1,0,1]
	s_waitcnt vmcnt(4)
	v_xor_b32_e32 v114, 0x80000000, v149
	v_mov_b32_e32 v115, v149
	v_pk_mul_f32 v[114:115], v[72:73], v[114:115] op_sel:[1,0] op_sel_hi:[0,1]
	v_pk_fma_f32 v[72:73], v[72:73], v[148:149], v[114:115] op_sel_hi:[1,0,1]
	v_pk_mul_f32 v[130:131], v[150:151], v[130:131] op_sel:[1,0] op_sel_hi:[0,1]
	s_waitcnt vmcnt(3)
	v_xor_b32_e32 v114, 0x80000000, v155
	v_mov_b32_e32 v115, v155
	v_pk_mul_f32 v[114:115], v[76:77], v[114:115] op_sel:[1,0] op_sel_hi:[0,1]
	v_pk_fma_f32 v[76:77], v[76:77], v[154:155], v[114:115] op_sel_hi:[1,0,1]
	s_waitcnt vmcnt(2)
	v_xor_b32_e32 v114, 0x80000000, v133
	v_mov_b32_e32 v115, v133
	v_pk_mul_f32 v[114:115], v[66:67], v[114:115] op_sel:[1,0] op_sel_hi:[0,1]
	v_pk_fma_f32 v[66:67], v[66:67], v[132:133], v[114:115] op_sel_hi:[1,0,1]
	v_xor_b32_e32 v114, 0x80000000, v177
	v_mov_b32_e32 v115, v177
	v_pk_mul_f32 v[114:115], v[88:89], v[114:115] op_sel:[1,0] op_sel_hi:[0,1]
	v_pk_fma_f32 v[88:89], v[88:89], v[176:177], v[114:115] op_sel_hi:[1,0,1]
	s_waitcnt vmcnt(1)
	v_xor_b32_e32 v114, 0x80000000, v159
	v_mov_b32_e32 v115, v159
	v_pk_mul_f32 v[114:115], v[70:71], v[114:115] op_sel:[1,0] op_sel_hi:[0,1]
	v_pk_fma_f32 v[70:71], v[70:71], v[158:159], v[114:115] op_sel_hi:[1,0,1]
	s_waitcnt vmcnt(0)
	v_xor_b32_e32 v114, 0x80000000, v129
	v_mov_b32_e32 v115, v129
	v_pk_mul_f32 v[114:115], v[78:79], v[114:115] op_sel:[1,0] op_sel_hi:[0,1]
	v_pk_fma_f32 v[78:79], v[78:79], v[128:129], v[114:115] op_sel_hi:[1,0,1]
	v_pk_add_f32 v[128:129], v[106:107], v[82:83]
	v_pk_add_f32 v[82:83], v[106:107], v[82:83] neg_lo:[0,1] neg_hi:[0,1]
	v_pk_fma_f32 v[130:131], v[150:151], v[164:165], v[130:131] op_sel_hi:[1,0,1]
	v_pk_mul_f32 v[106:107], v[82:83], s[50:51]
	v_pk_add_f32 v[114:115], v[134:135], v[80:81]
	v_pk_fma_f32 v[82:83], v[82:83], s[20:21], v[106:107] op_sel:[0,0,1] op_sel_hi:[1,0,0]
	v_pk_add_f32 v[106:107], v[122:123], v[108:109]
	v_pk_add_f32 v[108:109], v[122:123], v[108:109] neg_lo:[0,1] neg_hi:[0,1]
	s_mov_b32 s21, s34
	v_pk_mul_f32 v[122:123], v[108:109], s[14:15]
	v_pk_add_f32 v[80:81], v[134:135], v[80:81] neg_lo:[0,1] neg_hi:[0,1]
	v_pk_fma_f32 v[108:109], v[108:109], s[6:7], v[122:123] op_sel:[0,0,1] op_sel_hi:[1,0,0]
	v_pk_add_f32 v[122:123], v[84:85], v[74:75]
	v_pk_add_f32 v[74:75], v[84:85], v[74:75] neg_lo:[0,1] neg_hi:[0,1]
	s_mov_b32 s7, s12
	v_pk_mul_f32 v[84:85], v[74:75], s[52:53]
	v_add_u32_e32 v0, v0, v170
	v_pk_fma_f32 v[74:75], v[74:75], s[24:25], v[84:85] op_sel:[0,0,1] op_sel_hi:[1,0,0]
	v_pk_add_f32 v[84:85], v[86:87], v[98:99]
	v_pk_add_f32 v[86:87], v[86:87], v[98:99] neg_lo:[0,1] neg_hi:[0,1]
	s_mov_b32 s25, s26
	v_pk_mul_f32 v[98:99], v[86:87], s[10:11]
	v_lshlrev_b32_e32 v105, 5, v0
	v_pk_fma_f32 v[86:87], v[86:87], s[10:11], v[98:99] op_sel:[0,0,1] op_sel_hi:[1,0,0]
	v_pk_add_f32 v[98:99], v[94:95], v[92:93]
	v_pk_add_f32 v[92:93], v[94:95], v[92:93] neg_lo:[0,1] neg_hi:[0,1]
	s_nop 0
	v_pk_mul_f32 v[94:95], v[92:93], s[24:25]
	s_nop 0
	v_pk_fma_f32 v[92:93], v[92:93], s[0:1], v[94:95] op_sel:[0,0,1] op_sel_hi:[1,0,0]
	v_pk_add_f32 v[94:95], v[124:125], v[100:101]
	v_pk_add_f32 v[100:101], v[124:125], v[100:101] neg_lo:[0,1] neg_hi:[0,1]
	s_nop 0
	v_pk_mul_f32 v[124:125], v[100:101], s[6:7]
	s_nop 0
	v_pk_fma_f32 v[100:101], v[100:101], s[14:15], v[124:125] op_sel:[0,0,1] op_sel_hi:[1,0,0]
	v_pk_add_f32 v[124:125], v[90:91], v[136:137]
	v_pk_add_f32 v[90:91], v[90:91], v[136:137] neg_lo:[0,1] neg_hi:[0,1]
	s_nop 0
	v_pk_mul_f32 v[132:133], v[90:91], s[20:21]
	s_nop 0
	v_pk_fma_f32 v[90:91], v[90:91], s[48:49], v[132:133] op_sel:[0,0,1] op_sel_hi:[1,0,0]
	v_pk_add_f32 v[132:133], v[116:117], v[68:69]
	v_pk_add_f32 v[68:69], v[116:117], v[68:69] neg_lo:[0,1] neg_hi:[0,1]
	s_nop 0
	v_xor_b32_e32 v116, 0x80000000, v69
	v_mov_b32_e32 v117, v68
	v_pk_add_f32 v[68:69], v[118:119], v[96:97]
	v_pk_add_f32 v[96:97], v[118:119], v[96:97] neg_lo:[0,1] neg_hi:[0,1]
	s_nop 0
	v_pk_mul_f32 v[118:119], v[96:97], s[20:21]
	s_nop 0
	v_pk_fma_f32 v[96:97], v[96:97], s[18:19], v[118:119] op_sel:[0,0,1] op_sel_hi:[1,0,0]
	v_pk_add_f32 v[118:119], v[110:111], v[72:73]
	v_pk_add_f32 v[72:73], v[110:111], v[72:73] neg_lo:[0,1] neg_hi:[0,1]
	s_nop 0
	v_pk_mul_f32 v[110:111], v[72:73], s[6:7]
	s_nop 0
	v_pk_fma_f32 v[72:73], v[72:73], s[4:5], v[110:111] op_sel:[0,0,1] op_sel_hi:[1,0,0]
	v_pk_add_f32 v[110:111], v[102:103], v[76:77]
	v_pk_add_f32 v[76:77], v[102:103], v[76:77] neg_lo:[0,1] neg_hi:[0,1]
	s_nop 0
	v_pk_mul_f32 v[102:103], v[76:77], s[24:25]
	s_nop 0
	v_pk_fma_f32 v[76:77], v[76:77], s[22:23], v[102:103] op_sel:[0,0,1] op_sel_hi:[1,0,0]
	v_pk_add_f32 v[102:103], v[120:121], v[66:67]
	v_pk_add_f32 v[66:67], v[120:121], v[66:67] neg_lo:[0,1] neg_hi:[0,1]
	s_nop 0
	v_pk_mul_f32 v[120:121], v[66:67], s[10:11]
	s_nop 0
	v_pk_fma_f32 v[66:67], v[66:67], s[8:9], v[120:121] op_sel:[0,0,1] op_sel_hi:[1,0,0]
	v_pk_add_f32 v[120:121], v[126:127], v[88:89]
	v_pk_add_f32 v[88:89], v[126:127], v[88:89] neg_lo:[0,1] neg_hi:[0,1]
	s_nop 0
	v_pk_mul_f32 v[126:127], v[88:89], s[52:53]
	s_nop 0
	v_pk_fma_f32 v[88:89], v[88:89], s[26:27], v[126:127] op_sel:[0,0,1] op_sel_hi:[1,0,0]
	v_pk_add_f32 v[126:127], v[112:113], v[70:71]
	v_pk_add_f32 v[70:71], v[112:113], v[70:71] neg_lo:[0,1] neg_hi:[0,1]
	s_nop 0
	v_pk_mul_f32 v[112:113], v[70:71], s[14:15]
	s_nop 0
	v_pk_fma_f32 v[70:71], v[70:71], s[12:13], v[112:113] op_sel:[0,0,1] op_sel_hi:[1,0,0]
	v_pk_add_f32 v[112:113], v[130:131], v[78:79]
	v_pk_add_f32 v[78:79], v[130:131], v[78:79] neg_lo:[0,1] neg_hi:[0,1]
	s_nop 0
	v_pk_mul_f32 v[130:131], v[78:79], s[50:51]
	s_nop 0
	v_pk_fma_f32 v[78:79], v[78:79], s[34:35], v[130:131] op_sel:[0,0,1] op_sel_hi:[1,0,0]
	v_pk_add_f32 v[130:131], v[114:115], v[132:133]
	v_pk_add_f32 v[114:115], v[114:115], v[132:133] neg_lo:[0,1] neg_hi:[0,1]
	v_pk_add_f32 v[132:133], v[128:129], v[68:69]
	v_pk_add_f32 v[68:69], v[128:129], v[68:69] neg_lo:[0,1] neg_hi:[0,1]
	s_nop 0
	v_pk_mul_f32 v[128:129], v[68:69], s[14:15]
	s_nop 0
	v_pk_fma_f32 v[68:69], v[68:69], s[6:7], v[128:129] op_sel:[0,0,1] op_sel_hi:[1,0,0]
	v_pk_add_f32 v[128:129], v[106:107], v[118:119]
	v_pk_add_f32 v[106:107], v[106:107], v[118:119] neg_lo:[0,1] neg_hi:[0,1]
	s_nop 0
	v_pk_mul_f32 v[118:119], v[106:107], s[10:11]
	s_nop 0
	v_pk_fma_f32 v[106:107], v[106:107], s[10:11], v[118:119] op_sel:[0,0,1] op_sel_hi:[1,0,0]
	v_pk_add_f32 v[118:119], v[122:123], v[110:111]
	v_pk_add_f32 v[110:111], v[122:123], v[110:111] neg_lo:[0,1] neg_hi:[0,1]
	s_nop 0
	v_pk_mul_f32 v[122:123], v[110:111], s[6:7]
	s_nop 0
	v_pk_fma_f32 v[110:111], v[110:111], s[14:15], v[122:123] op_sel:[0,0,1] op_sel_hi:[1,0,0]
	v_pk_add_f32 v[122:123], v[84:85], v[102:103]
	v_pk_add_f32 v[84:85], v[84:85], v[102:103] neg_lo:[0,1] neg_hi:[0,1]
	s_nop 0
	v_xor_b32_e32 v102, 0x80000000, v85
	v_mov_b32_e32 v103, v84
	v_pk_add_f32 v[84:85], v[98:99], v[120:121]
	v_pk_add_f32 v[98:99], v[98:99], v[120:121] neg_lo:[0,1] neg_hi:[0,1]
	s_nop 0
	v_pk_mul_f32 v[120:121], v[98:99], s[6:7]
	s_nop 0
	v_pk_fma_f32 v[98:99], v[98:99], s[4:5], v[120:121] op_sel:[0,0,1] op_sel_hi:[1,0,0]
	v_pk_add_f32 v[120:121], v[94:95], v[126:127]
	v_pk_add_f32 v[94:95], v[94:95], v[126:127] neg_lo:[0,1] neg_hi:[0,1]
	s_nop 0
	v_pk_mul_f32 v[126:127], v[94:95], s[10:11]
	s_nop 0
	v_pk_fma_f32 v[94:95], v[94:95], s[8:9], v[126:127] op_sel:[0,0,1] op_sel_hi:[1,0,0]
	v_pk_add_f32 v[126:127], v[124:125], v[112:113]
	v_pk_add_f32 v[112:113], v[124:125], v[112:113] neg_lo:[0,1] neg_hi:[0,1]
	s_nop 0
	v_pk_mul_f32 v[124:125], v[112:113], s[14:15]
	s_nop 0
	v_pk_fma_f32 v[112:113], v[112:113], s[12:13], v[124:125] op_sel:[0,0,1] op_sel_hi:[1,0,0]
	v_pk_add_f32 v[124:125], v[80:81], v[116:117]
	v_pk_add_f32 v[80:81], v[80:81], v[116:117] neg_lo:[0,1] neg_hi:[0,1]
	v_pk_add_f32 v[116:117], v[82:83], v[96:97]
	v_pk_add_f32 v[82:83], v[82:83], v[96:97] neg_lo:[0,1] neg_hi:[0,1]
	s_nop 0
	v_pk_mul_f32 v[96:97], v[82:83], s[14:15]
	s_nop 0
	v_pk_fma_f32 v[82:83], v[82:83], s[6:7], v[96:97] op_sel:[0,0,1] op_sel_hi:[1,0,0]
	v_pk_add_f32 v[96:97], v[108:109], v[72:73]
	v_pk_add_f32 v[72:73], v[108:109], v[72:73] neg_lo:[0,1] neg_hi:[0,1]
	s_nop 0
	v_pk_mul_f32 v[108:109], v[72:73], s[10:11]
	s_nop 0
	v_pk_fma_f32 v[72:73], v[72:73], s[10:11], v[108:109] op_sel:[0,0,1] op_sel_hi:[1,0,0]
	v_pk_add_f32 v[108:109], v[74:75], v[76:77]
	v_pk_add_f32 v[74:75], v[74:75], v[76:77] neg_lo:[0,1] neg_hi:[0,1]
	s_nop 0
	v_pk_mul_f32 v[76:77], v[74:75], s[6:7]
	s_nop 0
	v_pk_fma_f32 v[74:75], v[74:75], s[14:15], v[76:77] op_sel:[0,0,1] op_sel_hi:[1,0,0]
	v_pk_add_f32 v[76:77], v[86:87], v[66:67]
	v_pk_add_f32 v[66:67], v[86:87], v[66:67] neg_lo:[0,1] neg_hi:[0,1]
	s_nop 0
	v_xor_b32_e32 v86, 0x80000000, v67
	v_mov_b32_e32 v87, v66
	v_pk_add_f32 v[66:67], v[92:93], v[88:89]
	v_pk_add_f32 v[88:89], v[92:93], v[88:89] neg_lo:[0,1] neg_hi:[0,1]
	s_nop 0
	v_pk_mul_f32 v[92:93], v[88:89], s[6:7]
	s_nop 0
	v_pk_fma_f32 v[88:89], v[88:89], s[4:5], v[92:93] op_sel:[0,0,1] op_sel_hi:[1,0,0]
	v_pk_add_f32 v[92:93], v[100:101], v[70:71]
	v_pk_add_f32 v[70:71], v[100:101], v[70:71] neg_lo:[0,1] neg_hi:[0,1]
	s_nop 0
	v_pk_mul_f32 v[100:101], v[70:71], s[10:11]
	s_nop 0
	v_pk_fma_f32 v[70:71], v[70:71], s[8:9], v[100:101] op_sel:[0,0,1] op_sel_hi:[1,0,0]
	v_pk_add_f32 v[100:101], v[90:91], v[78:79]
	v_pk_add_f32 v[78:79], v[90:91], v[78:79] neg_lo:[0,1] neg_hi:[0,1]
	s_nop 0
	v_pk_mul_f32 v[90:91], v[78:79], s[14:15]
	s_nop 0
	v_pk_fma_f32 v[78:79], v[78:79], s[12:13], v[90:91] op_sel:[0,0,1] op_sel_hi:[1,0,0]
	v_pk_add_f32 v[90:91], v[130:131], v[122:123]
	v_pk_add_f32 v[122:123], v[130:131], v[122:123] neg_lo:[0,1] neg_hi:[0,1]
	v_pk_add_f32 v[130:131], v[132:133], v[84:85]
	v_pk_add_f32 v[84:85], v[132:133], v[84:85] neg_lo:[0,1] neg_hi:[0,1]
	s_nop 0
	v_pk_mul_f32 v[132:133], v[84:85], s[10:11]
	s_nop 0
	v_pk_fma_f32 v[84:85], v[84:85], s[10:11], v[132:133] op_sel:[0,0,1] op_sel_hi:[1,0,0]
	v_pk_add_f32 v[132:133], v[128:129], v[120:121]
	v_pk_add_f32 v[120:121], v[128:129], v[120:121] neg_lo:[0,1] neg_hi:[0,1]
	s_nop 0
	v_xor_b32_e32 v128, 0x80000000, v121
	v_mov_b32_e32 v129, v120
	v_pk_add_f32 v[120:121], v[118:119], v[126:127]
	v_pk_add_f32 v[118:119], v[118:119], v[126:127] neg_lo:[0,1] neg_hi:[0,1]
	s_nop 0
	v_pk_mul_f32 v[126:127], v[118:119], s[10:11]
	s_nop 0
	v_pk_fma_f32 v[118:119], v[118:119], s[8:9], v[126:127] op_sel:[0,0,1] op_sel_hi:[1,0,0]
	v_pk_add_f32 v[126:127], v[114:115], v[102:103]
	v_pk_add_f32 v[102:103], v[114:115], v[102:103] neg_lo:[0,1] neg_hi:[0,1]
	v_pk_add_f32 v[114:115], v[68:69], v[98:99]
	v_pk_add_f32 v[68:69], v[68:69], v[98:99] neg_lo:[0,1] neg_hi:[0,1]
	s_nop 0
	v_pk_mul_f32 v[98:99], v[68:69], s[10:11]
	s_nop 0
	v_pk_fma_f32 v[68:69], v[68:69], s[10:11], v[98:99] op_sel:[0,0,1] op_sel_hi:[1,0,0]
	v_pk_add_f32 v[98:99], v[106:107], v[94:95]
	v_pk_add_f32 v[94:95], v[106:107], v[94:95] neg_lo:[0,1] neg_hi:[0,1]
	s_nop 0
	v_xor_b32_e32 v106, 0x80000000, v95
	v_mov_b32_e32 v107, v94
	v_pk_add_f32 v[94:95], v[110:111], v[112:113]
	v_pk_add_f32 v[110:111], v[110:111], v[112:113] neg_lo:[0,1] neg_hi:[0,1]
	s_nop 0
	v_pk_mul_f32 v[112:113], v[110:111], s[10:11]
	s_nop 0
	v_pk_fma_f32 v[110:111], v[110:111], s[8:9], v[112:113] op_sel:[0,0,1] op_sel_hi:[1,0,0]
	v_pk_add_f32 v[112:113], v[124:125], v[76:77]
	v_pk_add_f32 v[76:77], v[124:125], v[76:77] neg_lo:[0,1] neg_hi:[0,1]
	v_pk_add_f32 v[124:125], v[116:117], v[66:67]
	v_pk_add_f32 v[66:67], v[116:117], v[66:67] neg_lo:[0,1] neg_hi:[0,1]
	s_nop 0
	v_pk_mul_f32 v[116:117], v[66:67], s[10:11]
	s_nop 0
	v_pk_fma_f32 v[66:67], v[66:67], s[10:11], v[116:117] op_sel:[0,0,1] op_sel_hi:[1,0,0]
	v_pk_add_f32 v[116:117], v[96:97], v[92:93]
	v_pk_add_f32 v[92:93], v[96:97], v[92:93] neg_lo:[0,1] neg_hi:[0,1]
	v_pk_add_f32 v[134:135], v[112:113], v[116:117]
	v_xor_b32_e32 v96, 0x80000000, v93
	v_mov_b32_e32 v97, v92
	v_pk_add_f32 v[92:93], v[108:109], v[100:101]
	v_pk_add_f32 v[100:101], v[108:109], v[100:101] neg_lo:[0,1] neg_hi:[0,1]
	v_pk_add_f32 v[112:113], v[112:113], v[116:117] neg_lo:[0,1] neg_hi:[0,1]
	v_pk_mul_f32 v[108:109], v[100:101], s[10:11]
	v_pk_add_f32 v[116:117], v[124:125], v[92:93]
	v_pk_fma_f32 v[100:101], v[100:101], s[8:9], v[108:109] op_sel:[0,0,1] op_sel_hi:[1,0,0]
	v_pk_add_f32 v[108:109], v[80:81], v[86:87]
	v_pk_add_f32 v[80:81], v[80:81], v[86:87] neg_lo:[0,1] neg_hi:[0,1]
	v_pk_add_f32 v[86:87], v[82:83], v[88:89]
	v_pk_add_f32 v[82:83], v[82:83], v[88:89] neg_lo:[0,1] neg_hi:[0,1]
	s_nop 0
	v_pk_mul_f32 v[88:89], v[82:83], s[10:11]
	s_nop 0
	v_pk_fma_f32 v[82:83], v[82:83], s[10:11], v[88:89] op_sel:[0,0,1] op_sel_hi:[1,0,0]
	v_pk_add_f32 v[88:89], v[72:73], v[70:71]
	v_pk_add_f32 v[70:71], v[72:73], v[70:71] neg_lo:[0,1] neg_hi:[0,1]
	v_pk_add_f32 v[136:137], v[108:109], v[88:89]
	v_xor_b32_e32 v72, 0x80000000, v71
	v_mov_b32_e32 v73, v70
	v_pk_add_f32 v[70:71], v[74:75], v[78:79]
	v_pk_add_f32 v[74:75], v[74:75], v[78:79] neg_lo:[0,1] neg_hi:[0,1]
	v_pk_add_f32 v[88:89], v[108:109], v[88:89] neg_lo:[0,1] neg_hi:[0,1]
	v_pk_mul_f32 v[78:79], v[74:75], s[10:11]
	v_pk_add_f32 v[108:109], v[86:87], v[70:71]
	v_pk_fma_f32 v[74:75], v[74:75], s[8:9], v[78:79] op_sel:[0,0,1] op_sel_hi:[1,0,0]
	v_pk_add_f32 v[78:79], v[90:91], v[132:133]
	v_pk_add_f32 v[90:91], v[90:91], v[132:133] neg_lo:[0,1] neg_hi:[0,1]
	v_pk_add_f32 v[132:133], v[130:131], v[120:121]
	v_pk_add_f32 v[120:121], v[130:131], v[120:121] neg_lo:[0,1] neg_hi:[0,1]
	v_pk_add_f32 v[138:139], v[80:81], v[72:73] neg_lo:[0,1] neg_hi:[0,1]
	v_xor_b32_e32 v130, 0x80000000, v121
	v_mov_b32_e32 v131, v120
	v_pk_add_f32 v[120:121], v[122:123], v[128:129]
	v_pk_add_f32 v[122:123], v[122:123], v[128:129] neg_lo:[0,1] neg_hi:[0,1]
	v_pk_add_f32 v[128:129], v[84:85], v[118:119]
	v_pk_add_f32 v[84:85], v[84:85], v[118:119] neg_lo:[0,1] neg_hi:[0,1]
	v_pk_add_f32 v[140:141], v[82:83], v[74:75]
	v_xor_b32_e32 v118, 0x80000000, v85
	v_mov_b32_e32 v119, v84
	v_pk_add_f32 v[84:85], v[126:127], v[98:99]
	v_pk_add_f32 v[98:99], v[126:127], v[98:99] neg_lo:[0,1] neg_hi:[0,1]
	v_pk_add_f32 v[126:127], v[114:115], v[94:95]
	v_pk_add_f32 v[94:95], v[114:115], v[94:95] neg_lo:[0,1] neg_hi:[0,1]
	v_pk_add_f32 v[142:143], v[78:79], v[132:133]
	v_xor_b32_e32 v114, 0x80000000, v95
	v_mov_b32_e32 v115, v94
	v_pk_add_f32 v[94:95], v[102:103], v[106:107]
	v_pk_add_f32 v[102:103], v[102:103], v[106:107] neg_lo:[0,1] neg_hi:[0,1]
	v_pk_add_f32 v[106:107], v[68:69], v[110:111]
	v_pk_add_f32 v[68:69], v[68:69], v[110:111] neg_lo:[0,1] neg_hi:[0,1]
	v_pk_add_f32 v[132:133], v[78:79], v[132:133] neg_lo:[0,1] neg_hi:[0,1]
	v_xor_b32_e32 v110, 0x80000000, v69
	v_mov_b32_e32 v111, v68
	v_pk_add_f32 v[68:69], v[124:125], v[92:93] neg_lo:[0,1] neg_hi:[0,1]
	v_pk_add_f32 v[124:125], v[76:77], v[96:97]
	v_pk_add_f32 v[76:77], v[76:77], v[96:97] neg_lo:[0,1] neg_hi:[0,1]
	v_pk_add_f32 v[96:97], v[66:67], v[100:101]
	v_pk_add_f32 v[66:67], v[66:67], v[100:101] neg_lo:[0,1] neg_hi:[0,1]
	v_xor_b32_e32 v92, 0x80000000, v69
	v_xor_b32_e32 v100, 0x80000000, v67
	v_mov_b32_e32 v101, v66
	v_pk_add_f32 v[66:67], v[86:87], v[70:71] neg_lo:[0,1] neg_hi:[0,1]
	v_mov_b32_e32 v93, v68
	v_xor_b32_e32 v70, 0x80000000, v67
	v_mov_b32_e32 v71, v66
	v_pk_add_f32 v[66:67], v[82:83], v[74:75] neg_lo:[0,1] neg_hi:[0,1]
	v_pk_add_f32 v[86:87], v[80:81], v[72:73]
	v_xor_b32_e32 v74, 0x80000000, v67
	v_mov_b32_e32 v75, v66
	v_pk_add_f32 v[144:145], v[90:91], v[130:131]
	v_pk_add_f32 v[82:83], v[90:91], v[130:131] neg_lo:[0,1] neg_hi:[0,1]
	v_pk_add_f32 v[90:91], v[120:121], v[128:129]
	v_pk_add_f32 v[120:121], v[120:121], v[128:129] neg_lo:[0,1] neg_hi:[0,1]
	v_pk_add_f32 v[128:129], v[122:123], v[118:119]
	v_pk_add_f32 v[68:69], v[122:123], v[118:119] neg_lo:[0,1] neg_hi:[0,1]
	v_pk_add_f32 v[118:119], v[84:85], v[126:127]
	v_pk_add_f32 v[122:123], v[84:85], v[126:127] neg_lo:[0,1] neg_hi:[0,1]
	v_pk_add_f32 v[126:127], v[98:99], v[114:115]
	v_pk_add_f32 v[78:79], v[98:99], v[114:115] neg_lo:[0,1] neg_hi:[0,1]
	v_pk_add_f32 v[98:99], v[94:95], v[106:107]
	v_pk_add_f32 v[94:95], v[94:95], v[106:107] neg_lo:[0,1] neg_hi:[0,1]
	v_pk_add_f32 v[106:107], v[102:103], v[110:111]
	v_pk_add_f32 v[66:67], v[102:103], v[110:111] neg_lo:[0,1] neg_hi:[0,1]
	v_pk_add_f32 v[102:103], v[134:135], v[116:117]
	v_pk_add_f32 v[110:111], v[134:135], v[116:117] neg_lo:[0,1] neg_hi:[0,1]
	v_pk_add_f32 v[116:117], v[88:89], v[70:71]
	v_pk_add_f32 v[80:81], v[88:89], v[70:71] neg_lo:[0,1] neg_hi:[0,1]
	v_lshlrev_b32_e32 v70, 4, v0
	v_and_b32_e32 v70, 0x1f0, v70
	v_pk_add_f32 v[114:115], v[112:113], v[92:93]
	v_pk_add_f32 v[84:85], v[112:113], v[92:93] neg_lo:[0,1] neg_hi:[0,1]
	v_pk_add_f32 v[112:113], v[76:77], v[100:101]
	v_pk_add_f32 v[72:73], v[76:77], v[100:101] neg_lo:[0,1] neg_hi:[0,1]
	v_cvt_f32_u32_e32 v76, v70
	v_pk_add_f32 v[92:93], v[124:125], v[96:97]
	v_pk_add_f32 v[96:97], v[124:125], v[96:97] neg_lo:[0,1] neg_hi:[0,1]
	v_pk_add_f32 v[124:125], v[138:139], v[74:75]
	v_mul_f32_e32 v76, 0x38800000, v76
	v_pk_add_f32 v[70:71], v[138:139], v[74:75] neg_lo:[0,1] neg_hi:[0,1]
	v_sin_f32_e32 v75, v76
	v_ashrrev_i32_e32 v74, 2, v105
	v_lshlrev_b32_e32 v0, 8, v0
	v_add3_u32 v0, 0, v74, v0
	v_cos_f32_e32 v74, v76
	v_xor_b32_e32 v76, 0x80000000, v75
	v_mov_b32_e32 v77, v75
	v_pk_mul_f32 v[130:131], v[76:77], v[102:103] op_sel:[0,1] op_sel_hi:[1,0]
	v_pk_add_f32 v[100:101], v[136:137], v[108:109]
	v_pk_fma_f32 v[102:103], v[102:103], v[74:75], v[130:131] op_sel_hi:[1,0,1]
	ds_write2_b64 v0, v[142:143], v[102:103] offset1:1
	v_pk_mul_f32 v[102:103], v[76:77], v[74:75] op_sel:[0,1] op_sel_hi:[1,0]
	v_pk_add_f32 v[88:89], v[86:87], v[140:141]
	v_pk_fma_f32 v[102:103], v[74:75], v[74:75], v[102:103] op_sel_hi:[1,0,1]
	v_pk_add_f32 v[108:109], v[136:137], v[108:109] neg_lo:[0,1] neg_hi:[0,1]
	v_xor_b32_e32 v130, 0x80000000, v103
	v_mov_b32_e32 v131, v103
	v_pk_mul_f32 v[130:131], v[118:119], v[130:131] op_sel:[1,0] op_sel_hi:[0,1]
	v_pk_fma_f32 v[118:119], v[118:119], v[102:103], v[130:131] op_sel_hi:[1,0,1]
	v_pk_mul_f32 v[130:131], v[76:77], v[102:103] op_sel:[0,1] op_sel_hi:[1,0]
	v_pk_add_f32 v[86:87], v[86:87], v[140:141] neg_lo:[0,1] neg_hi:[0,1]
	v_pk_fma_f32 v[102:103], v[102:103], v[74:75], v[130:131] op_sel_hi:[1,0,1]
	s_nop 0
	v_xor_b32_e32 v130, 0x80000000, v103
	v_mov_b32_e32 v131, v103
	v_pk_mul_f32 v[130:131], v[100:101], v[130:131] op_sel:[1,0] op_sel_hi:[0,1]
	v_pk_fma_f32 v[100:101], v[100:101], v[102:103], v[130:131] op_sel_hi:[1,0,1]
	ds_write2_b64 v0, v[118:119], v[100:101] offset0:2 offset1:3
	v_pk_mul_f32 v[100:101], v[76:77], v[102:103] op_sel:[0,1] op_sel_hi:[1,0]
	s_nop 0
	v_pk_fma_f32 v[100:101], v[102:103], v[74:75], v[100:101] op_sel_hi:[1,0,1]
	s_nop 0
	v_xor_b32_e32 v102, 0x80000000, v101
	v_mov_b32_e32 v103, v101
	v_pk_mul_f32 v[102:103], v[90:91], v[102:103] op_sel:[1,0] op_sel_hi:[0,1]
	v_pk_fma_f32 v[90:91], v[90:91], v[100:101], v[102:103] op_sel_hi:[1,0,1]
	v_pk_mul_f32 v[102:103], v[76:77], v[100:101] op_sel:[0,1] op_sel_hi:[1,0]
	s_nop 0
	v_pk_fma_f32 v[100:101], v[100:101], v[74:75], v[102:103] op_sel_hi:[1,0,1]
	s_nop 0
	v_xor_b32_e32 v102, 0x80000000, v101
	v_mov_b32_e32 v103, v101
	v_pk_mul_f32 v[102:103], v[92:93], v[102:103] op_sel:[1,0] op_sel_hi:[0,1]
	v_pk_fma_f32 v[92:93], v[92:93], v[100:101], v[102:103] op_sel_hi:[1,0,1]
	ds_write2_b64 v0, v[90:91], v[92:93] offset0:4 offset1:5
	v_pk_mul_f32 v[90:91], v[76:77], v[100:101] op_sel:[0,1] op_sel_hi:[1,0]
	s_nop 0
	v_pk_fma_f32 v[90:91], v[100:101], v[74:75], v[90:91] op_sel_hi:[1,0,1]
	s_nop 0
	v_xor_b32_e32 v92, 0x80000000, v91
	v_mov_b32_e32 v93, v91
	v_pk_mul_f32 v[92:93], v[98:99], v[92:93] op_sel:[1,0] op_sel_hi:[0,1]
	v_pk_fma_f32 v[92:93], v[98:99], v[90:91], v[92:93] op_sel_hi:[1,0,1]
	v_pk_mul_f32 v[98:99], v[76:77], v[90:91] op_sel:[0,1] op_sel_hi:[1,0]
	s_nop 0
	v_pk_fma_f32 v[90:91], v[90:91], v[74:75], v[98:99] op_sel_hi:[1,0,1]
	s_nop 0
	v_xor_b32_e32 v98, 0x80000000, v91
	v_mov_b32_e32 v99, v91
	v_pk_mul_f32 v[98:99], v[88:89], v[98:99] op_sel:[1,0] op_sel_hi:[0,1]
	v_pk_fma_f32 v[88:89], v[88:89], v[90:91], v[98:99] op_sel_hi:[1,0,1]
	ds_write2_b64 v0, v[92:93], v[88:89] offset0:6 offset1:7
	v_pk_mul_f32 v[88:89], v[76:77], v[90:91] op_sel:[0,1] op_sel_hi:[1,0]
	s_nop 0
	v_pk_fma_f32 v[88:89], v[90:91], v[74:75], v[88:89] op_sel_hi:[1,0,1]
	s_nop 0
	v_xor_b32_e32 v90, 0x80000000, v89
	v_mov_b32_e32 v91, v89
	v_pk_mul_f32 v[90:91], v[144:145], v[90:91] op_sel:[1,0] op_sel_hi:[0,1]
	v_pk_mul_f32 v[92:93], v[76:77], v[88:89] op_sel:[0,1] op_sel_hi:[1,0]
	v_pk_fma_f32 v[90:91], v[144:145], v[88:89], v[90:91] op_sel_hi:[1,0,1]
	v_pk_fma_f32 v[88:89], v[88:89], v[74:75], v[92:93] op_sel_hi:[1,0,1]
	s_nop 0
	v_xor_b32_e32 v92, 0x80000000, v89
	v_mov_b32_e32 v93, v89
	v_pk_mul_f32 v[92:93], v[114:115], v[92:93] op_sel:[1,0] op_sel_hi:[0,1]
	v_pk_fma_f32 v[92:93], v[114:115], v[88:89], v[92:93] op_sel_hi:[1,0,1]
	ds_write2_b64 v0, v[90:91], v[92:93] offset0:8 offset1:9
	v_pk_mul_f32 v[90:91], v[76:77], v[88:89] op_sel:[0,1] op_sel_hi:[1,0]
	s_nop 0
	v_pk_fma_f32 v[88:89], v[88:89], v[74:75], v[90:91] op_sel_hi:[1,0,1]
	s_nop 0
	v_xor_b32_e32 v90, 0x80000000, v89
	v_mov_b32_e32 v91, v89
	v_pk_mul_f32 v[90:91], v[126:127], v[90:91] op_sel:[1,0] op_sel_hi:[0,1]
	v_pk_mul_f32 v[92:93], v[76:77], v[88:89] op_sel:[0,1] op_sel_hi:[1,0]
	v_pk_fma_f32 v[90:91], v[126:127], v[88:89], v[90:91] op_sel_hi:[1,0,1]
	v_pk_fma_f32 v[88:89], v[88:89], v[74:75], v[92:93] op_sel_hi:[1,0,1]
	s_nop 0
	v_xor_b32_e32 v92, 0x80000000, v89
	v_mov_b32_e32 v93, v89
	v_pk_mul_f32 v[92:93], v[116:117], v[92:93] op_sel:[1,0] op_sel_hi:[0,1]
	v_pk_fma_f32 v[92:93], v[116:117], v[88:89], v[92:93] op_sel_hi:[1,0,1]
	ds_write2_b64 v0, v[90:91], v[92:93] offset0:10 offset1:11
	v_pk_mul_f32 v[90:91], v[76:77], v[88:89] op_sel:[0,1] op_sel_hi:[1,0]
	s_nop 0
	v_pk_fma_f32 v[88:89], v[88:89], v[74:75], v[90:91] op_sel_hi:[1,0,1]
	s_nop 0
	v_xor_b32_e32 v90, 0x80000000, v89
	v_mov_b32_e32 v91, v89
	v_pk_mul_f32 v[90:91], v[128:129], v[90:91] op_sel:[1,0] op_sel_hi:[0,1]
	v_pk_mul_f32 v[92:93], v[76:77], v[88:89] op_sel:[0,1] op_sel_hi:[1,0]
	v_pk_fma_f32 v[90:91], v[128:129], v[88:89], v[90:91] op_sel_hi:[1,0,1]
	v_pk_fma_f32 v[88:89], v[88:89], v[74:75], v[92:93] op_sel_hi:[1,0,1]
	s_nop 0
	v_xor_b32_e32 v92, 0x80000000, v89
	v_mov_b32_e32 v93, v89
	v_pk_mul_f32 v[92:93], v[112:113], v[92:93] op_sel:[1,0] op_sel_hi:[0,1]
	v_pk_fma_f32 v[92:93], v[112:113], v[88:89], v[92:93] op_sel_hi:[1,0,1]
	ds_write2_b64 v0, v[90:91], v[92:93] offset0:12 offset1:13
	v_pk_mul_f32 v[90:91], v[76:77], v[88:89] op_sel:[0,1] op_sel_hi:[1,0]
	s_nop 0
	v_pk_fma_f32 v[88:89], v[88:89], v[74:75], v[90:91] op_sel_hi:[1,0,1]
	s_nop 0
	v_xor_b32_e32 v90, 0x80000000, v89
	v_mov_b32_e32 v91, v89
	v_pk_mul_f32 v[90:91], v[106:107], v[90:91] op_sel:[1,0] op_sel_hi:[0,1]
	v_pk_mul_f32 v[92:93], v[76:77], v[88:89] op_sel:[0,1] op_sel_hi:[1,0]
	v_pk_fma_f32 v[90:91], v[106:107], v[88:89], v[90:91] op_sel_hi:[1,0,1]
	v_pk_fma_f32 v[88:89], v[88:89], v[74:75], v[92:93] op_sel_hi:[1,0,1]
	s_nop 0
	v_xor_b32_e32 v92, 0x80000000, v89
	v_mov_b32_e32 v93, v89
	v_pk_mul_f32 v[92:93], v[124:125], v[92:93] op_sel:[1,0] op_sel_hi:[0,1]
	v_pk_fma_f32 v[92:93], v[124:125], v[88:89], v[92:93] op_sel_hi:[1,0,1]
	ds_write2_b64 v0, v[90:91], v[92:93] offset0:14 offset1:15
	v_pk_mul_f32 v[90:91], v[76:77], v[88:89] op_sel:[0,1] op_sel_hi:[1,0]
	s_nop 0
	v_pk_fma_f32 v[88:89], v[88:89], v[74:75], v[90:91] op_sel_hi:[1,0,1]
	s_nop 0
	v_xor_b32_e32 v90, 0x80000000, v89
	v_mov_b32_e32 v91, v89
	v_pk_mul_f32 v[90:91], v[132:133], v[90:91] op_sel:[1,0] op_sel_hi:[0,1]
	v_pk_mul_f32 v[92:93], v[76:77], v[88:89] op_sel:[0,1] op_sel_hi:[1,0]
	v_pk_fma_f32 v[90:91], v[132:133], v[88:89], v[90:91] op_sel_hi:[1,0,1]
	v_pk_fma_f32 v[88:89], v[88:89], v[74:75], v[92:93] op_sel_hi:[1,0,1]
	s_nop 0
	v_xor_b32_e32 v92, 0x80000000, v89
	v_mov_b32_e32 v93, v89
	v_pk_mul_f32 v[92:93], v[110:111], v[92:93] op_sel:[1,0] op_sel_hi:[0,1]
	v_pk_fma_f32 v[92:93], v[110:111], v[88:89], v[92:93] op_sel_hi:[1,0,1]
	ds_write2_b64 v0, v[90:91], v[92:93] offset0:16 offset1:17
	v_pk_mul_f32 v[90:91], v[76:77], v[88:89] op_sel:[0,1] op_sel_hi:[1,0]
	s_nop 0
	v_pk_fma_f32 v[88:89], v[88:89], v[74:75], v[90:91] op_sel_hi:[1,0,1]
	s_nop 0
	v_xor_b32_e32 v90, 0x80000000, v89
	v_mov_b32_e32 v91, v89
	v_pk_mul_f32 v[90:91], v[122:123], v[90:91] op_sel:[1,0] op_sel_hi:[0,1]
	v_pk_mul_f32 v[92:93], v[76:77], v[88:89] op_sel:[0,1] op_sel_hi:[1,0]
	v_pk_fma_f32 v[90:91], v[122:123], v[88:89], v[90:91] op_sel_hi:[1,0,1]
	v_pk_fma_f32 v[88:89], v[88:89], v[74:75], v[92:93] op_sel_hi:[1,0,1]
	s_nop 0
	v_xor_b32_e32 v92, 0x80000000, v89
	v_mov_b32_e32 v93, v89
	v_pk_mul_f32 v[92:93], v[108:109], v[92:93] op_sel:[1,0] op_sel_hi:[0,1]
	v_pk_fma_f32 v[92:93], v[108:109], v[88:89], v[92:93] op_sel_hi:[1,0,1]
	ds_write2_b64 v0, v[90:91], v[92:93] offset0:18 offset1:19
	v_pk_mul_f32 v[90:91], v[76:77], v[88:89] op_sel:[0,1] op_sel_hi:[1,0]
	s_nop 0
	v_pk_fma_f32 v[88:89], v[88:89], v[74:75], v[90:91] op_sel_hi:[1,0,1]
	s_nop 0
	v_xor_b32_e32 v90, 0x80000000, v89
	v_mov_b32_e32 v91, v89
	v_pk_mul_f32 v[90:91], v[120:121], v[90:91] op_sel:[1,0] op_sel_hi:[0,1]
	v_pk_mul_f32 v[92:93], v[76:77], v[88:89] op_sel:[0,1] op_sel_hi:[1,0]
	v_pk_fma_f32 v[90:91], v[120:121], v[88:89], v[90:91] op_sel_hi:[1,0,1]
	v_pk_fma_f32 v[88:89], v[88:89], v[74:75], v[92:93] op_sel_hi:[1,0,1]
	s_nop 0
	v_xor_b32_e32 v92, 0x80000000, v89
	v_mov_b32_e32 v93, v89
	v_pk_mul_f32 v[92:93], v[96:97], v[92:93] op_sel:[1,0] op_sel_hi:[0,1]
	v_pk_fma_f32 v[92:93], v[96:97], v[88:89], v[92:93] op_sel_hi:[1,0,1]
	ds_write2_b64 v0, v[90:91], v[92:93] offset0:20 offset1:21
	v_pk_mul_f32 v[90:91], v[76:77], v[88:89] op_sel:[0,1] op_sel_hi:[1,0]
	s_nop 0
	v_pk_fma_f32 v[88:89], v[88:89], v[74:75], v[90:91] op_sel_hi:[1,0,1]
	s_nop 0
	v_xor_b32_e32 v90, 0x80000000, v89
	v_mov_b32_e32 v91, v89
	v_pk_mul_f32 v[90:91], v[94:95], v[90:91] op_sel:[1,0] op_sel_hi:[0,1]
	v_pk_mul_f32 v[92:93], v[76:77], v[88:89] op_sel:[0,1] op_sel_hi:[1,0]
	v_pk_fma_f32 v[90:91], v[94:95], v[88:89], v[90:91] op_sel_hi:[1,0,1]
	v_pk_fma_f32 v[88:89], v[88:89], v[74:75], v[92:93] op_sel_hi:[1,0,1]
	s_nop 0
	v_xor_b32_e32 v92, 0x80000000, v89
	v_mov_b32_e32 v93, v89
	v_pk_mul_f32 v[92:93], v[86:87], v[92:93] op_sel:[1,0] op_sel_hi:[0,1]
	v_pk_fma_f32 v[86:87], v[86:87], v[88:89], v[92:93] op_sel_hi:[1,0,1]
	ds_write2_b64 v0, v[90:91], v[86:87] offset0:22 offset1:23
	v_pk_mul_f32 v[86:87], v[76:77], v[88:89] op_sel:[0,1] op_sel_hi:[1,0]
	s_nop 0
	v_pk_fma_f32 v[86:87], v[88:89], v[74:75], v[86:87] op_sel_hi:[1,0,1]
	s_nop 0
	v_xor_b32_e32 v88, 0x80000000, v87
	v_mov_b32_e32 v89, v87
	v_pk_mul_f32 v[88:89], v[82:83], v[88:89] op_sel:[1,0] op_sel_hi:[0,1]
	v_pk_fma_f32 v[82:83], v[82:83], v[86:87], v[88:89] op_sel_hi:[1,0,1]
	v_pk_mul_f32 v[88:89], v[76:77], v[86:87] op_sel:[0,1] op_sel_hi:[1,0]
	s_nop 0
	v_pk_fma_f32 v[86:87], v[86:87], v[74:75], v[88:89] op_sel_hi:[1,0,1]
	s_nop 0
	v_xor_b32_e32 v88, 0x80000000, v87
	v_mov_b32_e32 v89, v87
	v_pk_mul_f32 v[88:89], v[84:85], v[88:89] op_sel:[1,0] op_sel_hi:[0,1]
	v_pk_fma_f32 v[84:85], v[84:85], v[86:87], v[88:89] op_sel_hi:[1,0,1]
	ds_write2_b64 v0, v[82:83], v[84:85] offset0:24 offset1:25
	v_pk_mul_f32 v[82:83], v[76:77], v[86:87] op_sel:[0,1] op_sel_hi:[1,0]
	s_nop 0
	v_pk_fma_f32 v[82:83], v[86:87], v[74:75], v[82:83] op_sel_hi:[1,0,1]
	s_nop 0
	v_xor_b32_e32 v84, 0x80000000, v83
	v_mov_b32_e32 v85, v83
	v_pk_mul_f32 v[84:85], v[78:79], v[84:85] op_sel:[1,0] op_sel_hi:[0,1]
	v_pk_fma_f32 v[78:79], v[78:79], v[82:83], v[84:85] op_sel_hi:[1,0,1]
	v_pk_mul_f32 v[84:85], v[76:77], v[82:83] op_sel:[0,1] op_sel_hi:[1,0]
	s_nop 0
	v_pk_fma_f32 v[82:83], v[82:83], v[74:75], v[84:85] op_sel_hi:[1,0,1]
	s_nop 0
	v_xor_b32_e32 v84, 0x80000000, v83
	v_mov_b32_e32 v85, v83
	v_pk_mul_f32 v[84:85], v[80:81], v[84:85] op_sel:[1,0] op_sel_hi:[0,1]
	v_pk_fma_f32 v[80:81], v[80:81], v[82:83], v[84:85] op_sel_hi:[1,0,1]
	ds_write2_b64 v0, v[78:79], v[80:81] offset0:26 offset1:27
	v_pk_mul_f32 v[78:79], v[76:77], v[82:83] op_sel:[0,1] op_sel_hi:[1,0]
	s_nop 0
	v_pk_fma_f32 v[78:79], v[82:83], v[74:75], v[78:79] op_sel_hi:[1,0,1]
	s_nop 0
	v_xor_b32_e32 v80, 0x80000000, v79
	v_mov_b32_e32 v81, v79
	v_pk_mul_f32 v[80:81], v[68:69], v[80:81] op_sel:[1,0] op_sel_hi:[0,1]
	v_pk_fma_f32 v[68:69], v[68:69], v[78:79], v[80:81] op_sel_hi:[1,0,1]
	v_pk_mul_f32 v[80:81], v[76:77], v[78:79] op_sel:[0,1] op_sel_hi:[1,0]
	s_nop 0
	v_pk_fma_f32 v[78:79], v[78:79], v[74:75], v[80:81] op_sel_hi:[1,0,1]
	s_nop 0
	v_xor_b32_e32 v80, 0x80000000, v79
	v_mov_b32_e32 v81, v79
	v_pk_mul_f32 v[80:81], v[72:73], v[80:81] op_sel:[1,0] op_sel_hi:[0,1]
	v_pk_fma_f32 v[72:73], v[72:73], v[78:79], v[80:81] op_sel_hi:[1,0,1]
	ds_write2_b64 v0, v[68:69], v[72:73] offset0:28 offset1:29
	v_pk_mul_f32 v[68:69], v[76:77], v[78:79] op_sel:[0,1] op_sel_hi:[1,0]
	s_nop 0
	v_pk_fma_f32 v[68:69], v[78:79], v[74:75], v[68:69] op_sel_hi:[1,0,1]
	s_nop 0
	v_xor_b32_e32 v72, 0x80000000, v69
	v_mov_b32_e32 v73, v69
	v_pk_mul_f32 v[72:73], v[66:67], v[72:73] op_sel:[1,0] op_sel_hi:[0,1]
	v_pk_fma_f32 v[66:67], v[66:67], v[68:69], v[72:73] op_sel_hi:[1,0,1]
	v_pk_mul_f32 v[72:73], v[76:77], v[68:69] op_sel:[0,1] op_sel_hi:[1,0]
	s_nop 0
	v_pk_fma_f32 v[68:69], v[68:69], v[74:75], v[72:73] op_sel_hi:[1,0,1]
	s_nop 0
	v_xor_b32_e32 v72, 0x80000000, v69
	v_mov_b32_e32 v73, v69
	v_pk_mul_f32 v[72:73], v[70:71], v[72:73] op_sel:[1,0] op_sel_hi:[0,1]
	v_pk_fma_f32 v[68:69], v[70:71], v[68:69], v[72:73] op_sel_hi:[1,0,1]
	ds_write2_b64 v0, v[66:67], v[68:69] offset0:30 offset1:31
	s_waitcnt lgkmcnt(0)
	s_barrier
	v_mov_b32 v0, 0
	s_nop 0
	v_add_u32_e32 v71, v0, v170
	v_ashrrev_i32_e32 v105, 5, v71
	v_lshlrev_b32_e32 v0, 10, v105
	v_and_b32_e32 v140, 31, v71
	v_ashrrev_i32_e32 v0, 2, v0
	v_lshlrev_b32_e32 v67, 13, v105
	v_lshlrev_b32_e32 v68, 3, v140
	v_add_u32_e32 v0, 0, v0
	v_lshl_add_u32 v66, v105, 8, 0
	v_add3_u32 v0, v0, v67, v68
	v_add3_u32 v142, v66, v67, v68
	v_add_u32_e32 v143, 0x400, v0
	v_add_u32_e32 v144, 0x800, v0
	v_add_u32_e32 v145, 0xc00, v0
	ds_read_b64 v[130:131], v142
	ds_read2_b64 v[66:69], v0 offset0:33 offset1:66
	ds_read2_b64 v[72:75], v0 offset0:99 offset1:132
	ds_read2_b64 v[76:79], v0 offset0:165 offset1:198
	ds_read2_b64 v[80:83], v143 offset0:103 offset1:136
	ds_read2_b64 v[84:87], v144 offset0:41 offset1:74
	ds_read2_b64 v[88:91], v144 offset0:107 offset1:140
	ds_read2_b64 v[92:95], v144 offset0:173 offset1:206
	ds_read2_b64 v[96:99], v145 offset0:111 offset1:144
	v_add_u32_e32 v146, 0x1000, v0
	ds_read2_b64 v[100:103], v146 offset0:49 offset1:82
	ds_read2_b64 v[106:109], v146 offset0:115 offset1:148
	ds_read2_b64 v[110:113], v146 offset0:181 offset1:214
	v_add_u32_e32 v147, 0x1400, v0
	ds_read2_b64 v[114:117], v147 offset0:119 offset1:152
	s_waitcnt lgkmcnt(4)
	v_pk_add_f32 v[134:135], v[130:131], v[98:99]
	v_pk_add_f32 v[98:99], v[130:131], v[98:99] neg_lo:[0,1] neg_hi:[0,1]
	s_waitcnt lgkmcnt(3)
	v_pk_add_f32 v[130:131], v[66:67], v[100:101]
	v_pk_add_f32 v[66:67], v[66:67], v[100:101] neg_lo:[0,1] neg_hi:[0,1]
	v_add_u32_e32 v70, 0x1800, v0
	v_pk_mul_f32 v[100:101], v[66:67], s[50:51]
	ds_read2_b64 v[118:121], v70 offset0:57 offset1:90
	ds_read2_b64 v[122:125], v70 offset0:123 offset1:156
	ds_read2_b64 v[126:129], v70 offset0:189 offset1:222
	ds_read_b64 v[132:133], v0 offset:8184
	v_pk_fma_f32 v[66:67], v[66:67], s[20:21], v[100:101] op_sel:[0,0,1] op_sel_hi:[1,0,0]
	v_pk_add_f32 v[100:101], v[68:69], v[102:103]
	v_pk_add_f32 v[68:69], v[68:69], v[102:103] neg_lo:[0,1] neg_hi:[0,1]
	v_mul_lo_u32 v105, v140, v105
	v_pk_mul_f32 v[102:103], v[68:69], s[14:15]
	v_cvt_f32_i32_e32 v105, v105
	v_pk_fma_f32 v[68:69], v[68:69], s[6:7], v[102:103] op_sel:[0,0,1] op_sel_hi:[1,0,0]
	s_waitcnt lgkmcnt(6)
	v_pk_add_f32 v[102:103], v[72:73], v[106:107]
	v_pk_add_f32 v[72:73], v[72:73], v[106:107] neg_lo:[0,1] neg_hi:[0,1]
	v_and_b32_e32 v71, 0xffffffe0, v71
	v_pk_mul_f32 v[106:107], v[72:73], s[52:53]
	v_cvt_f32_i32_e32 v71, v71
	v_pk_fma_f32 v[72:73], v[72:73], s[24:25], v[106:107] op_sel:[0,0,1] op_sel_hi:[1,0,0]
	v_pk_add_f32 v[106:107], v[74:75], v[108:109]
	v_pk_add_f32 v[74:75], v[74:75], v[108:109] neg_lo:[0,1] neg_hi:[0,1]
	v_mul_f32_e32 v71, 0x38800000, v71
	v_pk_mul_f32 v[108:109], v[74:75], s[10:11]
	s_nop 0
	v_pk_fma_f32 v[74:75], v[74:75], s[10:11], v[108:109] op_sel:[0,0,1] op_sel_hi:[1,0,0]
	s_waitcnt lgkmcnt(5)
	v_pk_add_f32 v[108:109], v[76:77], v[110:111]
	v_pk_add_f32 v[76:77], v[76:77], v[110:111] neg_lo:[0,1] neg_hi:[0,1]
	s_nop 0
	v_pk_mul_f32 v[110:111], v[76:77], s[24:25]
	s_nop 0
	v_pk_fma_f32 v[76:77], v[76:77], s[0:1], v[110:111] op_sel:[0,0,1] op_sel_hi:[1,0,0]
	v_pk_add_f32 v[110:111], v[78:79], v[112:113]
	v_pk_add_f32 v[78:79], v[78:79], v[112:113] neg_lo:[0,1] neg_hi:[0,1]
	s_nop 0
	v_pk_mul_f32 v[112:113], v[78:79], s[6:7]
	s_nop 0
	v_pk_fma_f32 v[78:79], v[78:79], s[14:15], v[112:113] op_sel:[0,0,1] op_sel_hi:[1,0,0]
	s_waitcnt lgkmcnt(4)
	v_pk_add_f32 v[112:113], v[80:81], v[114:115]
	v_pk_add_f32 v[80:81], v[80:81], v[114:115] neg_lo:[0,1] neg_hi:[0,1]
	s_nop 0
	v_pk_mul_f32 v[114:115], v[80:81], s[20:21]
	s_nop 0
	v_pk_fma_f32 v[80:81], v[80:81], s[48:49], v[114:115] op_sel:[0,0,1] op_sel_hi:[1,0,0]
	v_pk_add_f32 v[114:115], v[82:83], v[116:117]
	v_pk_add_f32 v[82:83], v[82:83], v[116:117] neg_lo:[0,1] neg_hi:[0,1]
	s_mov_b64 s[48:49], -1
	v_xor_b32_e32 v116, 0x80000000, v83
	v_mov_b32_e32 v117, v82
	s_waitcnt lgkmcnt(3)
	v_pk_add_f32 v[82:83], v[84:85], v[118:119]
	v_pk_add_f32 v[84:85], v[84:85], v[118:119] neg_lo:[0,1] neg_hi:[0,1]
	s_nop 0
	v_pk_mul_f32 v[118:119], v[84:85], s[20:21]
	s_nop 0
	v_pk_fma_f32 v[84:85], v[84:85], s[18:19], v[118:119] op_sel:[0,0,1] op_sel_hi:[1,0,0]
	v_pk_add_f32 v[118:119], v[86:87], v[120:121]
	v_pk_add_f32 v[86:87], v[86:87], v[120:121] neg_lo:[0,1] neg_hi:[0,1]
	s_nop 0
	v_pk_mul_f32 v[120:121], v[86:87], s[6:7]
	s_nop 0
	v_pk_fma_f32 v[86:87], v[86:87], s[4:5], v[120:121] op_sel:[0,0,1] op_sel_hi:[1,0,0]
	s_waitcnt lgkmcnt(2)
	v_pk_add_f32 v[120:121], v[88:89], v[122:123]
	v_pk_add_f32 v[88:89], v[88:89], v[122:123] neg_lo:[0,1] neg_hi:[0,1]
	s_nop 0
	v_pk_mul_f32 v[122:123], v[88:89], s[24:25]
	s_nop 0
	v_pk_fma_f32 v[88:89], v[88:89], s[22:23], v[122:123] op_sel:[0,0,1] op_sel_hi:[1,0,0]
	v_pk_add_f32 v[122:123], v[90:91], v[124:125]
	v_pk_add_f32 v[90:91], v[90:91], v[124:125] neg_lo:[0,1] neg_hi:[0,1]
	s_nop 0
	v_pk_mul_f32 v[124:125], v[90:91], s[10:11]
	s_nop 0
	v_pk_fma_f32 v[90:91], v[90:91], s[8:9], v[124:125] op_sel:[0,0,1] op_sel_hi:[1,0,0]
	s_waitcnt lgkmcnt(1)
	v_pk_add_f32 v[124:125], v[92:93], v[126:127]
	v_pk_add_f32 v[92:93], v[92:93], v[126:127] neg_lo:[0,1] neg_hi:[0,1]
	s_nop 0
	v_pk_mul_f32 v[126:127], v[92:93], s[52:53]
	s_nop 0
	v_pk_fma_f32 v[92:93], v[92:93], s[26:27], v[126:127] op_sel:[0,0,1] op_sel_hi:[1,0,0]
	v_pk_add_f32 v[126:127], v[94:95], v[128:129]
	v_pk_add_f32 v[94:95], v[94:95], v[128:129] neg_lo:[0,1] neg_hi:[0,1]
	s_nop 0
	v_pk_mul_f32 v[128:129], v[94:95], s[14:15]
	s_nop 0
	v_pk_fma_f32 v[94:95], v[94:95], s[12:13], v[128:129] op_sel:[0,0,1] op_sel_hi:[1,0,0]
	s_waitcnt lgkmcnt(0)
	v_pk_add_f32 v[128:129], v[96:97], v[132:133]
	v_pk_add_f32 v[96:97], v[96:97], v[132:133] neg_lo:[0,1] neg_hi:[0,1]
	s_nop 0
	v_pk_mul_f32 v[132:133], v[96:97], s[50:51]
	s_nop 0
	v_pk_fma_f32 v[96:97], v[96:97], s[34:35], v[132:133] op_sel:[0,0,1] op_sel_hi:[1,0,0]
	v_pk_add_f32 v[132:133], v[134:135], v[114:115]
	v_pk_add_f32 v[114:115], v[134:135], v[114:115] neg_lo:[0,1] neg_hi:[0,1]
	v_pk_add_f32 v[134:135], v[130:131], v[82:83]
	v_pk_add_f32 v[82:83], v[130:131], v[82:83] neg_lo:[0,1] neg_hi:[0,1]
	s_nop 0
	v_pk_mul_f32 v[130:131], v[82:83], s[14:15]
	s_nop 0
	v_pk_fma_f32 v[82:83], v[82:83], s[6:7], v[130:131] op_sel:[0,0,1] op_sel_hi:[1,0,0]
	v_pk_add_f32 v[130:131], v[100:101], v[118:119]
	v_pk_add_f32 v[100:101], v[100:101], v[118:119] neg_lo:[0,1] neg_hi:[0,1]
	s_nop 0
	v_pk_mul_f32 v[118:119], v[100:101], s[10:11]
	s_nop 0
	v_pk_fma_f32 v[100:101], v[100:101], s[10:11], v[118:119] op_sel:[0,0,1] op_sel_hi:[1,0,0]
	v_pk_add_f32 v[118:119], v[102:103], v[120:121]
	v_pk_add_f32 v[102:103], v[102:103], v[120:121] neg_lo:[0,1] neg_hi:[0,1]
	s_nop 0
	v_pk_mul_f32 v[120:121], v[102:103], s[6:7]
	s_nop 0
	v_pk_fma_f32 v[102:103], v[102:103], s[14:15], v[120:121] op_sel:[0,0,1] op_sel_hi:[1,0,0]
	v_pk_add_f32 v[120:121], v[106:107], v[122:123]
	v_pk_add_f32 v[106:107], v[106:107], v[122:123] neg_lo:[0,1] neg_hi:[0,1]
	s_nop 0
	v_xor_b32_e32 v122, 0x80000000, v107
	v_mov_b32_e32 v123, v106
	v_pk_add_f32 v[106:107], v[108:109], v[124:125]
	v_pk_add_f32 v[108:109], v[108:109], v[124:125] neg_lo:[0,1] neg_hi:[0,1]
	s_nop 0
	v_pk_mul_f32 v[124:125], v[108:109], s[6:7]
	s_nop 0
	v_pk_fma_f32 v[108:109], v[108:109], s[4:5], v[124:125] op_sel:[0,0,1] op_sel_hi:[1,0,0]
	v_pk_add_f32 v[124:125], v[110:111], v[126:127]
	v_pk_add_f32 v[110:111], v[110:111], v[126:127] neg_lo:[0,1] neg_hi:[0,1]
	s_nop 0
	v_pk_mul_f32 v[126:127], v[110:111], s[10:11]
	s_nop 0
	v_pk_fma_f32 v[110:111], v[110:111], s[8:9], v[126:127] op_sel:[0,0,1] op_sel_hi:[1,0,0]
	v_pk_add_f32 v[126:127], v[112:113], v[128:129]
	v_pk_add_f32 v[112:113], v[112:113], v[128:129] neg_lo:[0,1] neg_hi:[0,1]
	s_nop 0
	v_pk_mul_f32 v[128:129], v[112:113], s[14:15]
	s_nop 0
	v_pk_fma_f32 v[112:113], v[112:113], s[12:13], v[128:129] op_sel:[0,0,1] op_sel_hi:[1,0,0]
	v_pk_add_f32 v[128:129], v[98:99], v[116:117]
	v_pk_add_f32 v[98:99], v[98:99], v[116:117] neg_lo:[0,1] neg_hi:[0,1]
	v_pk_add_f32 v[116:117], v[66:67], v[84:85]
	v_pk_add_f32 v[66:67], v[66:67], v[84:85] neg_lo:[0,1] neg_hi:[0,1]
	s_nop 0
	v_pk_mul_f32 v[84:85], v[66:67], s[14:15]
	s_nop 0
	v_pk_fma_f32 v[66:67], v[66:67], s[6:7], v[84:85] op_sel:[0,0,1] op_sel_hi:[1,0,0]
	v_pk_add_f32 v[84:85], v[68:69], v[86:87]
	v_pk_add_f32 v[68:69], v[68:69], v[86:87] neg_lo:[0,1] neg_hi:[0,1]
	s_nop 0
	v_pk_mul_f32 v[86:87], v[68:69], s[10:11]
	s_nop 0
	v_pk_fma_f32 v[68:69], v[68:69], s[10:11], v[86:87] op_sel:[0,0,1] op_sel_hi:[1,0,0]
	v_pk_add_f32 v[86:87], v[72:73], v[88:89]
	v_pk_add_f32 v[72:73], v[72:73], v[88:89] neg_lo:[0,1] neg_hi:[0,1]
	s_nop 0
	v_pk_mul_f32 v[88:89], v[72:73], s[6:7]
	s_nop 0
	v_pk_fma_f32 v[72:73], v[72:73], s[14:15], v[88:89] op_sel:[0,0,1] op_sel_hi:[1,0,0]
	v_pk_add_f32 v[88:89], v[74:75], v[90:91]
	v_pk_add_f32 v[74:75], v[74:75], v[90:91] neg_lo:[0,1] neg_hi:[0,1]
	s_nop 0
	v_xor_b32_e32 v90, 0x80000000, v75
	v_mov_b32_e32 v91, v74
	v_pk_add_f32 v[74:75], v[76:77], v[92:93]
	v_pk_add_f32 v[76:77], v[76:77], v[92:93] neg_lo:[0,1] neg_hi:[0,1]
	s_nop 0
	v_pk_mul_f32 v[92:93], v[76:77], s[6:7]
	s_nop 0
	v_pk_fma_f32 v[76:77], v[76:77], s[4:5], v[92:93] op_sel:[0,0,1] op_sel_hi:[1,0,0]
	v_pk_add_f32 v[92:93], v[78:79], v[94:95]
	v_pk_add_f32 v[78:79], v[78:79], v[94:95] neg_lo:[0,1] neg_hi:[0,1]
	s_mov_b32 s5, 0
	v_pk_mul_f32 v[94:95], v[78:79], s[10:11]
	s_nop 0
	v_pk_fma_f32 v[78:79], v[78:79], s[8:9], v[94:95] op_sel:[0,0,1] op_sel_hi:[1,0,0]
	v_pk_add_f32 v[94:95], v[80:81], v[96:97]
	v_pk_add_f32 v[80:81], v[80:81], v[96:97] neg_lo:[0,1] neg_hi:[0,1]
	s_nop 0
	v_pk_mul_f32 v[96:97], v[80:81], s[14:15]
	s_nop 0
	v_pk_fma_f32 v[80:81], v[80:81], s[12:13], v[96:97] op_sel:[0,0,1] op_sel_hi:[1,0,0]
	v_pk_add_f32 v[96:97], v[132:133], v[120:121]
	v_pk_add_f32 v[120:121], v[132:133], v[120:121] neg_lo:[0,1] neg_hi:[0,1]
	v_pk_add_f32 v[132:133], v[134:135], v[106:107]
	v_pk_add_f32 v[106:107], v[134:135], v[106:107] neg_lo:[0,1] neg_hi:[0,1]
	s_nop 0
	v_pk_mul_f32 v[134:135], v[106:107], s[10:11]
	s_nop 0
	v_pk_fma_f32 v[106:107], v[106:107], s[10:11], v[134:135] op_sel:[0,0,1] op_sel_hi:[1,0,0]
	v_pk_add_f32 v[134:135], v[130:131], v[124:125]
	v_pk_add_f32 v[124:125], v[130:131], v[124:125] neg_lo:[0,1] neg_hi:[0,1]
	s_nop 0
	v_xor_b32_e32 v130, 0x80000000, v125
	v_mov_b32_e32 v131, v124
	v_pk_add_f32 v[124:125], v[118:119], v[126:127]
	v_pk_add_f32 v[118:119], v[118:119], v[126:127] neg_lo:[0,1] neg_hi:[0,1]
	s_nop 0
	v_pk_mul_f32 v[126:127], v[118:119], s[10:11]
	s_nop 0
	v_pk_fma_f32 v[118:119], v[118:119], s[8:9], v[126:127] op_sel:[0,0,1] op_sel_hi:[1,0,0]
	v_pk_add_f32 v[126:127], v[114:115], v[122:123]
	v_pk_add_f32 v[114:115], v[114:115], v[122:123] neg_lo:[0,1] neg_hi:[0,1]
	v_pk_add_f32 v[122:123], v[82:83], v[108:109]
	v_pk_add_f32 v[82:83], v[82:83], v[108:109] neg_lo:[0,1] neg_hi:[0,1]
	s_nop 0
	v_pk_mul_f32 v[108:109], v[82:83], s[10:11]
	s_nop 0
	v_pk_fma_f32 v[82:83], v[82:83], s[10:11], v[108:109] op_sel:[0,0,1] op_sel_hi:[1,0,0]
	v_pk_add_f32 v[108:109], v[100:101], v[110:111]
	v_pk_add_f32 v[100:101], v[100:101], v[110:111] neg_lo:[0,1] neg_hi:[0,1]
	s_nop 0
	v_xor_b32_e32 v110, 0x80000000, v101
	v_mov_b32_e32 v111, v100
	v_pk_add_f32 v[100:101], v[102:103], v[112:113]
	v_pk_add_f32 v[102:103], v[102:103], v[112:113] neg_lo:[0,1] neg_hi:[0,1]
	s_nop 0
	v_pk_mul_f32 v[112:113], v[102:103], s[10:11]
	s_nop 0
	v_pk_fma_f32 v[102:103], v[102:103], s[8:9], v[112:113] op_sel:[0,0,1] op_sel_hi:[1,0,0]
	v_pk_add_f32 v[112:113], v[128:129], v[88:89]
	v_pk_add_f32 v[88:89], v[128:129], v[88:89] neg_lo:[0,1] neg_hi:[0,1]
	v_pk_add_f32 v[128:129], v[116:117], v[74:75]
	v_pk_add_f32 v[74:75], v[116:117], v[74:75] neg_lo:[0,1] neg_hi:[0,1]
	s_nop 0
	v_pk_mul_f32 v[116:117], v[74:75], s[10:11]
	s_nop 0
	v_pk_fma_f32 v[74:75], v[74:75], s[10:11], v[116:117] op_sel:[0,0,1] op_sel_hi:[1,0,0]
	v_pk_add_f32 v[116:117], v[84:85], v[92:93]
	v_pk_add_f32 v[84:85], v[84:85], v[92:93] neg_lo:[0,1] neg_hi:[0,1]
	s_nop 0
	v_xor_b32_e32 v92, 0x80000000, v85
	v_mov_b32_e32 v93, v84
	v_pk_add_f32 v[84:85], v[86:87], v[94:95]
	v_pk_add_f32 v[86:87], v[86:87], v[94:95] neg_lo:[0,1] neg_hi:[0,1]
	s_nop 0
	v_pk_mul_f32 v[94:95], v[86:87], s[10:11]
	s_nop 0
	v_pk_fma_f32 v[86:87], v[86:87], s[8:9], v[94:95] op_sel:[0,0,1] op_sel_hi:[1,0,0]
	v_pk_add_f32 v[94:95], v[98:99], v[90:91]
	v_pk_add_f32 v[90:91], v[98:99], v[90:91] neg_lo:[0,1] neg_hi:[0,1]
	v_pk_add_f32 v[98:99], v[66:67], v[76:77]
	v_pk_add_f32 v[66:67], v[66:67], v[76:77] neg_lo:[0,1] neg_hi:[0,1]
	s_nop 0
	v_pk_mul_f32 v[76:77], v[66:67], s[10:11]
	s_nop 0
	v_pk_fma_f32 v[66:67], v[66:67], s[10:11], v[76:77] op_sel:[0,0,1] op_sel_hi:[1,0,0]
	v_pk_add_f32 v[76:77], v[68:69], v[78:79]
	v_pk_add_f32 v[68:69], v[68:69], v[78:79] neg_lo:[0,1] neg_hi:[0,1]
	s_nop 0
	v_xor_b32_e32 v78, 0x80000000, v69
	v_mov_b32_e32 v79, v68
	v_pk_add_f32 v[68:69], v[72:73], v[80:81]
	v_pk_add_f32 v[72:73], v[72:73], v[80:81] neg_lo:[0,1] neg_hi:[0,1]
	v_pk_add_f32 v[136:137], v[90:91], v[78:79]
	v_pk_mul_f32 v[80:81], v[72:73], s[10:11]
	v_pk_add_f32 v[78:79], v[90:91], v[78:79] neg_lo:[0,1] neg_hi:[0,1]
	v_pk_fma_f32 v[72:73], v[72:73], s[8:9], v[80:81] op_sel:[0,0,1] op_sel_hi:[1,0,0]
	v_pk_add_f32 v[80:81], v[96:97], v[134:135]
	v_pk_add_f32 v[96:97], v[96:97], v[134:135] neg_lo:[0,1] neg_hi:[0,1]
	v_pk_add_f32 v[134:135], v[132:133], v[124:125]
	v_pk_add_f32 v[124:125], v[132:133], v[124:125] neg_lo:[0,1] neg_hi:[0,1]
	v_pk_add_f32 v[90:91], v[66:67], v[72:73]
	v_xor_b32_e32 v132, 0x80000000, v125
	v_mov_b32_e32 v133, v124
	v_pk_add_f32 v[124:125], v[120:121], v[130:131]
	v_pk_add_f32 v[120:121], v[120:121], v[130:131] neg_lo:[0,1] neg_hi:[0,1]
	v_pk_add_f32 v[130:131], v[106:107], v[118:119]
	v_pk_add_f32 v[106:107], v[106:107], v[118:119] neg_lo:[0,1] neg_hi:[0,1]
	v_pk_add_f32 v[66:67], v[66:67], v[72:73] neg_lo:[0,1] neg_hi:[0,1]
	v_xor_b32_e32 v118, 0x80000000, v107
	v_mov_b32_e32 v119, v106
	v_pk_add_f32 v[106:107], v[126:127], v[108:109]
	v_pk_add_f32 v[108:109], v[126:127], v[108:109] neg_lo:[0,1] neg_hi:[0,1]
	v_pk_add_f32 v[126:127], v[122:123], v[100:101]
	v_pk_add_f32 v[100:101], v[122:123], v[100:101] neg_lo:[0,1] neg_hi:[0,1]
	v_xor_b32_e32 v72, 0x80000000, v67
	v_xor_b32_e32 v122, 0x80000000, v101
	v_mov_b32_e32 v123, v100
	v_pk_add_f32 v[100:101], v[114:115], v[110:111]
	v_pk_add_f32 v[110:111], v[114:115], v[110:111] neg_lo:[0,1] neg_hi:[0,1]
	v_pk_add_f32 v[114:115], v[82:83], v[102:103]
	v_pk_add_f32 v[82:83], v[82:83], v[102:103] neg_lo:[0,1] neg_hi:[0,1]
	v_mov_b32_e32 v73, v66
	v_xor_b32_e32 v102, 0x80000000, v83
	v_mov_b32_e32 v103, v82
	v_pk_add_f32 v[82:83], v[112:113], v[116:117]
	v_pk_add_f32 v[112:113], v[112:113], v[116:117] neg_lo:[0,1] neg_hi:[0,1]
	v_pk_add_f32 v[116:117], v[128:129], v[84:85]
	v_pk_add_f32 v[84:85], v[128:129], v[84:85] neg_lo:[0,1] neg_hi:[0,1]
	v_pk_add_f32 v[138:139], v[80:81], v[134:135]
	v_xor_b32_e32 v128, 0x80000000, v85
	v_mov_b32_e32 v129, v84
	v_pk_add_f32 v[84:85], v[88:89], v[92:93]
	v_pk_add_f32 v[88:89], v[88:89], v[92:93] neg_lo:[0,1] neg_hi:[0,1]
	v_pk_add_f32 v[92:93], v[74:75], v[86:87]
	v_pk_add_f32 v[74:75], v[74:75], v[86:87] neg_lo:[0,1] neg_hi:[0,1]
	v_pk_add_f32 v[80:81], v[80:81], v[134:135] neg_lo:[0,1] neg_hi:[0,1]
	v_xor_b32_e32 v86, 0x80000000, v75
	v_mov_b32_e32 v87, v74
	v_pk_add_f32 v[74:75], v[94:95], v[76:77]
	v_pk_add_f32 v[76:77], v[94:95], v[76:77] neg_lo:[0,1] neg_hi:[0,1]
	v_pk_add_f32 v[94:95], v[98:99], v[68:69]
	v_pk_add_f32 v[68:69], v[98:99], v[68:69] neg_lo:[0,1] neg_hi:[0,1]
	v_pk_add_f32 v[134:135], v[96:97], v[132:133]
	v_xor_b32_e32 v98, 0x80000000, v69
	v_mov_b32_e32 v99, v68
	v_pk_add_f32 v[96:97], v[96:97], v[132:133] neg_lo:[0,1] neg_hi:[0,1]
	v_pk_add_f32 v[132:133], v[124:125], v[130:131]
	v_pk_add_f32 v[124:125], v[124:125], v[130:131] neg_lo:[0,1] neg_hi:[0,1]
	v_pk_add_f32 v[130:131], v[120:121], v[118:119]
	v_pk_add_f32 v[68:69], v[120:121], v[118:119] neg_lo:[0,1] neg_hi:[0,1]
	v_pk_add_f32 v[118:119], v[106:107], v[126:127]
	v_pk_add_f32 v[106:107], v[106:107], v[126:127] neg_lo:[0,1] neg_hi:[0,1]
	v_pk_add_f32 v[126:127], v[78:79], v[72:73]
	v_pk_add_f32 v[72:73], v[78:79], v[72:73] neg_lo:[0,1] neg_hi:[0,1]
	v_mul_f32_e32 v78, 0x38800000, v105
	v_sin_f32_e32 v79, v78
	v_cos_f32_e32 v78, v78
	v_pk_add_f32 v[120:121], v[108:109], v[122:123]
	v_pk_add_f32 v[108:109], v[108:109], v[122:123] neg_lo:[0,1] neg_hi:[0,1]
	v_pk_add_f32 v[122:123], v[100:101], v[114:115]
	v_pk_add_f32 v[100:101], v[100:101], v[114:115] neg_lo:[0,1] neg_hi:[0,1]
	v_pk_add_f32 v[114:115], v[110:111], v[102:103]
	v_pk_add_f32 v[66:67], v[110:111], v[102:103] neg_lo:[0,1] neg_hi:[0,1]
	v_pk_add_f32 v[102:103], v[82:83], v[116:117]
	v_pk_add_f32 v[82:83], v[82:83], v[116:117] neg_lo:[0,1] neg_hi:[0,1]
	v_pk_add_f32 v[116:117], v[84:85], v[92:93]
	v_pk_add_f32 v[84:85], v[84:85], v[92:93] neg_lo:[0,1] neg_hi:[0,1]
	v_pk_add_f32 v[92:93], v[88:89], v[86:87]
	v_pk_add_f32 v[86:87], v[88:89], v[86:87] neg_lo:[0,1] neg_hi:[0,1]
	v_pk_add_f32 v[88:89], v[74:75], v[94:95]
	v_pk_add_f32 v[74:75], v[74:75], v[94:95] neg_lo:[0,1] neg_hi:[0,1]
	v_pk_add_f32 v[94:95], v[76:77], v[98:99]
	v_pk_add_f32 v[76:77], v[76:77], v[98:99] neg_lo:[0,1] neg_hi:[0,1]
	v_pk_add_f32 v[98:99], v[136:137], v[90:91]
	v_pk_add_f32 v[90:91], v[136:137], v[90:91] neg_lo:[0,1] neg_hi:[0,1]
	v_sin_f32_e32 v136, v71
	v_pk_add_f32 v[110:111], v[112:113], v[128:129]
	v_pk_add_f32 v[112:113], v[112:113], v[128:129] neg_lo:[0,1] neg_hi:[0,1]
	v_cos_f32_e32 v128, v71
	v_xor_b32_e32 v140, 0x80000000, v79
	v_mov_b32_e32 v141, v79
	v_pk_mul_f32 v[140:141], v[140:141], v[138:139] op_sel:[0,1] op_sel_hi:[1,0]
	s_nop 0
	v_pk_fma_f32 v[138:139], v[138:139], v[78:79], v[140:141] op_sel_hi:[1,0,1]
	ds_write_b64 v142, v[138:139]
	v_pk_mul_f32 v[138:139], v[136:137], v[78:79] op_sel:[0,1] op_sel_hi:[0,0] neg_lo:[1,0]
	v_pk_fma_f32 v[78:79], v[78:79], v[128:129], v[138:139] op_sel_hi:[1,0,1]
	s_nop 0
	v_xor_b32_e32 v138, 0x80000000, v79
	v_mov_b32_e32 v139, v79
	v_pk_mul_f32 v[138:139], v[138:139], v[102:103] op_sel:[0,1] op_sel_hi:[1,0]
	s_nop 0
	v_pk_fma_f32 v[102:103], v[102:103], v[78:79], v[138:139] op_sel_hi:[1,0,1]
	v_pk_mul_f32 v[138:139], v[136:137], v[78:79] op_sel:[0,1] op_sel_hi:[0,0] neg_lo:[1,0]
	v_pk_fma_f32 v[78:79], v[78:79], v[128:129], v[138:139] op_sel_hi:[1,0,1]
	s_nop 0
	v_xor_b32_e32 v138, 0x80000000, v79
	v_mov_b32_e32 v139, v79
	v_pk_mul_f32 v[138:139], v[138:139], v[118:119] op_sel:[0,1] op_sel_hi:[1,0]
	s_nop 0
	v_pk_fma_f32 v[118:119], v[118:119], v[78:79], v[138:139] op_sel_hi:[1,0,1]
	ds_write2_b64 v0, v[102:103], v[118:119] offset0:33 offset1:66
	v_pk_mul_f32 v[102:103], v[136:137], v[78:79] op_sel:[0,1] op_sel_hi:[0,0] neg_lo:[1,0]
	v_pk_fma_f32 v[78:79], v[78:79], v[128:129], v[102:103] op_sel_hi:[1,0,1]
	s_nop 0
	v_xor_b32_e32 v102, 0x80000000, v79
	v_mov_b32_e32 v103, v79
	v_pk_mul_f32 v[102:103], v[102:103], v[88:89] op_sel:[0,1] op_sel_hi:[1,0]
	s_nop 0
	v_pk_fma_f32 v[88:89], v[88:89], v[78:79], v[102:103] op_sel_hi:[1,0,1]
	v_pk_mul_f32 v[102:103], v[136:137], v[78:79] op_sel:[0,1] op_sel_hi:[0,0] neg_lo:[1,0]
	v_pk_fma_f32 v[78:79], v[78:79], v[128:129], v[102:103] op_sel_hi:[1,0,1]
	s_nop 0
	v_xor_b32_e32 v102, 0x80000000, v79
	v_mov_b32_e32 v103, v79
	v_pk_mul_f32 v[102:103], v[102:103], v[132:133] op_sel:[0,1] op_sel_hi:[1,0]
	s_nop 0
	v_pk_fma_f32 v[102:103], v[132:133], v[78:79], v[102:103] op_sel_hi:[1,0,1]
	ds_write2_b64 v0, v[88:89], v[102:103] offset0:99 offset1:132
	v_pk_mul_f32 v[88:89], v[136:137], v[78:79] op_sel:[0,1] op_sel_hi:[0,0] neg_lo:[1,0]
	v_pk_fma_f32 v[78:79], v[78:79], v[128:129], v[88:89] op_sel_hi:[1,0,1]
	s_nop 0
	v_xor_b32_e32 v88, 0x80000000, v79
	v_mov_b32_e32 v89, v79
	v_pk_mul_f32 v[88:89], v[88:89], v[116:117] op_sel:[0,1] op_sel_hi:[1,0]
	v_pk_mul_f32 v[102:103], v[136:137], v[78:79] op_sel:[0,1] op_sel_hi:[0,0] neg_lo:[1,0]
	v_pk_fma_f32 v[88:89], v[116:117], v[78:79], v[88:89] op_sel_hi:[1,0,1]
	v_pk_fma_f32 v[78:79], v[78:79], v[128:129], v[102:103] op_sel_hi:[1,0,1]
	s_nop 0
	v_xor_b32_e32 v102, 0x80000000, v79
	v_mov_b32_e32 v103, v79
	v_pk_mul_f32 v[102:103], v[102:103], v[122:123] op_sel:[0,1] op_sel_hi:[1,0]
	s_nop 0
	v_pk_fma_f32 v[102:103], v[122:123], v[78:79], v[102:103] op_sel_hi:[1,0,1]
	ds_write2_b64 v0, v[88:89], v[102:103] offset0:165 offset1:198
	v_pk_mul_f32 v[88:89], v[136:137], v[78:79] op_sel:[0,1] op_sel_hi:[0,0] neg_lo:[1,0]
	v_pk_fma_f32 v[78:79], v[78:79], v[128:129], v[88:89] op_sel_hi:[1,0,1]
	s_nop 0
	v_xor_b32_e32 v88, 0x80000000, v79
	v_mov_b32_e32 v89, v79
	v_pk_mul_f32 v[88:89], v[88:89], v[98:99] op_sel:[0,1] op_sel_hi:[1,0]
	s_nop 0
	v_pk_fma_f32 v[88:89], v[98:99], v[78:79], v[88:89] op_sel_hi:[1,0,1]
	v_pk_mul_f32 v[98:99], v[136:137], v[78:79] op_sel:[0,1] op_sel_hi:[0,0] neg_lo:[1,0]
	v_pk_fma_f32 v[78:79], v[78:79], v[128:129], v[98:99] op_sel_hi:[1,0,1]
	s_nop 0
	v_xor_b32_e32 v98, 0x80000000, v79
	v_mov_b32_e32 v99, v79
	v_pk_mul_f32 v[98:99], v[98:99], v[134:135] op_sel:[0,1] op_sel_hi:[1,0]
	s_nop 0
	v_pk_fma_f32 v[98:99], v[134:135], v[78:79], v[98:99] op_sel_hi:[1,0,1]
	ds_write2_b64 v143, v[88:89], v[98:99] offset0:103 offset1:136
	v_pk_mul_f32 v[88:89], v[136:137], v[78:79] op_sel:[0,1] op_sel_hi:[0,0] neg_lo:[1,0]
	v_pk_fma_f32 v[78:79], v[78:79], v[128:129], v[88:89] op_sel_hi:[1,0,1]
	s_nop 0
	v_xor_b32_e32 v88, 0x80000000, v79
	v_mov_b32_e32 v89, v79
	v_pk_mul_f32 v[88:89], v[88:89], v[110:111] op_sel:[0,1] op_sel_hi:[1,0]
	v_pk_mul_f32 v[98:99], v[136:137], v[78:79] op_sel:[0,1] op_sel_hi:[0,0] neg_lo:[1,0]
	v_pk_fma_f32 v[88:89], v[110:111], v[78:79], v[88:89] op_sel_hi:[1,0,1]
	v_pk_fma_f32 v[78:79], v[78:79], v[128:129], v[98:99] op_sel_hi:[1,0,1]
	s_nop 0
	v_xor_b32_e32 v98, 0x80000000, v79
	v_mov_b32_e32 v99, v79
	v_pk_mul_f32 v[98:99], v[98:99], v[120:121] op_sel:[0,1] op_sel_hi:[1,0]
	s_nop 0
	v_pk_fma_f32 v[98:99], v[120:121], v[78:79], v[98:99] op_sel_hi:[1,0,1]
	ds_write2_b64 v144, v[88:89], v[98:99] offset0:41 offset1:74
	v_pk_mul_f32 v[88:89], v[136:137], v[78:79] op_sel:[0,1] op_sel_hi:[0,0] neg_lo:[1,0]
	v_pk_fma_f32 v[78:79], v[78:79], v[128:129], v[88:89] op_sel_hi:[1,0,1]
	s_nop 0
	v_xor_b32_e32 v88, 0x80000000, v79
	v_mov_b32_e32 v89, v79
	v_pk_mul_f32 v[88:89], v[88:89], v[94:95] op_sel:[0,1] op_sel_hi:[1,0]
	s_nop 0
	v_pk_fma_f32 v[88:89], v[94:95], v[78:79], v[88:89] op_sel_hi:[1,0,1]
	v_pk_mul_f32 v[94:95], v[136:137], v[78:79] op_sel:[0,1] op_sel_hi:[0,0] neg_lo:[1,0]
	v_pk_fma_f32 v[78:79], v[78:79], v[128:129], v[94:95] op_sel_hi:[1,0,1]
	s_nop 0
	v_xor_b32_e32 v94, 0x80000000, v79
	v_mov_b32_e32 v95, v79
	v_pk_mul_f32 v[94:95], v[130:131], v[94:95] op_sel:[1,0] op_sel_hi:[0,1]
	v_pk_fma_f32 v[94:95], v[130:131], v[78:79], v[94:95] op_sel_hi:[1,0,1]
	ds_write2_b64 v144, v[88:89], v[94:95] offset0:107 offset1:140
	v_pk_mul_f32 v[88:89], v[136:137], v[78:79] op_sel:[0,1] op_sel_hi:[0,0] neg_lo:[1,0]
	v_pk_fma_f32 v[78:79], v[78:79], v[128:129], v[88:89] op_sel_hi:[1,0,1]
	s_nop 0
	v_xor_b32_e32 v88, 0x80000000, v79
	v_mov_b32_e32 v89, v79
	v_pk_mul_f32 v[88:89], v[92:93], v[88:89] op_sel:[1,0] op_sel_hi:[0,1]
	v_pk_fma_f32 v[88:89], v[92:93], v[78:79], v[88:89] op_sel_hi:[1,0,1]
	v_pk_mul_f32 v[92:93], v[136:137], v[78:79] op_sel:[0,1] op_sel_hi:[0,0] neg_lo:[1,0]
	v_pk_fma_f32 v[78:79], v[78:79], v[128:129], v[92:93] op_sel_hi:[1,0,1]
	s_nop 0
	v_xor_b32_e32 v92, 0x80000000, v79
	v_mov_b32_e32 v93, v79
	v_pk_mul_f32 v[92:93], v[114:115], v[92:93] op_sel:[1,0] op_sel_hi:[0,1]
	v_pk_fma_f32 v[92:93], v[114:115], v[78:79], v[92:93] op_sel_hi:[1,0,1]
	ds_write2_b64 v144, v[88:89], v[92:93] offset0:173 offset1:206
	v_pk_mul_f32 v[88:89], v[136:137], v[78:79] op_sel:[0,1] op_sel_hi:[0,0] neg_lo:[1,0]
	v_pk_fma_f32 v[78:79], v[78:79], v[128:129], v[88:89] op_sel_hi:[1,0,1]
	s_nop 0
	v_xor_b32_e32 v88, 0x80000000, v79
	v_mov_b32_e32 v89, v79
	v_pk_mul_f32 v[88:89], v[126:127], v[88:89] op_sel:[1,0] op_sel_hi:[0,1]
	v_pk_mul_f32 v[92:93], v[136:137], v[78:79] op_sel:[0,1] op_sel_hi:[0,0] neg_lo:[1,0]
	v_pk_fma_f32 v[88:89], v[126:127], v[78:79], v[88:89] op_sel_hi:[1,0,1]
	v_pk_fma_f32 v[78:79], v[78:79], v[128:129], v[92:93] op_sel_hi:[1,0,1]
	s_nop 0
	v_xor_b32_e32 v92, 0x80000000, v79
	v_mov_b32_e32 v93, v79
	v_pk_mul_f32 v[92:93], v[80:81], v[92:93] op_sel:[1,0] op_sel_hi:[0,1]
	v_pk_fma_f32 v[80:81], v[80:81], v[78:79], v[92:93] op_sel_hi:[1,0,1]
	ds_write2_b64 v145, v[88:89], v[80:81] offset0:111 offset1:144
	v_pk_mul_f32 v[80:81], v[136:137], v[78:79] op_sel:[0,1] op_sel_hi:[0,0] neg_lo:[1,0]
	v_pk_fma_f32 v[78:79], v[78:79], v[128:129], v[80:81] op_sel_hi:[1,0,1]
	s_nop 0
	v_xor_b32_e32 v80, 0x80000000, v79
	v_mov_b32_e32 v81, v79
	v_pk_mul_f32 v[80:81], v[82:83], v[80:81] op_sel:[1,0] op_sel_hi:[0,1]
	v_pk_fma_f32 v[80:81], v[82:83], v[78:79], v[80:81] op_sel_hi:[1,0,1]
	v_pk_mul_f32 v[82:83], v[136:137], v[78:79] op_sel:[0,1] op_sel_hi:[0,0] neg_lo:[1,0]
	v_pk_fma_f32 v[78:79], v[78:79], v[128:129], v[82:83] op_sel_hi:[1,0,1]
	s_nop 0
	v_xor_b32_e32 v82, 0x80000000, v79
	v_mov_b32_e32 v83, v79
	v_pk_mul_f32 v[82:83], v[106:107], v[82:83] op_sel:[1,0] op_sel_hi:[0,1]
	v_pk_fma_f32 v[82:83], v[106:107], v[78:79], v[82:83] op_sel_hi:[1,0,1]
	ds_write2_b64 v146, v[80:81], v[82:83] offset0:49 offset1:82
	v_pk_mul_f32 v[80:81], v[136:137], v[78:79] op_sel:[0,1] op_sel_hi:[0,0] neg_lo:[1,0]
	v_pk_fma_f32 v[78:79], v[78:79], v[128:129], v[80:81] op_sel_hi:[1,0,1]
	s_nop 0
	v_xor_b32_e32 v80, 0x80000000, v79
	v_mov_b32_e32 v81, v79
	v_pk_mul_f32 v[80:81], v[74:75], v[80:81] op_sel:[1,0] op_sel_hi:[0,1]
	v_pk_fma_f32 v[74:75], v[74:75], v[78:79], v[80:81] op_sel_hi:[1,0,1]
	v_pk_mul_f32 v[80:81], v[136:137], v[78:79] op_sel:[0,1] op_sel_hi:[0,0] neg_lo:[1,0]
	v_pk_fma_f32 v[78:79], v[78:79], v[128:129], v[80:81] op_sel_hi:[1,0,1]
	s_nop 0
	v_xor_b32_e32 v80, 0x80000000, v79
	v_mov_b32_e32 v81, v79
	v_pk_mul_f32 v[80:81], v[124:125], v[80:81] op_sel:[1,0] op_sel_hi:[0,1]
	v_pk_fma_f32 v[80:81], v[124:125], v[78:79], v[80:81] op_sel_hi:[1,0,1]
	ds_write2_b64 v146, v[74:75], v[80:81] offset0:115 offset1:148
	v_pk_mul_f32 v[74:75], v[136:137], v[78:79] op_sel:[0,1] op_sel_hi:[0,0] neg_lo:[1,0]
	v_pk_fma_f32 v[74:75], v[78:79], v[128:129], v[74:75] op_sel_hi:[1,0,1]
	s_nop 0
	v_xor_b32_e32 v78, 0x80000000, v75
	v_mov_b32_e32 v79, v75
	v_pk_mul_f32 v[78:79], v[84:85], v[78:79] op_sel:[1,0] op_sel_hi:[0,1]
	v_pk_mul_f32 v[80:81], v[136:137], v[74:75] op_sel:[0,1] op_sel_hi:[0,0] neg_lo:[1,0]
	v_pk_fma_f32 v[78:79], v[84:85], v[74:75], v[78:79] op_sel_hi:[1,0,1]
	v_pk_fma_f32 v[74:75], v[74:75], v[128:129], v[80:81] op_sel_hi:[1,0,1]
	s_nop 0
	v_xor_b32_e32 v80, 0x80000000, v75
	v_mov_b32_e32 v81, v75
	v_pk_mul_f32 v[80:81], v[100:101], v[80:81] op_sel:[1,0] op_sel_hi:[0,1]
	v_pk_fma_f32 v[80:81], v[100:101], v[74:75], v[80:81] op_sel_hi:[1,0,1]
	ds_write2_b64 v146, v[78:79], v[80:81] offset0:181 offset1:214
	v_pk_mul_f32 v[78:79], v[136:137], v[74:75] op_sel:[0,1] op_sel_hi:[0,0] neg_lo:[1,0]
	v_pk_fma_f32 v[74:75], v[74:75], v[128:129], v[78:79] op_sel_hi:[1,0,1]
	s_nop 0
	v_xor_b32_e32 v78, 0x80000000, v75
	v_mov_b32_e32 v79, v75
	v_pk_mul_f32 v[78:79], v[90:91], v[78:79] op_sel:[1,0] op_sel_hi:[0,1]
	v_pk_mul_f32 v[80:81], v[136:137], v[74:75] op_sel:[0,1] op_sel_hi:[0,0] neg_lo:[1,0]
	v_pk_fma_f32 v[78:79], v[90:91], v[74:75], v[78:79] op_sel_hi:[1,0,1]
	v_pk_fma_f32 v[74:75], v[74:75], v[128:129], v[80:81] op_sel_hi:[1,0,1]
	s_nop 0
	v_xor_b32_e32 v80, 0x80000000, v75
	v_mov_b32_e32 v81, v75
	v_pk_mul_f32 v[80:81], v[96:97], v[80:81] op_sel:[1,0] op_sel_hi:[0,1]
	v_pk_fma_f32 v[80:81], v[96:97], v[74:75], v[80:81] op_sel_hi:[1,0,1]
	ds_write2_b64 v147, v[78:79], v[80:81] offset0:119 offset1:152
	v_pk_mul_f32 v[78:79], v[136:137], v[74:75] op_sel:[0,1] op_sel_hi:[0,0] neg_lo:[1,0]
	v_pk_fma_f32 v[74:75], v[74:75], v[128:129], v[78:79] op_sel_hi:[1,0,1]
	s_nop 0
	v_xor_b32_e32 v78, 0x80000000, v75
	v_mov_b32_e32 v79, v75
	v_pk_mul_f32 v[78:79], v[112:113], v[78:79] op_sel:[1,0] op_sel_hi:[0,1]
	v_pk_mul_f32 v[80:81], v[136:137], v[74:75] op_sel:[0,1] op_sel_hi:[0,0] neg_lo:[1,0]
	v_pk_fma_f32 v[78:79], v[112:113], v[74:75], v[78:79] op_sel_hi:[1,0,1]
	v_pk_fma_f32 v[74:75], v[74:75], v[128:129], v[80:81] op_sel_hi:[1,0,1]
	s_nop 0
	v_xor_b32_e32 v80, 0x80000000, v75
	v_mov_b32_e32 v81, v75
	v_pk_mul_f32 v[80:81], v[108:109], v[80:81] op_sel:[1,0] op_sel_hi:[0,1]
	v_pk_fma_f32 v[80:81], v[108:109], v[74:75], v[80:81] op_sel_hi:[1,0,1]
	ds_write2_b64 v70, v[78:79], v[80:81] offset0:57 offset1:90
	v_pk_mul_f32 v[78:79], v[136:137], v[74:75] op_sel:[0,1] op_sel_hi:[0,0] neg_lo:[1,0]
	v_pk_fma_f32 v[74:75], v[74:75], v[128:129], v[78:79] op_sel_hi:[1,0,1]
	s_nop 0
	v_xor_b32_e32 v78, 0x80000000, v75
	v_mov_b32_e32 v79, v75
	v_pk_mul_f32 v[78:79], v[76:77], v[78:79] op_sel:[1,0] op_sel_hi:[0,1]
	v_pk_fma_f32 v[76:77], v[76:77], v[74:75], v[78:79] op_sel_hi:[1,0,1]
	v_pk_mul_f32 v[78:79], v[136:137], v[74:75] op_sel:[0,1] op_sel_hi:[0,0] neg_lo:[1,0]
	v_pk_fma_f32 v[74:75], v[74:75], v[128:129], v[78:79] op_sel_hi:[1,0,1]
	s_nop 0
	v_xor_b32_e32 v78, 0x80000000, v75
	v_mov_b32_e32 v79, v75
	v_pk_mul_f32 v[78:79], v[68:69], v[78:79] op_sel:[1,0] op_sel_hi:[0,1]
	v_pk_fma_f32 v[68:69], v[68:69], v[74:75], v[78:79] op_sel_hi:[1,0,1]
	ds_write2_b64 v70, v[76:77], v[68:69] offset0:123 offset1:156
	v_pk_mul_f32 v[68:69], v[136:137], v[74:75] op_sel:[0,1] op_sel_hi:[0,0] neg_lo:[1,0]
	v_pk_fma_f32 v[68:69], v[74:75], v[128:129], v[68:69] op_sel_hi:[1,0,1]
	s_nop 0
	v_xor_b32_e32 v74, 0x80000000, v69
	v_mov_b32_e32 v75, v69
	v_pk_mul_f32 v[74:75], v[86:87], v[74:75] op_sel:[1,0] op_sel_hi:[0,1]
	v_pk_mul_f32 v[76:77], v[136:137], v[68:69] op_sel:[0,1] op_sel_hi:[0,0] neg_lo:[1,0]
	v_pk_fma_f32 v[74:75], v[86:87], v[68:69], v[74:75] op_sel_hi:[1,0,1]
	v_pk_fma_f32 v[68:69], v[68:69], v[128:129], v[76:77] op_sel_hi:[1,0,1]
	s_nop 0
	v_xor_b32_e32 v76, 0x80000000, v69
	v_mov_b32_e32 v77, v69
	v_pk_mul_f32 v[76:77], v[66:67], v[76:77] op_sel:[1,0] op_sel_hi:[0,1]
	v_pk_fma_f32 v[66:67], v[66:67], v[68:69], v[76:77] op_sel_hi:[1,0,1]
	ds_write2_b64 v70, v[74:75], v[66:67] offset0:189 offset1:222
	v_pk_mul_f32 v[66:67], v[136:137], v[68:69] op_sel:[0,1] op_sel_hi:[0,0] neg_lo:[1,0]
	v_pk_fma_f32 v[66:67], v[68:69], v[128:129], v[66:67] op_sel_hi:[1,0,1]
	s_nop 0
	v_xor_b32_e32 v68, 0x80000000, v67
	v_mov_b32_e32 v69, v67
	v_pk_mul_f32 v[68:69], v[72:73], v[68:69] op_sel:[1,0] op_sel_hi:[0,1]
	v_pk_fma_f32 v[66:67], v[72:73], v[66:67], v[68:69] op_sel_hi:[1,0,1]
	ds_write_b64 v0, v[66:67] offset:8184
	s_waitcnt lgkmcnt(0)
	s_barrier
